# priority drop of the compute half deferred past the closing barrier so the compute tail ends on the barrier (on top of segment trim + merged waits)
# baseline (speedup 1.0000x reference)
;     __host__ __device__ bool next(int i, Unit& u) const { if (!b.next(i >> 1, u)) return false; u.sel = i & 1; return true; }
; #define PG8_STAGE(bufoff, gbase, voff) do { _Pragma("unroll") for (int _i = 0; _i < 2; ++_i) \
;         __builtin_amdgcn_global_load_lds((const unsigned*)((const char*)(gbase) + (voff)[_i]), (PG8_LAS unsigned*)(lds + (bufoff) + ldsw + _i * 8192), 16, 0, 0); } while (0)
; #define PG8_LDA(dst, b, h) do { _Pragma("unroll") for (int m = 0; m < 4; ++m) _Pragma("unroll") for (int k = 0; k < 2; ++k) dst[m][k] = *(const PG8_LAS bf16x8*)(lds + PG8_SA(b, h) + aoff + m * 2048 + k * 1024); } while (0)
; #define PG8_BAR __builtin_amdgcn_s_barrier()
;     __host__ __device__ bool next(int i, Unit& u) const {
;         const long L = (long)i * G + c; if (L >= nwg) return false;
;         int wgid = (int)L; { const int q = nwg / NXCD, r = nwg % NXCD, xcd = wgid % NXCD, off = wgid / NXCD; wgid = (xcd < r ? xcd * (q + 1) : r * (q + 1) + (xcd - r) * q) + off; }
;         const int nig = WGM * nN, gid = wgid / nig, fm = gid * WGM, gsz = (nM - fm) < WGM ? (nM - fm) : WGM;
;         u.pm = fm + ((wgid % nig) % gsz); u.pn = (wgid % nig) / gsz; u.sel = 0; return true;
; template <class Epi, class Sched, bool ALIGN_EPI = false, bool SP2 = false>
; __device__ __forceinline__ void gemm_phase(PG8_LAS unsigned char* lds, const Gemm g, const Sched& S, const Epi& E) {
;     ...
;             const bool last = (t == nt - 2);
;             const char* a1 = cA + (size_t)(t + 1) * kstepA;
;             const char* a2 = last ? nA : cA + (size_t)(t + 2) * kstepA; const char* b2 = last ? nB : cB + (size_t)(t + 2) * kstep;
;             const char* a3 = a2 + kstepA; const char* b3 = b2 + kstep;
;             if (last && has_next) S.a_ready(nxt);
;             if constexpr (SP2) {
;             PG8_LDB(B0, 0, 0); PG8_LDB(B1, 0, 1); PG8_SCHED; PG8_LDA(At, 0, 0); PG8_STAGE(PG8_SA(1, 1), a1 + hstep, voffA);
;             PG8_WAIT_V(8); PG8_WAIT_L(0); PG8_BAR; PG8_MMA(0, 0, At, B0); PG8_MMA(0, 1, At, B1); PG8_BAR; PG8_SCHED;
;             if constexpr (Epi::PREFETCH) { if (t == tpf) E.prefetch(cur, wid, lane); }
;             PG8_LDA(At, 0, 1); PG8_STAGE(PG8_SB(0, 0), b2, voffB); PG8_STAGE(PG8_SB(0, 1), b2 + hstep, voffB); PG8_STAGE(PG8_SA(0, 0), a2, voffA);
;             PG8_WAIT_V(8); PG8_WAIT_L(0); PG8_BAR; PG8_MMA(1, 0, At, B0); PG8_MMA(1, 1, At, B1); PG8_BAR; PG8_SCHED;
.LBB0_205:
	s_add_u32 s22, s22, 0x40080
	s_addc_u32 s23, s23, 0
	s_add_u32 s52, s24, 0x100
	s_addc_u32 s53, s25, 0
	s_mov_b32 s54, -2
	ds_read_b128 v[154:157], v150
	ds_read_b128 v[158:161], v150 offset:1024
	ds_read_b128 v[162:165], v150 offset:2048
	ds_read_b128 v[166:169], v150 offset:3072
	ds_read_b128 v[170:173], v151
	ds_read_b128 v[174:177], v151 offset:1024
	ds_read_b128 v[178:181], v151 offset:2048
	ds_read_b128 v[182:185], v151 offset:3072
	s_add_u32 s24, s22, 0xfffc0080
	s_addc_u32 s25, s23, -1
	s_cmp_eq_u32 s54, 12
	s_cselect_b32 s27, s15, s25
	s_cselect_b32 s26, s50, s24
	s_cselect_b32 s25, s13, s53
	s_cselect_b32 s24, s51, s52
	v_lshl_add_u64 v[218:219], s[22:23], 0, v[140:141]
	s_add_i32 m0, s37, 0xc000
	ds_read_b128 v[186:189], v152
	ds_read_b128 v[190:193], v152 offset:1024
	ds_read_b128 v[194:197], v152 offset:2048
	ds_read_b128 v[198:201], v152 offset:3072
	ds_read_b128 v[202:205], v152 offset:4096
	ds_read_b128 v[206:209], v152 offset:5120
	ds_read_b128 v[210:213], v152 offset:6144
	ds_read_b128 v[214:217], v152 offset:7168
	global_load_lds_dwordx4 v[218:219], off
	v_lshl_add_u64 v[218:219], s[22:23], 0, v[142:143]
	s_add_i32 m0, s37, 0xe000
	s_nop 0
	global_load_lds_dwordx4 v[218:219], off
	s_add_i32 s44, s44, 1
	s_mul_i32 s0, s44, s46
	s_mul_hi_u32 s1, s44, s33
	s_add_i32 s1, s1, s0
	s_mul_i32 s0, s44, s33
	s_add_u32 s16, s0, s87
	s_addc_u32 s17, s1, s35
	v_cmp_lt_i64_e64 s[0:1], s[16:17], v[144:145]
	s_ashr_i32 s12, s16, 31
	s_lshr_b32 s12, s12, 29
	s_add_i32 s12, s16, s12
	s_ashr_i32 s13, s12, 3
	s_and_b32 s12, s12, -8
	s_sub_i32 s12, s16, s12
	s_cmp_lt_i32 s12, 0
	s_cselect_b32 s14, s36, 0x160
	s_mul_i32 s12, s12, s14
	s_add_i32 s12, s12, s13
	s_mul_hi_i32 s13, s12, 0x2e8ba2e9
	s_lshr_b32 s14, s13, 31
	s_ashr_i32 s13, s13, 3
	s_add_i32 s13, s13, s14
	s_lshl_b32 s14, s13, 1
	s_mul_i32 s13, s13, 44
	s_sub_i32 s13, s12, s13
	s_lshr_b32 s12, s13, 1
	s_and_b32 s13, s13, 1
	s_add_i32 s14, s14, s13
	s_ashr_i32 s15, s14, 31
	s_lshl_b64 s[16:17], s[14:15], 19
	s_add_u32 s16, s28, s16
	s_addc_u32 s17, s29, s17
	s_and_b64 s[18:19], s[0:1], exec
	s_cselect_b32 s15, s17, s29
	s_cselect_b32 s50, s16, s28
	s_ashr_i32 s13, s12, 31
	s_lshl_b64 s[18:19], s[12:13], 19
	s_add_u32 s18, s30, s18
	s_addc_u32 s19, s31, s19
	s_and_b64 s[98:99], s[0:1], exec
	s_cselect_b32 s13, s19, s31
	s_cselect_b32 s51, s18, s30
	s_waitcnt vmcnt(8) lgkmcnt(0)
	s_barrier
	s_setprio 1
	v_mfma_f32_16x16x32_bf16 v[126:129], v[154:157], v[186:189], 0
	v_mfma_f32_16x16x32_bf16 v[122:125], v[162:165], v[186:189], 0
	v_mfma_f32_16x16x32_bf16 v[110:113], v[154:157], v[194:197], 0
	v_mfma_f32_16x16x32_bf16 v[106:109], v[162:165], v[194:197], 0
	v_mfma_f32_16x16x32_bf16 v[94:97], v[154:157], v[202:205], 0
	v_mfma_f32_16x16x32_bf16 v[90:93], v[162:165], v[202:205], 0
	v_mfma_f32_16x16x32_bf16 v[78:81], v[154:157], v[210:213], 0
	v_mfma_f32_16x16x32_bf16 v[74:77], v[162:165], v[210:213], 0
	v_mfma_f32_16x16x32_bf16 v[126:129], v[158:161], v[190:193], v[126:129]
	v_mfma_f32_16x16x32_bf16 v[122:125], v[166:169], v[190:193], v[122:125]
	v_mfma_f32_16x16x32_bf16 v[110:113], v[158:161], v[198:201], v[110:113]
	v_mfma_f32_16x16x32_bf16 v[106:109], v[166:169], v[198:201], v[106:109]
	v_mfma_f32_16x16x32_bf16 v[94:97], v[158:161], v[206:209], v[94:97]
	v_mfma_f32_16x16x32_bf16 v[90:93], v[166:169], v[206:209], v[90:93]
	v_mfma_f32_16x16x32_bf16 v[78:81], v[158:161], v[214:217], v[78:81]
	v_mfma_f32_16x16x32_bf16 v[74:77], v[166:169], v[214:217], v[74:77]
	v_mfma_f32_16x16x32_bf16 v[118:121], v[170:173], v[186:189], 0
	v_mfma_f32_16x16x32_bf16 v[114:117], v[178:181], v[186:189], 0
	v_mfma_f32_16x16x32_bf16 v[102:105], v[170:173], v[194:197], 0
	v_mfma_f32_16x16x32_bf16 v[98:101], v[178:181], v[194:197], 0
	v_mfma_f32_16x16x32_bf16 v[86:89], v[170:173], v[202:205], 0
	v_mfma_f32_16x16x32_bf16 v[82:85], v[178:181], v[202:205], 0
	v_mfma_f32_16x16x32_bf16 v[70:73], v[170:173], v[210:213], 0
	v_mfma_f32_16x16x32_bf16 v[66:69], v[178:181], v[210:213], 0
	v_mfma_f32_16x16x32_bf16 v[118:121], v[174:177], v[190:193], v[118:121]
	v_mfma_f32_16x16x32_bf16 v[114:117], v[182:185], v[190:193], v[114:117]
	v_mfma_f32_16x16x32_bf16 v[102:105], v[174:177], v[198:201], v[102:105]
	v_mfma_f32_16x16x32_bf16 v[98:101], v[182:185], v[198:201], v[98:101]
	v_mfma_f32_16x16x32_bf16 v[86:89], v[174:177], v[206:209], v[86:89]
	v_mfma_f32_16x16x32_bf16 v[82:85], v[182:185], v[206:209], v[82:85]
	v_mfma_f32_16x16x32_bf16 v[70:73], v[174:177], v[214:217], v[70:73]
	v_mfma_f32_16x16x32_bf16 v[66:69], v[182:185], v[214:217], v[66:69]
	s_barrier
	s_setprio 0
	s_add_i32 s55, s47, s34
	v_lshl_add_u64 v[218:219], s[24:25], 0, v[134:135]
	s_mov_b32 m0, s55
	ds_read_b128 v[186:189], v152 offset:16384
	ds_read_b128 v[190:193], v152 offset:17408
	ds_read_b128 v[194:197], v152 offset:18432
	ds_read_b128 v[198:201], v152 offset:19456
	ds_read_b128 v[202:205], v152 offset:20480
	ds_read_b128 v[206:209], v152 offset:21504
	ds_read_b128 v[210:213], v152 offset:22528
	ds_read_b128 v[214:217], v152 offset:23552
	global_load_lds_dwordx4 v[218:219], off
	s_add_i32 m0, s55, 0x2000
	s_add_u32 s56, s24, 0x40000
	v_lshl_add_u64 v[222:223], s[24:25], 0, v[130:131]
	s_addc_u32 s57, s25, 0
	s_add_i32 s55, s48, s34
	global_load_lds_dwordx4 v[222:223], off
	v_lshl_add_u64 v[224:225], s[56:57], 0, v[134:135]
	s_mov_b32 m0, s55
	v_lshl_add_u64 v[226:227], s[26:27], 0, v[132:133]
	global_load_lds_dwordx4 v[224:225], off
	v_lshl_add_u64 v[224:225], s[56:57], 0, v[130:131]
	s_add_i32 m0, s55, 0x2000
	s_nop 0
	global_load_lds_dwordx4 v[224:225], off
	v_lshl_add_u64 v[224:225], s[26:27], 0, v[136:137]
	s_mov_b32 m0, s37
	s_nop 0
	global_load_lds_dwordx4 v[224:225], off
	s_mov_b32 m0, s38
	s_nop 0
	global_load_lds_dwordx4 v[226:227], off
	s_waitcnt vmcnt(8) lgkmcnt(0)
	s_barrier
; #define PG8_STAGE(bufoff, gbase, voff) do { _Pragma("unroll") for (int _i = 0; _i < 2; ++_i) \
;         __builtin_amdgcn_global_load_lds((const unsigned*)((const char*)(gbase) + (voff)[_i]), (PG8_LAS unsigned*)(lds + (bufoff) + ldsw + _i * 8192), 16, 0, 0); } while (0)
; #define PG8_LDA(dst, b, h) do { _Pragma("unroll") for (int m = 0; m < 4; ++m) _Pragma("unroll") for (int k = 0; k < 2; ++k) dst[m][k] = *(const PG8_LAS bf16x8*)(lds + PG8_SA(b, h) + aoff + m * 2048 + k * 1024); } while (0)
; #define PG8_LDB(dst, b, h) do { _Pragma("unroll") for (int n = 0; n < 2; ++n) _Pragma("unroll") for (int k = 0; k < 2; ++k) dst[n][k] = *(const PG8_LAS bf16x8*)(lds + PG8_SB(b, h) + boff + n * 2048 + k * 1024); } while (0)
; #define PG8_MMA(ai, bj, At, Bt) do { __builtin_amdgcn_s_setprio(1); _Pragma("unroll") for (int m = 0; m < 4; ++m) _Pragma("unroll") for (int n = 0; n < 2; ++n) _Pragma("unroll") for (int k = 0; k < 2; ++k) \
;         acc[ai][bj][m][n] = __builtin_amdgcn_mfma_f32_16x16x32_bf16(Bt[n][k], At[m][k], acc[ai][bj][m][n], 0, 0, 0); __builtin_amdgcn_s_setprio(0); } while (0)
; #define PG8_WAIT_V(n) asm volatile("s_waitcnt vmcnt(" #n ")" ::: "memory")
; #define PG8_WAIT_L(n) asm volatile("s_waitcnt lgkmcnt(" #n ")" ::: "memory")
; #define PG8_BAR __builtin_amdgcn_s_barrier()
; #define PG8_SCHED __builtin_amdgcn_sched_barrier(0)
;     __device__ __forceinline__ void prefetch(const Unit& u, int wid, int lane) const { epi_prefetch(scr, ssq, bias + (size_t)(u.pm >> 5) * NGU + u.pn * BM, u, wid, lane); }
; template <class Epi, class Sched, bool ALIGN_EPI = false, bool SP2 = false>
; __device__ __forceinline__ void gemm_phase(PG8_LAS unsigned char* lds, const Gemm g, const Sched& S, const Epi& E) {
;     ...
;             PG8_LDB(B0, 0, 0); PG8_LDB(B1, 0, 1); PG8_SCHED; PG8_LDA(At, 0, 0); PG8_STAGE(PG8_SA(1, 1), a1 + hstep, voffA);
;             PG8_WAIT_V(8); PG8_WAIT_L(0); PG8_BAR; PG8_MMA(0, 0, At, B0); PG8_MMA(0, 1, At, B1); PG8_BAR; PG8_SCHED;
;             if constexpr (Epi::PREFETCH) { if (t == tpf) E.prefetch(cur, wid, lane); }
;             PG8_LDA(At, 0, 1); PG8_STAGE(PG8_SB(0, 0), b2, voffB); PG8_STAGE(PG8_SB(0, 1), b2 + hstep, voffB); PG8_STAGE(PG8_SA(0, 0), a2, voffA);
;             PG8_WAIT_V(8); PG8_WAIT_L(0); PG8_BAR; PG8_MMA(1, 0, At, B0); PG8_MMA(1, 1, At, B1); PG8_BAR; PG8_SCHED;
	s_setprio 1
	v_mfma_f32_16x16x32_bf16 v[62:65], v[154:157], v[186:189], 0
	v_mfma_f32_16x16x32_bf16 v[58:61], v[162:165], v[186:189], 0
	v_mfma_f32_16x16x32_bf16 v[46:49], v[154:157], v[194:197], 0
	v_mfma_f32_16x16x32_bf16 v[42:45], v[162:165], v[194:197], 0
	v_mfma_f32_16x16x32_bf16 v[30:33], v[154:157], v[202:205], 0
	v_mfma_f32_16x16x32_bf16 v[26:29], v[162:165], v[202:205], 0
	v_mfma_f32_16x16x32_bf16 v[14:17], v[154:157], v[210:213], 0
	v_mfma_f32_16x16x32_bf16 v[10:13], v[162:165], v[210:213], 0
	v_mfma_f32_16x16x32_bf16 v[62:65], v[158:161], v[190:193], v[62:65]
	v_mfma_f32_16x16x32_bf16 v[58:61], v[166:169], v[190:193], v[58:61]
	v_mfma_f32_16x16x32_bf16 v[46:49], v[158:161], v[198:201], v[46:49]
	v_mfma_f32_16x16x32_bf16 v[42:45], v[166:169], v[198:201], v[42:45]
	v_mfma_f32_16x16x32_bf16 v[30:33], v[158:161], v[206:209], v[30:33]
	v_mfma_f32_16x16x32_bf16 v[26:29], v[166:169], v[206:209], v[26:29]
	v_mfma_f32_16x16x32_bf16 v[14:17], v[158:161], v[214:217], v[14:17]
	v_mfma_f32_16x16x32_bf16 v[10:13], v[166:169], v[214:217], v[10:13]
	v_mfma_f32_16x16x32_bf16 v[54:57], v[170:173], v[186:189], 0
	v_mfma_f32_16x16x32_bf16 v[50:53], v[178:181], v[186:189], 0
	v_mfma_f32_16x16x32_bf16 v[38:41], v[170:173], v[194:197], 0
	v_mfma_f32_16x16x32_bf16 v[34:37], v[178:181], v[194:197], 0
	v_mfma_f32_16x16x32_bf16 v[22:25], v[170:173], v[202:205], 0
	v_mfma_f32_16x16x32_bf16 v[18:21], v[178:181], v[202:205], 0
	v_mfma_f32_16x16x32_bf16 v[6:9], v[170:173], v[210:213], 0
	v_mfma_f32_16x16x32_bf16 v[2:5], v[178:181], v[210:213], 0
	v_mfma_f32_16x16x32_bf16 v[54:57], v[174:177], v[190:193], v[54:57]
	v_mfma_f32_16x16x32_bf16 v[50:53], v[182:185], v[190:193], v[50:53]
	v_mfma_f32_16x16x32_bf16 v[38:41], v[174:177], v[198:201], v[38:41]
	v_mfma_f32_16x16x32_bf16 v[34:37], v[182:185], v[198:201], v[34:37]
	v_mfma_f32_16x16x32_bf16 v[22:25], v[174:177], v[206:209], v[22:25]
	v_mfma_f32_16x16x32_bf16 v[18:21], v[182:185], v[206:209], v[18:21]
	v_mfma_f32_16x16x32_bf16 v[6:9], v[174:177], v[214:217], v[6:9]
	v_mfma_f32_16x16x32_bf16 v[2:5], v[182:185], v[214:217], v[2:5]
	s_barrier
	s_setprio 0
	s_branch .Lpz1_mid
.LBB0_208:
	ds_read_b128 v[154:157], v150
	ds_read_b128 v[158:161], v150 offset:1024
	ds_read_b128 v[162:165], v150 offset:2048
	ds_read_b128 v[166:169], v150 offset:3072
	ds_read_b128 v[170:173], v151
	ds_read_b128 v[174:177], v151 offset:1024
	ds_read_b128 v[178:181], v151 offset:2048
	ds_read_b128 v[182:185], v151 offset:3072
	s_add_u32 s24, s22, 0xfffc0080
	s_addc_u32 s25, s23, -1
	s_cmp_eq_u32 s54, 12
	s_cselect_b32 s27, s15, s25
	s_cselect_b32 s26, s50, s24
	s_cselect_b32 s25, s13, s53
	s_cselect_b32 s24, s51, s52
	v_lshl_add_u64 v[218:219], s[22:23], 0, v[140:141]
	s_add_i32 m0, s37, 0xc000
	ds_read_b128 v[186:189], v152
	ds_read_b128 v[190:193], v152 offset:1024
	ds_read_b128 v[194:197], v152 offset:2048
	ds_read_b128 v[198:201], v152 offset:3072
	ds_read_b128 v[202:205], v152 offset:4096
	ds_read_b128 v[206:209], v152 offset:5120
	ds_read_b128 v[210:213], v152 offset:6144
	ds_read_b128 v[214:217], v152 offset:7168
	global_load_lds_dwordx4 v[218:219], off
	v_lshl_add_u64 v[218:219], s[22:23], 0, v[142:143]
	s_add_i32 m0, s37, 0xe000
	s_nop 0
	global_load_lds_dwordx4 v[218:219], off
	s_waitcnt vmcnt(8) lgkmcnt(0)
	s_barrier
	s_setprio 1
	v_mfma_f32_16x16x32_bf16 v[126:129], v[154:157], v[186:189], v[126:129]
	v_mfma_f32_16x16x32_bf16 v[122:125], v[162:165], v[186:189], v[122:125]
	v_mfma_f32_16x16x32_bf16 v[110:113], v[154:157], v[194:197], v[110:113]
	v_mfma_f32_16x16x32_bf16 v[106:109], v[162:165], v[194:197], v[106:109]
	v_mfma_f32_16x16x32_bf16 v[94:97], v[154:157], v[202:205], v[94:97]
	v_mfma_f32_16x16x32_bf16 v[90:93], v[162:165], v[202:205], v[90:93]
	v_mfma_f32_16x16x32_bf16 v[78:81], v[154:157], v[210:213], v[78:81]
	v_mfma_f32_16x16x32_bf16 v[74:77], v[162:165], v[210:213], v[74:77]
	v_mfma_f32_16x16x32_bf16 v[126:129], v[158:161], v[190:193], v[126:129]
	v_mfma_f32_16x16x32_bf16 v[122:125], v[166:169], v[190:193], v[122:125]
	v_mfma_f32_16x16x32_bf16 v[110:113], v[158:161], v[198:201], v[110:113]
	v_mfma_f32_16x16x32_bf16 v[106:109], v[166:169], v[198:201], v[106:109]
	v_mfma_f32_16x16x32_bf16 v[94:97], v[158:161], v[206:209], v[94:97]
	v_mfma_f32_16x16x32_bf16 v[90:93], v[166:169], v[206:209], v[90:93]
	v_mfma_f32_16x16x32_bf16 v[78:81], v[158:161], v[214:217], v[78:81]
	v_mfma_f32_16x16x32_bf16 v[74:77], v[166:169], v[214:217], v[74:77]
	v_mfma_f32_16x16x32_bf16 v[118:121], v[170:173], v[186:189], v[118:121]
	v_mfma_f32_16x16x32_bf16 v[114:117], v[178:181], v[186:189], v[114:117]
	v_mfma_f32_16x16x32_bf16 v[102:105], v[170:173], v[194:197], v[102:105]
	v_mfma_f32_16x16x32_bf16 v[98:101], v[178:181], v[194:197], v[98:101]
	v_mfma_f32_16x16x32_bf16 v[86:89], v[170:173], v[202:205], v[86:89]
	v_mfma_f32_16x16x32_bf16 v[82:85], v[178:181], v[202:205], v[82:85]
	v_mfma_f32_16x16x32_bf16 v[70:73], v[170:173], v[210:213], v[70:73]
	v_mfma_f32_16x16x32_bf16 v[66:69], v[178:181], v[210:213], v[66:69]
	v_mfma_f32_16x16x32_bf16 v[118:121], v[174:177], v[190:193], v[118:121]
	v_mfma_f32_16x16x32_bf16 v[114:117], v[182:185], v[190:193], v[114:117]
	v_mfma_f32_16x16x32_bf16 v[102:105], v[174:177], v[198:201], v[102:105]
	v_mfma_f32_16x16x32_bf16 v[98:101], v[182:185], v[198:201], v[98:101]
	v_mfma_f32_16x16x32_bf16 v[86:89], v[174:177], v[206:209], v[86:89]
	v_mfma_f32_16x16x32_bf16 v[82:85], v[182:185], v[206:209], v[82:85]
	v_mfma_f32_16x16x32_bf16 v[70:73], v[174:177], v[214:217], v[70:73]
	v_mfma_f32_16x16x32_bf16 v[66:69], v[182:185], v[214:217], v[66:69]
	s_barrier
; #define PG8_STAGE(bufoff, gbase, voff) do { _Pragma("unroll") for (int _i = 0; _i < 2; ++_i) \
;         __builtin_amdgcn_global_load_lds((const unsigned*)((const char*)(gbase) + (voff)[_i]), (PG8_LAS unsigned*)(lds + (bufoff) + ldsw + _i * 8192), 16, 0, 0); } while (0)
; #define PG8_LDA(dst, b, h) do { _Pragma("unroll") for (int m = 0; m < 4; ++m) _Pragma("unroll") for (int k = 0; k < 2; ++k) dst[m][k] = *(const PG8_LAS bf16x8*)(lds + PG8_SA(b, h) + aoff + m * 2048 + k * 1024); } while (0)
; #define PG8_LDB(dst, b, h) do { _Pragma("unroll") for (int n = 0; n < 2; ++n) _Pragma("unroll") for (int k = 0; k < 2; ++k) dst[n][k] = *(const PG8_LAS bf16x8*)(lds + PG8_SB(b, h) + boff + n * 2048 + k * 1024); } while (0)
; #define PG8_MMA(ai, bj, At, Bt) do { __builtin_amdgcn_s_setprio(1); _Pragma("unroll") for (int m = 0; m < 4; ++m) _Pragma("unroll") for (int n = 0; n < 2; ++n) _Pragma("unroll") for (int k = 0; k < 2; ++k) \
;         acc[ai][bj][m][n] = __builtin_amdgcn_mfma_f32_16x16x32_bf16(Bt[n][k], At[m][k], acc[ai][bj][m][n], 0, 0, 0); __builtin_amdgcn_s_setprio(0); } while (0)
; #define PG8_WAIT_V(n) asm volatile("s_waitcnt vmcnt(" #n ")" ::: "memory")
; #define PG8_WAIT_L(n) asm volatile("s_waitcnt lgkmcnt(" #n ")" ::: "memory")
; #define PG8_BAR __builtin_amdgcn_s_barrier()
; #define PG8_SCHED __builtin_amdgcn_sched_barrier(0)
; template <class Epi, class Sched, bool ALIGN_EPI = false, bool SP2 = false>
; __device__ __forceinline__ void gemm_phase(PG8_LAS unsigned char* lds, const Gemm g, const Sched& S, const Epi& E) {
;     ...
;             PG8_LDA(At, 0, 1); PG8_STAGE(PG8_SB(0, 0), b2, voffB); PG8_STAGE(PG8_SB(0, 1), b2 + hstep, voffB); PG8_STAGE(PG8_SA(0, 0), a2, voffA);
;             PG8_WAIT_V(8); PG8_WAIT_L(0); PG8_BAR; PG8_MMA(1, 0, At, B0); PG8_MMA(1, 1, At, B1); PG8_BAR; PG8_SCHED;
;             PG8_LDB(B0, 1, 0); PG8_LDB(B1, 1, 1); PG8_SCHED; PG8_LDA(At, 1, 0); PG8_STAGE(PG8_SA(0, 1), a2 + hstep, voffA);
;             PG8_WAIT_V(8); PG8_WAIT_L(0); PG8_BAR; PG8_MMA(0, 0, At, B0); PG8_MMA(0, 1, At, B1); PG8_BAR; PG8_SCHED;
	s_setprio 0
	s_add_i32 s55, s47, s34
	v_lshl_add_u64 v[218:219], s[24:25], 0, v[134:135]
	s_mov_b32 m0, s55
	ds_read_b128 v[186:189], v152 offset:16384
	ds_read_b128 v[190:193], v152 offset:17408
	ds_read_b128 v[194:197], v152 offset:18432
	ds_read_b128 v[198:201], v152 offset:19456
	ds_read_b128 v[202:205], v152 offset:20480
	ds_read_b128 v[206:209], v152 offset:21504
	ds_read_b128 v[210:213], v152 offset:22528
	ds_read_b128 v[214:217], v152 offset:23552
	global_load_lds_dwordx4 v[218:219], off
	s_add_i32 m0, s55, 0x2000
	s_add_u32 s56, s24, 0x40000
	v_lshl_add_u64 v[222:223], s[24:25], 0, v[130:131]
	s_addc_u32 s57, s25, 0
	s_add_i32 s55, s48, s34
	global_load_lds_dwordx4 v[222:223], off
	v_lshl_add_u64 v[224:225], s[56:57], 0, v[134:135]
	s_mov_b32 m0, s55
	v_lshl_add_u64 v[226:227], s[26:27], 0, v[132:133]
	global_load_lds_dwordx4 v[224:225], off
	v_lshl_add_u64 v[224:225], s[56:57], 0, v[130:131]
	s_add_i32 m0, s55, 0x2000
	s_nop 0
	global_load_lds_dwordx4 v[224:225], off
	v_lshl_add_u64 v[224:225], s[26:27], 0, v[136:137]
	s_mov_b32 m0, s37
	s_nop 0
	global_load_lds_dwordx4 v[224:225], off
	s_mov_b32 m0, s38
	s_nop 0
	global_load_lds_dwordx4 v[226:227], off
	s_waitcnt vmcnt(8) lgkmcnt(0)
	s_barrier
	s_setprio 1
	v_mfma_f32_16x16x32_bf16 v[62:65], v[154:157], v[186:189], v[62:65]
	v_mfma_f32_16x16x32_bf16 v[58:61], v[162:165], v[186:189], v[58:61]
	v_mfma_f32_16x16x32_bf16 v[46:49], v[154:157], v[194:197], v[46:49]
	v_mfma_f32_16x16x32_bf16 v[42:45], v[162:165], v[194:197], v[42:45]
	v_mfma_f32_16x16x32_bf16 v[30:33], v[154:157], v[202:205], v[30:33]
	v_mfma_f32_16x16x32_bf16 v[26:29], v[162:165], v[202:205], v[26:29]
	v_mfma_f32_16x16x32_bf16 v[14:17], v[154:157], v[210:213], v[14:17]
	v_mfma_f32_16x16x32_bf16 v[10:13], v[162:165], v[210:213], v[10:13]
	v_mfma_f32_16x16x32_bf16 v[62:65], v[158:161], v[190:193], v[62:65]
	v_mfma_f32_16x16x32_bf16 v[58:61], v[166:169], v[190:193], v[58:61]
	v_mfma_f32_16x16x32_bf16 v[46:49], v[158:161], v[198:201], v[46:49]
	v_mfma_f32_16x16x32_bf16 v[42:45], v[166:169], v[198:201], v[42:45]
	v_mfma_f32_16x16x32_bf16 v[30:33], v[158:161], v[206:209], v[30:33]
	v_mfma_f32_16x16x32_bf16 v[26:29], v[166:169], v[206:209], v[26:29]
	v_mfma_f32_16x16x32_bf16 v[14:17], v[158:161], v[214:217], v[14:17]
	v_mfma_f32_16x16x32_bf16 v[10:13], v[166:169], v[214:217], v[10:13]
	v_mfma_f32_16x16x32_bf16 v[54:57], v[170:173], v[186:189], v[54:57]
	v_mfma_f32_16x16x32_bf16 v[50:53], v[178:181], v[186:189], v[50:53]
	v_mfma_f32_16x16x32_bf16 v[38:41], v[170:173], v[194:197], v[38:41]
	v_mfma_f32_16x16x32_bf16 v[34:37], v[178:181], v[194:197], v[34:37]
	v_mfma_f32_16x16x32_bf16 v[22:25], v[170:173], v[202:205], v[22:25]
	v_mfma_f32_16x16x32_bf16 v[18:21], v[178:181], v[202:205], v[18:21]
	v_mfma_f32_16x16x32_bf16 v[6:9], v[170:173], v[210:213], v[6:9]
	v_mfma_f32_16x16x32_bf16 v[2:5], v[178:181], v[210:213], v[2:5]
	v_mfma_f32_16x16x32_bf16 v[54:57], v[174:177], v[190:193], v[54:57]
	v_mfma_f32_16x16x32_bf16 v[50:53], v[182:185], v[190:193], v[50:53]
	v_mfma_f32_16x16x32_bf16 v[38:41], v[174:177], v[198:201], v[38:41]
	v_mfma_f32_16x16x32_bf16 v[34:37], v[182:185], v[198:201], v[34:37]
	v_mfma_f32_16x16x32_bf16 v[22:25], v[174:177], v[206:209], v[22:25]
	v_mfma_f32_16x16x32_bf16 v[18:21], v[182:185], v[206:209], v[18:21]
	v_mfma_f32_16x16x32_bf16 v[6:9], v[174:177], v[214:217], v[6:9]
	v_mfma_f32_16x16x32_bf16 v[2:5], v[182:185], v[214:217], v[2:5]
	s_barrier
	s_setprio 0
.Lpz1_mid:
	s_add_i32 s55, 0, 0x18000
	v_add_u32_e32 v138, s55, v149
	s_add_i32 s56, 0, 0x1c000
	ds_read_b128 v[154:157], v138
	ds_read_b128 v[158:161], v138 offset:1024
	ds_read_b128 v[162:165], v138 offset:2048
	ds_read_b128 v[166:169], v138 offset:3072
	v_add_u32_e32 v138, s56, v149
	ds_read_b128 v[170:173], v138
	ds_read_b128 v[174:177], v138 offset:1024
	ds_read_b128 v[178:181], v138 offset:2048
	ds_read_b128 v[182:185], v138 offset:3072
	s_add_u32 s26, s26, 0x40000
	s_addc_u32 s27, s27, 0
	s_mov_b32 m0, s39
	v_lshl_add_u64 v[228:229], s[26:27], 0, v[136:137]
	ds_read_b128 v[186:189], v152 offset:32768
	ds_read_b128 v[190:193], v152 offset:33792
	ds_read_b128 v[194:197], v152 offset:34816
	ds_read_b128 v[198:201], v152 offset:35840
	ds_read_b128 v[202:205], v152 offset:36864
	ds_read_b128 v[206:209], v152 offset:37888
	ds_read_b128 v[210:213], v152 offset:38912
	ds_read_b128 v[214:217], v152 offset:39936
	global_load_lds_dwordx4 v[228:229], off
	v_lshl_add_u64 v[228:229], s[26:27], 0, v[132:133]
	s_mov_b32 m0, s40
	s_nop 0
	global_load_lds_dwordx4 v[228:229], off
	s_waitcnt vmcnt(8) lgkmcnt(0)
	s_barrier
; #define PG8_STAGE(bufoff, gbase, voff) do { _Pragma("unroll") for (int _i = 0; _i < 2; ++_i) \
;         __builtin_amdgcn_global_load_lds((const unsigned*)((const char*)(gbase) + (voff)[_i]), (PG8_LAS unsigned*)(lds + (bufoff) + ldsw + _i * 8192), 16, 0, 0); } while (0)
; #define PG8_LDA(dst, b, h) do { _Pragma("unroll") for (int m = 0; m < 4; ++m) _Pragma("unroll") for (int k = 0; k < 2; ++k) dst[m][k] = *(const PG8_LAS bf16x8*)(lds + PG8_SA(b, h) + aoff + m * 2048 + k * 1024); } while (0)
; #define PG8_MMA(ai, bj, At, Bt) do { __builtin_amdgcn_s_setprio(1); _Pragma("unroll") for (int m = 0; m < 4; ++m) _Pragma("unroll") for (int n = 0; n < 2; ++n) _Pragma("unroll") for (int k = 0; k < 2; ++k) \
;         acc[ai][bj][m][n] = __builtin_amdgcn_mfma_f32_16x16x32_bf16(Bt[n][k], At[m][k], acc[ai][bj][m][n], 0, 0, 0); __builtin_amdgcn_s_setprio(0); } while (0)
; #define PG8_WAIT_V(n) asm volatile("s_waitcnt vmcnt(" #n ")" ::: "memory")
; #define PG8_WAIT_L(n) asm volatile("s_waitcnt lgkmcnt(" #n ")" ::: "memory")
; #define PG8_BAR __builtin_amdgcn_s_barrier()
; #define PG8_SCHED __builtin_amdgcn_sched_barrier(0)
; template <class Epi, class Sched, bool ALIGN_EPI = false, bool SP2 = false>
; __device__ __forceinline__ void gemm_phase(PG8_LAS unsigned char* lds, const Gemm g, const Sched& S, const Epi& E) {
;     ...
;             PG8_WAIT_V(8); PG8_WAIT_L(0); PG8_BAR; PG8_MMA(0, 0, At, B0); PG8_MMA(0, 1, At, B1); PG8_BAR; PG8_SCHED;
;             PG8_LDA(At, 1, 1); PG8_STAGE(PG8_SB(1, 0), b3, voffB); PG8_STAGE(PG8_SB(1, 1), b3 + hstep, voffB); PG8_STAGE(PG8_SA(1, 0), a3, voffA);
;             PG8_WAIT_V(8); PG8_WAIT_L(0); PG8_BAR; PG8_MMA(1, 0, At, B0); PG8_MMA(1, 1, At, B1); PG8_BAR; PG8_SCHED;
;     ...
;         if constexpr (ALIGN_EPI) { if (wr == 0) PG8_BAR; }
	s_setprio 1
	v_mfma_f32_16x16x32_bf16 v[126:129], v[154:157], v[186:189], v[126:129]
	v_mfma_f32_16x16x32_bf16 v[122:125], v[162:165], v[186:189], v[122:125]
	v_mfma_f32_16x16x32_bf16 v[110:113], v[154:157], v[194:197], v[110:113]
	v_mfma_f32_16x16x32_bf16 v[106:109], v[162:165], v[194:197], v[106:109]
	v_mfma_f32_16x16x32_bf16 v[94:97], v[154:157], v[202:205], v[94:97]
	v_mfma_f32_16x16x32_bf16 v[90:93], v[162:165], v[202:205], v[90:93]
	v_mfma_f32_16x16x32_bf16 v[78:81], v[154:157], v[210:213], v[78:81]
	v_mfma_f32_16x16x32_bf16 v[74:77], v[162:165], v[210:213], v[74:77]
	v_mfma_f32_16x16x32_bf16 v[126:129], v[158:161], v[190:193], v[126:129]
	v_mfma_f32_16x16x32_bf16 v[122:125], v[166:169], v[190:193], v[122:125]
	v_mfma_f32_16x16x32_bf16 v[110:113], v[158:161], v[198:201], v[110:113]
	v_mfma_f32_16x16x32_bf16 v[106:109], v[166:169], v[198:201], v[106:109]
	v_mfma_f32_16x16x32_bf16 v[94:97], v[158:161], v[206:209], v[94:97]
	v_mfma_f32_16x16x32_bf16 v[90:93], v[166:169], v[206:209], v[90:93]
	v_mfma_f32_16x16x32_bf16 v[78:81], v[158:161], v[214:217], v[78:81]
	v_mfma_f32_16x16x32_bf16 v[74:77], v[166:169], v[214:217], v[74:77]
	v_mfma_f32_16x16x32_bf16 v[118:121], v[170:173], v[186:189], v[118:121]
	v_mfma_f32_16x16x32_bf16 v[114:117], v[178:181], v[186:189], v[114:117]
	v_mfma_f32_16x16x32_bf16 v[102:105], v[170:173], v[194:197], v[102:105]
	v_mfma_f32_16x16x32_bf16 v[98:101], v[178:181], v[194:197], v[98:101]
	v_mfma_f32_16x16x32_bf16 v[86:89], v[170:173], v[202:205], v[86:89]
	v_mfma_f32_16x16x32_bf16 v[82:85], v[178:181], v[202:205], v[82:85]
	v_mfma_f32_16x16x32_bf16 v[70:73], v[170:173], v[210:213], v[70:73]
	v_mfma_f32_16x16x32_bf16 v[66:69], v[178:181], v[210:213], v[66:69]
	v_mfma_f32_16x16x32_bf16 v[118:121], v[174:177], v[190:193], v[118:121]
	v_mfma_f32_16x16x32_bf16 v[114:117], v[182:185], v[190:193], v[114:117]
	v_mfma_f32_16x16x32_bf16 v[102:105], v[174:177], v[198:201], v[102:105]
	v_mfma_f32_16x16x32_bf16 v[98:101], v[182:185], v[198:201], v[98:101]
	v_mfma_f32_16x16x32_bf16 v[86:89], v[174:177], v[206:209], v[86:89]
	v_mfma_f32_16x16x32_bf16 v[82:85], v[182:185], v[206:209], v[82:85]
	v_mfma_f32_16x16x32_bf16 v[70:73], v[174:177], v[214:217], v[70:73]
	v_mfma_f32_16x16x32_bf16 v[66:69], v[182:185], v[214:217], v[66:69]
	s_barrier
	s_setprio 0
	s_add_i32 s26, s55, s34
	v_lshl_add_u64 v[218:219], v[218:219], 0, s[8:9]
	s_mov_b32 m0, s26
	ds_read_b128 v[186:189], v152 offset:49152
	ds_read_b128 v[190:193], v152 offset:50176
	ds_read_b128 v[194:197], v152 offset:51200
	ds_read_b128 v[198:201], v152 offset:52224
	ds_read_b128 v[202:205], v152 offset:53248
	ds_read_b128 v[206:209], v152 offset:54272
	ds_read_b128 v[210:213], v152 offset:55296
	ds_read_b128 v[214:217], v152 offset:56320
	global_load_lds_dwordx4 v[218:219], off
	s_add_i32 m0, s26, 0x2000
	s_add_u32 s24, s24, 0x40080
	v_lshl_add_u64 v[218:219], v[222:223], 0, s[8:9]
	s_addc_u32 s25, s25, 0
	s_add_i32 s26, s56, s34
	global_load_lds_dwordx4 v[218:219], off
	v_lshl_add_u64 v[218:219], s[24:25], 0, v[134:135]
	s_mov_b32 m0, s26
	s_nop 0
	global_load_lds_dwordx4 v[218:219], off
	v_lshl_add_u64 v[218:219], s[24:25], 0, v[130:131]
	s_add_i32 m0, s26, 0x2000
	s_nop 0
	global_load_lds_dwordx4 v[218:219], off
	v_lshl_add_u64 v[218:219], v[224:225], 0, s[8:9]
	s_mov_b32 m0, s42
	s_nop 0
	global_load_lds_dwordx4 v[218:219], off
	v_lshl_add_u64 v[218:219], v[226:227], 0, s[8:9]
	s_mov_b32 m0, s43
	s_nop 0
	global_load_lds_dwordx4 v[218:219], off
	s_waitcnt vmcnt(8) lgkmcnt(0)
	s_barrier
	s_setprio 1
	v_mfma_f32_16x16x32_bf16 v[62:65], v[154:157], v[186:189], v[62:65]
	v_mfma_f32_16x16x32_bf16 v[58:61], v[162:165], v[186:189], v[58:61]
	v_mfma_f32_16x16x32_bf16 v[46:49], v[154:157], v[194:197], v[46:49]
	v_mfma_f32_16x16x32_bf16 v[42:45], v[162:165], v[194:197], v[42:45]
	v_mfma_f32_16x16x32_bf16 v[30:33], v[154:157], v[202:205], v[30:33]
	v_mfma_f32_16x16x32_bf16 v[26:29], v[162:165], v[202:205], v[26:29]
	v_mfma_f32_16x16x32_bf16 v[14:17], v[154:157], v[210:213], v[14:17]
	v_mfma_f32_16x16x32_bf16 v[10:13], v[162:165], v[210:213], v[10:13]
	v_mfma_f32_16x16x32_bf16 v[62:65], v[158:161], v[190:193], v[62:65]
	v_mfma_f32_16x16x32_bf16 v[58:61], v[166:169], v[190:193], v[58:61]
	v_mfma_f32_16x16x32_bf16 v[46:49], v[158:161], v[198:201], v[46:49]
	v_mfma_f32_16x16x32_bf16 v[42:45], v[166:169], v[198:201], v[42:45]
	v_mfma_f32_16x16x32_bf16 v[30:33], v[158:161], v[206:209], v[30:33]
	v_mfma_f32_16x16x32_bf16 v[26:29], v[166:169], v[206:209], v[26:29]
	v_mfma_f32_16x16x32_bf16 v[14:17], v[158:161], v[214:217], v[14:17]
	v_mfma_f32_16x16x32_bf16 v[10:13], v[166:169], v[214:217], v[10:13]
	v_mfma_f32_16x16x32_bf16 v[54:57], v[170:173], v[186:189], v[54:57]
	v_mfma_f32_16x16x32_bf16 v[50:53], v[178:181], v[186:189], v[50:53]
	v_mfma_f32_16x16x32_bf16 v[38:41], v[170:173], v[194:197], v[38:41]
	v_mfma_f32_16x16x32_bf16 v[34:37], v[178:181], v[194:197], v[34:37]
	v_mfma_f32_16x16x32_bf16 v[22:25], v[170:173], v[202:205], v[22:25]
	v_mfma_f32_16x16x32_bf16 v[18:21], v[178:181], v[202:205], v[18:21]
	v_mfma_f32_16x16x32_bf16 v[6:9], v[170:173], v[210:213], v[6:9]
	v_mfma_f32_16x16x32_bf16 v[2:5], v[178:181], v[210:213], v[2:5]
	v_mfma_f32_16x16x32_bf16 v[54:57], v[174:177], v[190:193], v[54:57]
	v_mfma_f32_16x16x32_bf16 v[50:53], v[182:185], v[190:193], v[50:53]
	v_mfma_f32_16x16x32_bf16 v[38:41], v[174:177], v[198:201], v[38:41]
	v_mfma_f32_16x16x32_bf16 v[34:37], v[182:185], v[198:201], v[34:37]
	v_mfma_f32_16x16x32_bf16 v[22:25], v[174:177], v[206:209], v[22:25]
	v_mfma_f32_16x16x32_bf16 v[18:21], v[182:185], v[206:209], v[18:21]
	v_mfma_f32_16x16x32_bf16 v[6:9], v[174:177], v[214:217], v[6:9]
	v_mfma_f32_16x16x32_bf16 v[2:5], v[182:185], v[214:217], v[2:5]
	s_barrier
	s_setprio 0
	s_add_i32 s54, s54, 2
	s_add_u32 s22, s22, 0x100
	s_addc_u32 s23, s23, 0
	s_add_u32 s52, s52, 0x100
	s_addc_u32 s53, s53, 0
	s_cmp_gt_u32 s54, 13
	s_cbranch_scc0 .LBB0_208
	s_and_b64 vcc, exec, s[10:11]
	s_cbranch_vccz .LBB0_211
	s_barrier

; #define PG8_STAGE(bufoff, gbase, voff) do { _Pragma("unroll") for (int _i = 0; _i < 2; ++_i) \
;         __builtin_amdgcn_global_load_lds((const unsigned*)((const char*)(gbase) + (voff)[_i]), (PG8_LAS unsigned*)(lds + (bufoff) + ldsw + _i * 8192), 16, 0, 0); } while (0)
; #define PG8_LDA(dst, b, h) do { _Pragma("unroll") for (int m = 0; m < 4; ++m) _Pragma("unroll") for (int k = 0; k < 2; ++k) dst[m][k] = *(const PG8_LAS bf16x8*)(lds + PG8_SA(b, h) + aoff + m * 2048 + k * 1024); } while (0)
; #define PG8_LDB(dst, b, h) do { _Pragma("unroll") for (int n = 0; n < 2; ++n) _Pragma("unroll") for (int k = 0; k < 2; ++k) dst[n][k] = *(const PG8_LAS bf16x8*)(lds + PG8_SB(b, h) + boff + n * 2048 + k * 1024); } while (0)
; #define PG8_MMA(ai, bj, At, Bt) do { __builtin_amdgcn_s_setprio(1); _Pragma("unroll") for (int m = 0; m < 4; ++m) _Pragma("unroll") for (int n = 0; n < 2; ++n) _Pragma("unroll") for (int k = 0; k < 2; ++k) \
;         acc[ai][bj][m][n] = __builtin_amdgcn_mfma_f32_16x16x32_bf16(Bt[n][k], At[m][k], acc[ai][bj][m][n], 0, 0, 0); __builtin_amdgcn_s_setprio(0); } while (0)
; #define PG8_WAIT_V(n) asm volatile("s_waitcnt vmcnt(" #n ")" ::: "memory")
; #define PG8_WAIT_L(n) asm volatile("s_waitcnt lgkmcnt(" #n ")" ::: "memory")
; #define PG8_BAR __builtin_amdgcn_s_barrier()
; #define PG8_SCHED __builtin_amdgcn_sched_barrier(0)
;     __device__ __forceinline__ void prefetch(const Unit& u, int wid, int lane) const { epi_prefetch(scr, ssq, bias + (size_t)(u.pm >> 5) * NGU + u.pn * BM, u, wid, lane); }
; template <class Epi, class Sched, bool ALIGN_EPI = false, bool SP2 = false>
; __device__ __forceinline__ void gemm_phase(PG8_LAS unsigned char* lds, const Gemm g, const Sched& S, const Epi& E) {
;     ...
;             PG8_LDB(B0, 0, 0); PG8_LDB(B1, 0, 1); PG8_SCHED; PG8_LDA(At, 0, 0); PG8_STAGE(PG8_SA(1, 1), a1 + hstep, voffA);
;             PG8_WAIT_V(8); PG8_WAIT_L(0); PG8_BAR; PG8_MMA(0, 0, At, B0); PG8_MMA(0, 1, At, B1); PG8_BAR; PG8_SCHED;
;             if constexpr (Epi::PREFETCH) { if (t == tpf) E.prefetch(cur, wid, lane); }
;             PG8_LDA(At, 0, 1); PG8_STAGE(PG8_SB(0, 0), b2, voffB); PG8_STAGE(PG8_SB(0, 1), b2 + hstep, voffB); PG8_STAGE(PG8_SA(0, 0), a2, voffA);
;             PG8_WAIT_V(8); PG8_WAIT_L(0); PG8_BAR; PG8_MMA(1, 0, At, B0); PG8_MMA(1, 1, At, B1); PG8_BAR; PG8_SCHED;
.LBB0_288:
	s_add_u32 s39, s6, 0x100
	s_addc_u32 s40, s7, 0
	s_mov_b32 s41, -2
	ds_read_b128 v[130:133], v223
	ds_read_b128 v[134:137], v223 offset:1024
	ds_read_b128 v[138:141], v223 offset:2048
	ds_read_b128 v[142:145], v223 offset:3072
	ds_read_b128 v[164:167], v224
	ds_read_b128 v[168:171], v224 offset:1024
	ds_read_b128 v[172:175], v224 offset:2048
	ds_read_b128 v[176:179], v224 offset:3072
	s_add_u32 s0, s4, 0x200
	s_addc_u32 s1, s5, 0
	s_cmp_eq_u32 s41, 40
	s_cselect_b32 s37, s31, s1
	s_cselect_b32 s36, s30, s0
	s_cselect_b32 s7, s35, s40
	s_cselect_b32 s6, s34, s39
	v_lshl_add_u64 v[160:161], s[4:5], 0, v[156:157]
	s_add_i32 m0, s51, 0xc000
	ds_read_b128 v[180:183], v225
	ds_read_b128 v[184:187], v225 offset:1024
	ds_read_b128 v[188:191], v225 offset:2048
	ds_read_b128 v[192:195], v225 offset:3072
	ds_read_b128 v[196:199], v225 offset:4096
	ds_read_b128 v[200:203], v225 offset:5120
	ds_read_b128 v[204:207], v225 offset:6144
	ds_read_b128 v[208:211], v225 offset:7168
	global_load_lds_dwordx4 v[160:161], off
	v_lshl_add_u64 v[160:161], s[4:5], 0, v[158:159]
	s_add_i32 m0, s51, 0xe000
	s_nop 0
	global_load_lds_dwordx4 v[160:161], off
	s_waitcnt vmcnt(8) lgkmcnt(0)
	s_barrier
	s_setprio 1
	v_mfma_f32_16x16x32_bf16 v[126:129], v[130:133], v[180:183], 0
	v_mfma_f32_16x16x32_bf16 v[122:125], v[138:141], v[180:183], 0
	v_mfma_f32_16x16x32_bf16 v[110:113], v[130:133], v[188:191], 0
	v_mfma_f32_16x16x32_bf16 v[106:109], v[138:141], v[188:191], 0
	v_mfma_f32_16x16x32_bf16 v[94:97], v[130:133], v[196:199], 0
	v_mfma_f32_16x16x32_bf16 v[90:93], v[138:141], v[196:199], 0
	v_mfma_f32_16x16x32_bf16 v[78:81], v[130:133], v[204:207], 0
	v_mfma_f32_16x16x32_bf16 v[74:77], v[138:141], v[204:207], 0
	v_mfma_f32_16x16x32_bf16 v[126:129], v[134:137], v[184:187], v[126:129]
	v_mfma_f32_16x16x32_bf16 v[122:125], v[142:145], v[184:187], v[122:125]
	v_mfma_f32_16x16x32_bf16 v[110:113], v[134:137], v[192:195], v[110:113]
	v_mfma_f32_16x16x32_bf16 v[106:109], v[142:145], v[192:195], v[106:109]
	v_mfma_f32_16x16x32_bf16 v[94:97], v[134:137], v[200:203], v[94:97]
	v_mfma_f32_16x16x32_bf16 v[90:93], v[142:145], v[200:203], v[90:93]
	v_mfma_f32_16x16x32_bf16 v[78:81], v[134:137], v[208:211], v[78:81]
	v_mfma_f32_16x16x32_bf16 v[74:77], v[142:145], v[208:211], v[74:77]
	v_mfma_f32_16x16x32_bf16 v[118:121], v[164:167], v[180:183], 0
	v_mfma_f32_16x16x32_bf16 v[114:117], v[172:175], v[180:183], 0
	v_mfma_f32_16x16x32_bf16 v[102:105], v[164:167], v[188:191], 0
	v_mfma_f32_16x16x32_bf16 v[98:101], v[172:175], v[188:191], 0
	v_mfma_f32_16x16x32_bf16 v[86:89], v[164:167], v[196:199], 0
	v_mfma_f32_16x16x32_bf16 v[82:85], v[172:175], v[196:199], 0
	v_mfma_f32_16x16x32_bf16 v[70:73], v[164:167], v[204:207], 0
	v_mfma_f32_16x16x32_bf16 v[66:69], v[172:175], v[204:207], 0
	v_mfma_f32_16x16x32_bf16 v[118:121], v[168:171], v[184:187], v[118:121]
	v_mfma_f32_16x16x32_bf16 v[114:117], v[176:179], v[184:187], v[114:117]
	v_mfma_f32_16x16x32_bf16 v[102:105], v[168:171], v[192:195], v[102:105]
	v_mfma_f32_16x16x32_bf16 v[98:101], v[176:179], v[192:195], v[98:101]
	v_mfma_f32_16x16x32_bf16 v[86:89], v[168:171], v[200:203], v[86:89]
	v_mfma_f32_16x16x32_bf16 v[82:85], v[176:179], v[200:203], v[82:85]
	v_mfma_f32_16x16x32_bf16 v[70:73], v[168:171], v[208:211], v[70:73]
	v_mfma_f32_16x16x32_bf16 v[66:69], v[176:179], v[208:211], v[66:69]
	s_barrier
	s_setprio 0
	s_add_i32 s4, s68, s50
	v_lshl_add_u64 v[160:161], s[6:7], 0, v[148:149]
	s_mov_b32 m0, s4
	ds_read_b128 v[180:183], v225 offset:16384
	ds_read_b128 v[184:187], v225 offset:17408
	ds_read_b128 v[188:191], v225 offset:18432
	ds_read_b128 v[192:195], v225 offset:19456
	ds_read_b128 v[196:199], v225 offset:20480
	ds_read_b128 v[200:203], v225 offset:21504
	ds_read_b128 v[204:207], v225 offset:22528
	ds_read_b128 v[208:211], v225 offset:23552
	global_load_lds_dwordx4 v[160:161], off
	s_add_i32 m0, s4, 0x2000
	s_add_u32 s4, s6, 0xb0000
	v_lshl_add_u64 v[162:163], s[6:7], 0, v[152:153]
	s_addc_u32 s5, s7, 0
	s_add_i32 s42, s69, s50
	global_load_lds_dwordx4 v[162:163], off
	v_lshl_add_u64 v[212:213], s[4:5], 0, v[148:149]
	s_mov_b32 m0, s42
	v_lshl_add_u64 v[214:215], s[36:37], 0, v[150:151]
	global_load_lds_dwordx4 v[212:213], off
	v_lshl_add_u64 v[212:213], s[4:5], 0, v[152:153]
	s_add_i32 m0, s42, 0x2000
	s_nop 0
	global_load_lds_dwordx4 v[212:213], off
	v_lshl_add_u64 v[212:213], s[36:37], 0, v[146:147]
	s_mov_b32 m0, s51
	s_nop 0
	global_load_lds_dwordx4 v[212:213], off
	s_mov_b32 m0, s52
	s_nop 0
	global_load_lds_dwordx4 v[214:215], off
	s_waitcnt vmcnt(8) lgkmcnt(0)
	s_barrier
	s_setprio 1
	v_mfma_f32_16x16x32_bf16 v[62:65], v[130:133], v[180:183], 0
	v_mfma_f32_16x16x32_bf16 v[58:61], v[138:141], v[180:183], 0
	v_mfma_f32_16x16x32_bf16 v[46:49], v[130:133], v[188:191], 0
	v_mfma_f32_16x16x32_bf16 v[42:45], v[138:141], v[188:191], 0
	v_mfma_f32_16x16x32_bf16 v[30:33], v[130:133], v[196:199], 0
	v_mfma_f32_16x16x32_bf16 v[26:29], v[138:141], v[196:199], 0
	v_mfma_f32_16x16x32_bf16 v[14:17], v[130:133], v[204:207], 0
	v_mfma_f32_16x16x32_bf16 v[10:13], v[138:141], v[204:207], 0
	v_mfma_f32_16x16x32_bf16 v[62:65], v[134:137], v[184:187], v[62:65]
	v_mfma_f32_16x16x32_bf16 v[58:61], v[142:145], v[184:187], v[58:61]
	v_mfma_f32_16x16x32_bf16 v[46:49], v[134:137], v[192:195], v[46:49]
	v_mfma_f32_16x16x32_bf16 v[42:45], v[142:145], v[192:195], v[42:45]
	v_mfma_f32_16x16x32_bf16 v[30:33], v[134:137], v[200:203], v[30:33]
	v_mfma_f32_16x16x32_bf16 v[26:29], v[142:145], v[200:203], v[26:29]
	v_mfma_f32_16x16x32_bf16 v[14:17], v[134:137], v[208:211], v[14:17]
	v_mfma_f32_16x16x32_bf16 v[10:13], v[142:145], v[208:211], v[10:13]
	v_mfma_f32_16x16x32_bf16 v[54:57], v[164:167], v[180:183], 0
	v_mfma_f32_16x16x32_bf16 v[50:53], v[172:175], v[180:183], 0
	v_mfma_f32_16x16x32_bf16 v[38:41], v[164:167], v[188:191], 0
	v_mfma_f32_16x16x32_bf16 v[34:37], v[172:175], v[188:191], 0
	v_mfma_f32_16x16x32_bf16 v[22:25], v[164:167], v[196:199], 0
	v_mfma_f32_16x16x32_bf16 v[18:21], v[172:175], v[196:199], 0
	v_mfma_f32_16x16x32_bf16 v[6:9], v[164:167], v[204:207], 0
	v_mfma_f32_16x16x32_bf16 v[2:5], v[172:175], v[204:207], 0
	v_mfma_f32_16x16x32_bf16 v[54:57], v[168:171], v[184:187], v[54:57]
	v_mfma_f32_16x16x32_bf16 v[50:53], v[176:179], v[184:187], v[50:53]
	v_mfma_f32_16x16x32_bf16 v[38:41], v[168:171], v[192:195], v[38:41]
	v_mfma_f32_16x16x32_bf16 v[34:37], v[176:179], v[192:195], v[34:37]
	v_mfma_f32_16x16x32_bf16 v[22:25], v[168:171], v[200:203], v[22:25]
	v_mfma_f32_16x16x32_bf16 v[18:21], v[176:179], v[200:203], v[18:21]
	v_mfma_f32_16x16x32_bf16 v[6:9], v[168:171], v[208:211], v[6:9]
	v_mfma_f32_16x16x32_bf16 v[2:5], v[176:179], v[208:211], v[2:5]
	s_barrier
	s_setprio 0
	s_branch .Lpz2_mid
; #define PG8_STAGE(bufoff, gbase, voff) do { _Pragma("unroll") for (int _i = 0; _i < 2; ++_i) \
;         __builtin_amdgcn_global_load_lds((const unsigned*)((const char*)(gbase) + (voff)[_i]), (PG8_LAS unsigned*)(lds + (bufoff) + ldsw + _i * 8192), 16, 0, 0); } while (0)
; #define PG8_LDA(dst, b, h) do { _Pragma("unroll") for (int m = 0; m < 4; ++m) _Pragma("unroll") for (int k = 0; k < 2; ++k) dst[m][k] = *(const PG8_LAS bf16x8*)(lds + PG8_SA(b, h) + aoff + m * 2048 + k * 1024); } while (0)
; #define PG8_LDB(dst, b, h) do { _Pragma("unroll") for (int n = 0; n < 2; ++n) _Pragma("unroll") for (int k = 0; k < 2; ++k) dst[n][k] = *(const PG8_LAS bf16x8*)(lds + PG8_SB(b, h) + boff + n * 2048 + k * 1024); } while (0)
; #define PG8_MMA(ai, bj, At, Bt) do { __builtin_amdgcn_s_setprio(1); _Pragma("unroll") for (int m = 0; m < 4; ++m) _Pragma("unroll") for (int n = 0; n < 2; ++n) _Pragma("unroll") for (int k = 0; k < 2; ++k) \
;         acc[ai][bj][m][n] = __builtin_amdgcn_mfma_f32_16x16x32_bf16(Bt[n][k], At[m][k], acc[ai][bj][m][n], 0, 0, 0); __builtin_amdgcn_s_setprio(0); } while (0)
; #define PG8_WAIT_V(n) asm volatile("s_waitcnt vmcnt(" #n ")" ::: "memory")
; #define PG8_WAIT_L(n) asm volatile("s_waitcnt lgkmcnt(" #n ")" ::: "memory")
; #define PG8_BAR __builtin_amdgcn_s_barrier()
; #define PG8_SCHED __builtin_amdgcn_sched_barrier(0)
;     __device__ __forceinline__ void prefetch(const Unit& u, int wid, int lane) const { epi_prefetch(scr, ssq, bias + (size_t)(u.pm >> 5) * NGU + u.pn * BM, u, wid, lane); }
; template <class Epi, class Sched, bool ALIGN_EPI = false, bool SP2 = false>
; __device__ __forceinline__ void gemm_phase(PG8_LAS unsigned char* lds, const Gemm g, const Sched& S, const Epi& E) {
;     ...
;             PG8_LDB(B0, 0, 0); PG8_LDB(B1, 0, 1); PG8_SCHED; PG8_LDA(At, 0, 0); PG8_STAGE(PG8_SA(1, 1), a1 + hstep, voffA);
;             PG8_WAIT_V(8); PG8_WAIT_L(0); PG8_BAR; PG8_MMA(0, 0, At, B0); PG8_MMA(0, 1, At, B1); PG8_BAR; PG8_SCHED;
;             if constexpr (Epi::PREFETCH) { if (t == tpf) E.prefetch(cur, wid, lane); }
;             PG8_LDA(At, 0, 1); PG8_STAGE(PG8_SB(0, 0), b2, voffB); PG8_STAGE(PG8_SB(0, 1), b2 + hstep, voffB); PG8_STAGE(PG8_SA(0, 0), a2, voffA);
;             PG8_WAIT_V(8); PG8_WAIT_L(0); PG8_BAR; PG8_MMA(1, 0, At, B0); PG8_MMA(1, 1, At, B1); PG8_BAR; PG8_SCHED;
.LBB0_289:
	ds_read_b128 v[130:133], v223
	ds_read_b128 v[134:137], v223 offset:1024
	ds_read_b128 v[138:141], v223 offset:2048
	ds_read_b128 v[142:145], v223 offset:3072
	ds_read_b128 v[164:167], v224
	ds_read_b128 v[168:171], v224 offset:1024
	ds_read_b128 v[172:175], v224 offset:2048
	ds_read_b128 v[176:179], v224 offset:3072
	s_add_u32 s0, s4, 0x200
	s_addc_u32 s1, s5, 0
	s_cmp_eq_u32 s41, 40
	s_cselect_b32 s37, s31, s1
	s_cselect_b32 s36, s30, s0
	s_cselect_b32 s7, s35, s40
	s_cselect_b32 s6, s34, s39
	v_lshl_add_u64 v[160:161], s[4:5], 0, v[156:157]
	s_add_i32 m0, s51, 0xc000
	ds_read_b128 v[180:183], v225
	ds_read_b128 v[184:187], v225 offset:1024
	ds_read_b128 v[188:191], v225 offset:2048
	ds_read_b128 v[192:195], v225 offset:3072
	ds_read_b128 v[196:199], v225 offset:4096
	ds_read_b128 v[200:203], v225 offset:5120
	ds_read_b128 v[204:207], v225 offset:6144
	ds_read_b128 v[208:211], v225 offset:7168
	global_load_lds_dwordx4 v[160:161], off
	v_lshl_add_u64 v[160:161], s[4:5], 0, v[158:159]
	s_add_i32 m0, s51, 0xe000
	s_nop 0
	global_load_lds_dwordx4 v[160:161], off
	s_waitcnt vmcnt(8) lgkmcnt(0)
	s_barrier
	s_setprio 1
	v_mfma_f32_16x16x32_bf16 v[126:129], v[130:133], v[180:183], v[126:129]
	v_mfma_f32_16x16x32_bf16 v[122:125], v[138:141], v[180:183], v[122:125]
	v_mfma_f32_16x16x32_bf16 v[110:113], v[130:133], v[188:191], v[110:113]
	v_mfma_f32_16x16x32_bf16 v[106:109], v[138:141], v[188:191], v[106:109]
	v_mfma_f32_16x16x32_bf16 v[94:97], v[130:133], v[196:199], v[94:97]
	v_mfma_f32_16x16x32_bf16 v[90:93], v[138:141], v[196:199], v[90:93]
	v_mfma_f32_16x16x32_bf16 v[78:81], v[130:133], v[204:207], v[78:81]
	v_mfma_f32_16x16x32_bf16 v[74:77], v[138:141], v[204:207], v[74:77]
	v_mfma_f32_16x16x32_bf16 v[126:129], v[134:137], v[184:187], v[126:129]
	v_mfma_f32_16x16x32_bf16 v[122:125], v[142:145], v[184:187], v[122:125]
	v_mfma_f32_16x16x32_bf16 v[110:113], v[134:137], v[192:195], v[110:113]
	v_mfma_f32_16x16x32_bf16 v[106:109], v[142:145], v[192:195], v[106:109]
	v_mfma_f32_16x16x32_bf16 v[94:97], v[134:137], v[200:203], v[94:97]
	v_mfma_f32_16x16x32_bf16 v[90:93], v[142:145], v[200:203], v[90:93]
	v_mfma_f32_16x16x32_bf16 v[78:81], v[134:137], v[208:211], v[78:81]
	v_mfma_f32_16x16x32_bf16 v[74:77], v[142:145], v[208:211], v[74:77]
	v_mfma_f32_16x16x32_bf16 v[118:121], v[164:167], v[180:183], v[118:121]
	v_mfma_f32_16x16x32_bf16 v[114:117], v[172:175], v[180:183], v[114:117]
	v_mfma_f32_16x16x32_bf16 v[102:105], v[164:167], v[188:191], v[102:105]
	v_mfma_f32_16x16x32_bf16 v[98:101], v[172:175], v[188:191], v[98:101]
	v_mfma_f32_16x16x32_bf16 v[86:89], v[164:167], v[196:199], v[86:89]
	v_mfma_f32_16x16x32_bf16 v[82:85], v[172:175], v[196:199], v[82:85]
	v_mfma_f32_16x16x32_bf16 v[70:73], v[164:167], v[204:207], v[70:73]
	v_mfma_f32_16x16x32_bf16 v[66:69], v[172:175], v[204:207], v[66:69]
	v_mfma_f32_16x16x32_bf16 v[118:121], v[168:171], v[184:187], v[118:121]
	v_mfma_f32_16x16x32_bf16 v[114:117], v[176:179], v[184:187], v[114:117]
	v_mfma_f32_16x16x32_bf16 v[102:105], v[168:171], v[192:195], v[102:105]
	v_mfma_f32_16x16x32_bf16 v[98:101], v[176:179], v[192:195], v[98:101]
	v_mfma_f32_16x16x32_bf16 v[86:89], v[168:171], v[200:203], v[86:89]
	v_mfma_f32_16x16x32_bf16 v[82:85], v[176:179], v[200:203], v[82:85]
	v_mfma_f32_16x16x32_bf16 v[70:73], v[168:171], v[208:211], v[70:73]
	v_mfma_f32_16x16x32_bf16 v[66:69], v[176:179], v[208:211], v[66:69]
	s_barrier
	s_setprio 0
	s_add_i32 s4, s68, s50
	v_lshl_add_u64 v[160:161], s[6:7], 0, v[148:149]
	s_mov_b32 m0, s4
	ds_read_b128 v[180:183], v225 offset:16384
	ds_read_b128 v[184:187], v225 offset:17408
	ds_read_b128 v[188:191], v225 offset:18432
	ds_read_b128 v[192:195], v225 offset:19456
	ds_read_b128 v[196:199], v225 offset:20480
	ds_read_b128 v[200:203], v225 offset:21504
	ds_read_b128 v[204:207], v225 offset:22528
	ds_read_b128 v[208:211], v225 offset:23552
	global_load_lds_dwordx4 v[160:161], off
	s_add_i32 m0, s4, 0x2000
	s_add_u32 s4, s6, 0xb0000
	v_lshl_add_u64 v[162:163], s[6:7], 0, v[152:153]
	s_addc_u32 s5, s7, 0
	s_add_i32 s42, s69, s50
	global_load_lds_dwordx4 v[162:163], off
	v_lshl_add_u64 v[212:213], s[4:5], 0, v[148:149]
	s_mov_b32 m0, s42
	v_lshl_add_u64 v[214:215], s[36:37], 0, v[150:151]
	global_load_lds_dwordx4 v[212:213], off
	v_lshl_add_u64 v[212:213], s[4:5], 0, v[152:153]
	s_add_i32 m0, s42, 0x2000
	s_nop 0
	global_load_lds_dwordx4 v[212:213], off
	v_lshl_add_u64 v[212:213], s[36:37], 0, v[146:147]
	s_mov_b32 m0, s51
	s_nop 0
	global_load_lds_dwordx4 v[212:213], off
	s_mov_b32 m0, s52
	s_nop 0
	global_load_lds_dwordx4 v[214:215], off
	s_waitcnt vmcnt(8) lgkmcnt(0)
	s_barrier
	s_setprio 1
	v_mfma_f32_16x16x32_bf16 v[62:65], v[130:133], v[180:183], v[62:65]
	v_mfma_f32_16x16x32_bf16 v[58:61], v[138:141], v[180:183], v[58:61]
	v_mfma_f32_16x16x32_bf16 v[46:49], v[130:133], v[188:191], v[46:49]
	v_mfma_f32_16x16x32_bf16 v[42:45], v[138:141], v[188:191], v[42:45]
	v_mfma_f32_16x16x32_bf16 v[30:33], v[130:133], v[196:199], v[30:33]
	v_mfma_f32_16x16x32_bf16 v[26:29], v[138:141], v[196:199], v[26:29]
	v_mfma_f32_16x16x32_bf16 v[14:17], v[130:133], v[204:207], v[14:17]
	v_mfma_f32_16x16x32_bf16 v[10:13], v[138:141], v[204:207], v[10:13]
	v_mfma_f32_16x16x32_bf16 v[62:65], v[134:137], v[184:187], v[62:65]
	v_mfma_f32_16x16x32_bf16 v[58:61], v[142:145], v[184:187], v[58:61]
	v_mfma_f32_16x16x32_bf16 v[46:49], v[134:137], v[192:195], v[46:49]
	v_mfma_f32_16x16x32_bf16 v[42:45], v[142:145], v[192:195], v[42:45]
	v_mfma_f32_16x16x32_bf16 v[30:33], v[134:137], v[200:203], v[30:33]
	v_mfma_f32_16x16x32_bf16 v[26:29], v[142:145], v[200:203], v[26:29]
	v_mfma_f32_16x16x32_bf16 v[14:17], v[134:137], v[208:211], v[14:17]
	v_mfma_f32_16x16x32_bf16 v[10:13], v[142:145], v[208:211], v[10:13]
	v_mfma_f32_16x16x32_bf16 v[54:57], v[164:167], v[180:183], v[54:57]
	v_mfma_f32_16x16x32_bf16 v[50:53], v[172:175], v[180:183], v[50:53]
	v_mfma_f32_16x16x32_bf16 v[38:41], v[164:167], v[188:191], v[38:41]
	v_mfma_f32_16x16x32_bf16 v[34:37], v[172:175], v[188:191], v[34:37]
	v_mfma_f32_16x16x32_bf16 v[22:25], v[164:167], v[196:199], v[22:25]
	v_mfma_f32_16x16x32_bf16 v[18:21], v[172:175], v[196:199], v[18:21]
	v_mfma_f32_16x16x32_bf16 v[6:9], v[164:167], v[204:207], v[6:9]
	v_mfma_f32_16x16x32_bf16 v[2:5], v[172:175], v[204:207], v[2:5]
	v_mfma_f32_16x16x32_bf16 v[54:57], v[168:171], v[184:187], v[54:57]
	v_mfma_f32_16x16x32_bf16 v[50:53], v[176:179], v[184:187], v[50:53]
	v_mfma_f32_16x16x32_bf16 v[38:41], v[168:171], v[192:195], v[38:41]
	v_mfma_f32_16x16x32_bf16 v[34:37], v[176:179], v[192:195], v[34:37]
	v_mfma_f32_16x16x32_bf16 v[22:25], v[168:171], v[200:203], v[22:25]
	v_mfma_f32_16x16x32_bf16 v[18:21], v[176:179], v[200:203], v[18:21]
	v_mfma_f32_16x16x32_bf16 v[6:9], v[168:171], v[208:211], v[6:9]
	v_mfma_f32_16x16x32_bf16 v[2:5], v[176:179], v[208:211], v[2:5]
	s_barrier
	s_setprio 0
; #define PG8_STAGE(bufoff, gbase, voff) do { _Pragma("unroll") for (int _i = 0; _i < 2; ++_i) \
;         __builtin_amdgcn_global_load_lds((const unsigned*)((const char*)(gbase) + (voff)[_i]), (PG8_LAS unsigned*)(lds + (bufoff) + ldsw + _i * 8192), 16, 0, 0); } while (0)
; #define PG8_LDA(dst, b, h) do { _Pragma("unroll") for (int m = 0; m < 4; ++m) _Pragma("unroll") for (int k = 0; k < 2; ++k) dst[m][k] = *(const PG8_LAS bf16x8*)(lds + PG8_SA(b, h) + aoff + m * 2048 + k * 1024); } while (0)
; #define PG8_LDB(dst, b, h) do { _Pragma("unroll") for (int n = 0; n < 2; ++n) _Pragma("unroll") for (int k = 0; k < 2; ++k) dst[n][k] = *(const PG8_LAS bf16x8*)(lds + PG8_SB(b, h) + boff + n * 2048 + k * 1024); } while (0)
; #define PG8_MMA(ai, bj, At, Bt) do { __builtin_amdgcn_s_setprio(1); _Pragma("unroll") for (int m = 0; m < 4; ++m) _Pragma("unroll") for (int n = 0; n < 2; ++n) _Pragma("unroll") for (int k = 0; k < 2; ++k) \
;         acc[ai][bj][m][n] = __builtin_amdgcn_mfma_f32_16x16x32_bf16(Bt[n][k], At[m][k], acc[ai][bj][m][n], 0, 0, 0); __builtin_amdgcn_s_setprio(0); } while (0)
; #define PG8_WAIT_V(n) asm volatile("s_waitcnt vmcnt(" #n ")" ::: "memory")
; #define PG8_WAIT_L(n) asm volatile("s_waitcnt lgkmcnt(" #n ")" ::: "memory")
; #define PG8_BAR __builtin_amdgcn_s_barrier()
; #define PG8_SCHED __builtin_amdgcn_sched_barrier(0)
; template <class Epi, class Sched, bool ALIGN_EPI = false, bool SP2 = false>
; __device__ __forceinline__ void gemm_phase(PG8_LAS unsigned char* lds, const Gemm g, const Sched& S, const Epi& E) {
;     ...
;             PG8_LDB(B0, 1, 0); PG8_LDB(B1, 1, 1); PG8_SCHED; PG8_LDA(At, 1, 0); PG8_STAGE(PG8_SA(0, 1), a2 + hstep, voffA);
;             PG8_WAIT_V(8); PG8_WAIT_L(0); PG8_BAR; PG8_MMA(0, 0, At, B0); PG8_MMA(0, 1, At, B1); PG8_BAR; PG8_SCHED;
.Lpz2_mid:
	s_add_i32 s42, 0, 0x18000
	s_add_i32 s43, 0, 0x1c000
	v_add_u32_e32 v142, s42, v222
	v_add_u32_e32 v154, s43, v222
	ds_read_b128 v[130:133], v142
	ds_read_b128 v[134:137], v142 offset:1024
	ds_read_b128 v[138:141], v142 offset:2048
	ds_read_b128 v[142:145], v142 offset:3072
	ds_read_b128 v[164:167], v154
	ds_read_b128 v[168:171], v154 offset:1024
	ds_read_b128 v[172:175], v154 offset:2048
	ds_read_b128 v[176:179], v154 offset:3072
	s_add_u32 s4, s36, 0xb0000
	s_addc_u32 s5, s37, 0
	s_mov_b32 m0, s53
	v_lshl_add_u64 v[216:217], s[4:5], 0, v[146:147]
	ds_read_b128 v[180:183], v225 offset:32768
	ds_read_b128 v[184:187], v225 offset:33792
	ds_read_b128 v[188:191], v225 offset:34816
	ds_read_b128 v[192:195], v225 offset:35840
	ds_read_b128 v[196:199], v225 offset:36864
	ds_read_b128 v[200:203], v225 offset:37888
	ds_read_b128 v[204:207], v225 offset:38912
	ds_read_b128 v[208:211], v225 offset:39936
	global_load_lds_dwordx4 v[216:217], off
	v_lshl_add_u64 v[216:217], s[4:5], 0, v[150:151]
	s_mov_b32 m0, s54
	s_nop 0
	global_load_lds_dwordx4 v[216:217], off
	s_waitcnt vmcnt(8) lgkmcnt(0)
	s_barrier
	s_setprio 1
	v_mfma_f32_16x16x32_bf16 v[126:129], v[130:133], v[180:183], v[126:129]
	v_mfma_f32_16x16x32_bf16 v[122:125], v[138:141], v[180:183], v[122:125]
	v_mfma_f32_16x16x32_bf16 v[110:113], v[130:133], v[188:191], v[110:113]
	v_mfma_f32_16x16x32_bf16 v[106:109], v[138:141], v[188:191], v[106:109]
	v_mfma_f32_16x16x32_bf16 v[94:97], v[130:133], v[196:199], v[94:97]
	v_mfma_f32_16x16x32_bf16 v[90:93], v[138:141], v[196:199], v[90:93]
	v_mfma_f32_16x16x32_bf16 v[78:81], v[130:133], v[204:207], v[78:81]
	v_mfma_f32_16x16x32_bf16 v[74:77], v[138:141], v[204:207], v[74:77]
	v_mfma_f32_16x16x32_bf16 v[126:129], v[134:137], v[184:187], v[126:129]
	v_mfma_f32_16x16x32_bf16 v[122:125], v[142:145], v[184:187], v[122:125]
	v_mfma_f32_16x16x32_bf16 v[110:113], v[134:137], v[192:195], v[110:113]
	v_mfma_f32_16x16x32_bf16 v[106:109], v[142:145], v[192:195], v[106:109]
	v_mfma_f32_16x16x32_bf16 v[94:97], v[134:137], v[200:203], v[94:97]
	v_mfma_f32_16x16x32_bf16 v[90:93], v[142:145], v[200:203], v[90:93]
	v_mfma_f32_16x16x32_bf16 v[78:81], v[134:137], v[208:211], v[78:81]
	v_mfma_f32_16x16x32_bf16 v[74:77], v[142:145], v[208:211], v[74:77]
	v_mfma_f32_16x16x32_bf16 v[118:121], v[164:167], v[180:183], v[118:121]
	v_mfma_f32_16x16x32_bf16 v[114:117], v[172:175], v[180:183], v[114:117]
	v_mfma_f32_16x16x32_bf16 v[102:105], v[164:167], v[188:191], v[102:105]
	v_mfma_f32_16x16x32_bf16 v[98:101], v[172:175], v[188:191], v[98:101]
	v_mfma_f32_16x16x32_bf16 v[86:89], v[164:167], v[196:199], v[86:89]
	v_mfma_f32_16x16x32_bf16 v[82:85], v[172:175], v[196:199], v[82:85]
	v_mfma_f32_16x16x32_bf16 v[70:73], v[164:167], v[204:207], v[70:73]
	v_mfma_f32_16x16x32_bf16 v[66:69], v[172:175], v[204:207], v[66:69]
	v_mfma_f32_16x16x32_bf16 v[118:121], v[168:171], v[184:187], v[118:121]
	v_mfma_f32_16x16x32_bf16 v[114:117], v[176:179], v[184:187], v[114:117]
	v_mfma_f32_16x16x32_bf16 v[102:105], v[168:171], v[192:195], v[102:105]
	v_mfma_f32_16x16x32_bf16 v[98:101], v[176:179], v[192:195], v[98:101]
	v_mfma_f32_16x16x32_bf16 v[86:89], v[168:171], v[200:203], v[86:89]
	v_mfma_f32_16x16x32_bf16 v[82:85], v[176:179], v[200:203], v[82:85]
	v_mfma_f32_16x16x32_bf16 v[70:73], v[168:171], v[208:211], v[70:73]
	v_mfma_f32_16x16x32_bf16 v[66:69], v[176:179], v[208:211], v[66:69]
	s_barrier
; #define PG8_STAGE(bufoff, gbase, voff) do { _Pragma("unroll") for (int _i = 0; _i < 2; ++_i) \
;         __builtin_amdgcn_global_load_lds((const unsigned*)((const char*)(gbase) + (voff)[_i]), (PG8_LAS unsigned*)(lds + (bufoff) + ldsw + _i * 8192), 16, 0, 0); } while (0)
; #define PG8_LDA(dst, b, h) do { _Pragma("unroll") for (int m = 0; m < 4; ++m) _Pragma("unroll") for (int k = 0; k < 2; ++k) dst[m][k] = *(const PG8_LAS bf16x8*)(lds + PG8_SA(b, h) + aoff + m * 2048 + k * 1024); } while (0)
; #define PG8_MMA(ai, bj, At, Bt) do { __builtin_amdgcn_s_setprio(1); _Pragma("unroll") for (int m = 0; m < 4; ++m) _Pragma("unroll") for (int n = 0; n < 2; ++n) _Pragma("unroll") for (int k = 0; k < 2; ++k) \
;         acc[ai][bj][m][n] = __builtin_amdgcn_mfma_f32_16x16x32_bf16(Bt[n][k], At[m][k], acc[ai][bj][m][n], 0, 0, 0); __builtin_amdgcn_s_setprio(0); } while (0)
; #define PG8_WAIT_V(n) asm volatile("s_waitcnt vmcnt(" #n ")" ::: "memory")
; #define PG8_WAIT_L(n) asm volatile("s_waitcnt lgkmcnt(" #n ")" ::: "memory")
; #define PG8_BAR __builtin_amdgcn_s_barrier()
; #define PG8_SCHED __builtin_amdgcn_sched_barrier(0)
; template <class Epi, class Sched, bool ALIGN_EPI = false, bool SP2 = false>
; __device__ __forceinline__ void gemm_phase(PG8_LAS unsigned char* lds, const Gemm g, const Sched& S, const Epi& E) {
;     ...
;             PG8_LDA(At, 1, 1); PG8_STAGE(PG8_SB(1, 0), b3, voffB); PG8_STAGE(PG8_SB(1, 1), b3 + hstep, voffB); PG8_STAGE(PG8_SA(1, 0), a3, voffA);
;             PG8_WAIT_V(8); PG8_WAIT_L(0); PG8_BAR; PG8_MMA(1, 0, At, B0); PG8_MMA(1, 1, At, B1); PG8_BAR; PG8_SCHED;
;     ...
;         if constexpr (ALIGN_EPI) { if (wr == 0) PG8_BAR; }
	s_setprio 0
	s_add_i32 s4, s42, s50
	v_lshl_add_u64 v[160:161], v[160:161], 0, s[22:23]
	s_mov_b32 m0, s4
	ds_read_b128 v[180:183], v225 offset:49152
	ds_read_b128 v[184:187], v225 offset:50176
	ds_read_b128 v[188:191], v225 offset:51200
	ds_read_b128 v[192:195], v225 offset:52224
	ds_read_b128 v[196:199], v225 offset:53248
	ds_read_b128 v[200:203], v225 offset:54272
	ds_read_b128 v[204:207], v225 offset:55296
	ds_read_b128 v[208:211], v225 offset:56320
	global_load_lds_dwordx4 v[160:161], off
	s_add_i32 m0, s4, 0x2000
	s_add_u32 s4, s6, 0xb0080
	v_lshl_add_u64 v[160:161], v[162:163], 0, s[22:23]
	s_addc_u32 s5, s7, 0
	s_add_i32 s6, s43, s50
	global_load_lds_dwordx4 v[160:161], off
	v_lshl_add_u64 v[160:161], s[4:5], 0, v[148:149]
	s_mov_b32 m0, s6
	s_nop 0
	global_load_lds_dwordx4 v[160:161], off
	v_lshl_add_u64 v[160:161], s[4:5], 0, v[152:153]
	s_add_i32 m0, s6, 0x2000
	s_nop 0
	global_load_lds_dwordx4 v[160:161], off
	v_lshl_add_u64 v[160:161], v[212:213], 0, s[24:25]
	s_mov_b32 m0, s63
	s_nop 0
	global_load_lds_dwordx4 v[160:161], off
	v_lshl_add_u64 v[160:161], v[214:215], 0, s[24:25]
	s_mov_b32 m0, s64
	s_nop 0
	global_load_lds_dwordx4 v[160:161], off
	s_waitcnt vmcnt(8) lgkmcnt(0)
	s_barrier
	s_setprio 1
	v_mfma_f32_16x16x32_bf16 v[62:65], v[130:133], v[180:183], v[62:65]
	v_mfma_f32_16x16x32_bf16 v[58:61], v[138:141], v[180:183], v[58:61]
	v_mfma_f32_16x16x32_bf16 v[46:49], v[130:133], v[188:191], v[46:49]
	v_mfma_f32_16x16x32_bf16 v[42:45], v[138:141], v[188:191], v[42:45]
	v_mfma_f32_16x16x32_bf16 v[30:33], v[130:133], v[196:199], v[30:33]
	v_mfma_f32_16x16x32_bf16 v[26:29], v[138:141], v[196:199], v[26:29]
	v_mfma_f32_16x16x32_bf16 v[14:17], v[130:133], v[204:207], v[14:17]
	v_mfma_f32_16x16x32_bf16 v[10:13], v[138:141], v[204:207], v[10:13]
	v_mfma_f32_16x16x32_bf16 v[62:65], v[134:137], v[184:187], v[62:65]
	v_mfma_f32_16x16x32_bf16 v[58:61], v[142:145], v[184:187], v[58:61]
	v_mfma_f32_16x16x32_bf16 v[46:49], v[134:137], v[192:195], v[46:49]
	v_mfma_f32_16x16x32_bf16 v[42:45], v[142:145], v[192:195], v[42:45]
	v_mfma_f32_16x16x32_bf16 v[30:33], v[134:137], v[200:203], v[30:33]
	v_mfma_f32_16x16x32_bf16 v[26:29], v[142:145], v[200:203], v[26:29]
	v_mfma_f32_16x16x32_bf16 v[14:17], v[134:137], v[208:211], v[14:17]
	v_mfma_f32_16x16x32_bf16 v[10:13], v[142:145], v[208:211], v[10:13]
	v_mfma_f32_16x16x32_bf16 v[54:57], v[164:167], v[180:183], v[54:57]
	v_mfma_f32_16x16x32_bf16 v[50:53], v[172:175], v[180:183], v[50:53]
	v_mfma_f32_16x16x32_bf16 v[38:41], v[164:167], v[188:191], v[38:41]
	v_mfma_f32_16x16x32_bf16 v[34:37], v[172:175], v[188:191], v[34:37]
	v_mfma_f32_16x16x32_bf16 v[22:25], v[164:167], v[196:199], v[22:25]
	v_mfma_f32_16x16x32_bf16 v[18:21], v[172:175], v[196:199], v[18:21]
	v_mfma_f32_16x16x32_bf16 v[6:9], v[164:167], v[204:207], v[6:9]
	v_mfma_f32_16x16x32_bf16 v[2:5], v[172:175], v[204:207], v[2:5]
	v_mfma_f32_16x16x32_bf16 v[54:57], v[168:171], v[184:187], v[54:57]
	v_mfma_f32_16x16x32_bf16 v[50:53], v[176:179], v[184:187], v[50:53]
	v_mfma_f32_16x16x32_bf16 v[38:41], v[168:171], v[192:195], v[38:41]
	v_mfma_f32_16x16x32_bf16 v[34:37], v[176:179], v[192:195], v[34:37]
	v_mfma_f32_16x16x32_bf16 v[22:25], v[168:171], v[200:203], v[22:25]
	v_mfma_f32_16x16x32_bf16 v[18:21], v[176:179], v[200:203], v[18:21]
	v_mfma_f32_16x16x32_bf16 v[6:9], v[168:171], v[208:211], v[6:9]
	v_mfma_f32_16x16x32_bf16 v[2:5], v[176:179], v[208:211], v[2:5]
	s_barrier
	s_setprio 0
	s_add_i32 s41, s41, 2
	s_add_u32 s39, s39, 0x100
	s_addc_u32 s40, s40, 0
	s_cmp_gt_u32 s41, 41
	s_mov_b64 s[4:5], s[0:1]
	s_cbranch_scc0 .LBB0_289
	s_and_b64 vcc, exec, s[26:27]
	s_cbranch_vccz .LBB0_292
	s_barrier

;     __host__ __device__ bool next(int i, Unit& u) const { if (!b.next(i >> 1, u)) return false; u.sel = i & 1; return true; }
; #define PG8_STAGE(bufoff, gbase, voff) do { _Pragma("unroll") for (int _i = 0; _i < 2; ++_i) \
;         __builtin_amdgcn_global_load_lds((const unsigned*)((const char*)(gbase) + (voff)[_i]), (PG8_LAS unsigned*)(lds + (bufoff) + ldsw + _i * 8192), 16, 0, 0); } while (0)
; #define PG8_LDA(dst, b, h) do { _Pragma("unroll") for (int m = 0; m < 4; ++m) _Pragma("unroll") for (int k = 0; k < 2; ++k) dst[m][k] = *(const PG8_LAS bf16x8*)(lds + PG8_SA(b, h) + aoff + m * 2048 + k * 1024); } while (0)
; #define PG8_WAIT_V(n) asm volatile("s_waitcnt vmcnt(" #n ")" ::: "memory")
;     __host__ __device__ bool next(int i, Unit& u) const {
;         const long L = (long)i * G + c; if (L >= nwg) return false;
;         int wgid = (int)L; { const int q = nwg / NXCD, r = nwg % NXCD, xcd = wgid % NXCD, off = wgid / NXCD; wgid = (xcd < r ? xcd * (q + 1) : r * (q + 1) + (xcd - r) * q) + off; }
;         const int nig = WGM * nN, gid = wgid / nig, fm = gid * WGM, gsz = (nM - fm) < WGM ? (nM - fm) : WGM;
;         u.pm = fm + ((wgid % nig) % gsz); u.pn = (wgid % nig) / gsz; u.sel = 0; return true;
; template <class Epi, class Sched, bool ALIGN_EPI = false, bool SP2 = false>
; __device__ __forceinline__ void gemm_phase(PG8_LAS unsigned char* lds, const Gemm g, const Sched& S, const Epi& E) {
;     ...
;         const bool has_next = S.next(ui + 1, nxt);
;         const char* nA = has_next ? PG8_ABASE(nxt) : cA; const char* nB = has_next ? PG8_BBASE(nxt) : cB;
;         for (int t = 0; t < nt; t += 2) {
;             const bool last = (t == nt - 2);
;             const char* a1 = cA + (size_t)(t + 1) * kstepA;
;             const char* a2 = last ? nA : cA + (size_t)(t + 2) * kstepA; const char* b2 = last ? nB : cB + (size_t)(t + 2) * kstep;
;             const char* a3 = a2 + kstepA; const char* b3 = b2 + kstep;
;             if (last && has_next) S.a_ready(nxt);
;             if constexpr (SP2) {
;             PG8_LDB(B0, 0, 0); PG8_LDB(B1, 0, 1); PG8_SCHED; PG8_LDA(At, 0, 0); PG8_STAGE(PG8_SA(1, 1), a1 + hstep, voffA);
;             PG8_WAIT_V(8); PG8_WAIT_L(0); PG8_BAR; PG8_MMA(0, 0, At, B0); PG8_MMA(0, 1, At, B1); PG8_BAR; PG8_SCHED;
;             if constexpr (Epi::PREFETCH) { if (t == tpf) E.prefetch(cur, wid, lane); }
.LBB0_435:
	s_ashr_i32 s5, s4, 31
	s_lshl_b32 s8, s6, 8
	s_lshl_b64 s[28:29], s[4:5], 14
	s_ashr_i32 s5, s4, 5
	s_ashr_i32 s9, s8, 31
	s_add_u32 s52, s14, s28
	s_mul_hi_i32 s54, s5, 0x6800
	s_mulk_i32 s5, 0x6800
	s_addc_u32 s53, s88, s29
	s_add_u32 s5, s77, s5
	s_addc_u32 s55, s78, s54
	s_lshl_b64 s[28:29], s[8:9], 2
	s_add_u32 s54, s5, s28
	s_addc_u32 s55, s55, s29
	s_add_u32 s5, s56, 0x100
	v_lshl_add_u64 v[196:197], s[10:11], 0, v[188:189]
	v_lshl_add_u64 v[198:199], s[10:11], 0, v[190:191]
	s_addc_u32 s9, s57, 0
	s_mov_b32 s28, 0
	s_mov_b64 s[56:57], 0
	ds_read_b128 v[162:165], v208
	ds_read_b128 v[166:169], v208 offset:1024
	ds_read_b128 v[170:173], v208 offset:2048
	ds_read_b128 v[174:177], v208 offset:3072
	ds_read_b128 v[146:149], v209
	ds_read_b128 v[150:153], v209 offset:1024
	ds_read_b128 v[154:157], v209 offset:2048
	ds_read_b128 v[158:161], v209 offset:3072
	v_lshl_add_u64 v[42:43], v[196:197], 0, s[56:57]
	s_add_i32 m0, s69, 0xc000
	ds_read_b128 v[212:215], v210
	ds_read_b128 v[216:219], v210 offset:1024
	ds_read_b128 v[222:225], v210 offset:2048
	ds_read_b128 v[226:229], v210 offset:3072
	ds_read_b128 v[230:233], v210 offset:4096
	ds_read_b128 v[234:237], v210 offset:5120
	ds_read_b128 v[238:241], v210 offset:6144
	ds_read_b128 v[242:245], v210 offset:7168
	global_load_lds_dwordx4 v[42:43], off
	v_lshl_add_u64 v[42:43], v[198:199], 0, s[56:57]
	s_add_i32 m0, s69, 0xe000
	s_nop 0
	global_load_lds_dwordx4 v[42:43], off
	s_add_i32 s15, s15, 1
	s_mul_i32 s2, s15, s86
	s_mul_hi_u32 s3, s15, s33
	s_add_i32 s3, s3, s2
	s_mul_i32 s2, s15, s33
	v_readlane_b32 s98, v254, 12
	s_add_u32 s100, s2, s98
	s_addc_u32 s101, s3, s87
	v_cmp_lt_i64_e64 s[2:3], s[100:101], v[192:193]
	s_ashr_i32 s98, s100, 31
	s_lshr_b32 s98, s98, 29
	s_add_i32 s98, s100, s98
	s_ashr_i32 s7, s98, 3
	s_and_b32 s98, s98, -8
	s_sub_i32 s98, s100, s98
	s_cmp_lt_i32 s98, 0
	s_movk_i32 s100, 0x1a1
	s_cselect_b32 s100, s100, 0x1a0
	s_mul_i32 s98, s98, s100
	s_add_i32 s98, s98, s7
	s_mul_hi_i32 s7, s98, 0x4ec4ec4f
	s_lshr_b32 s100, s7, 31
	s_ashr_i32 s7, s7, 4
	s_add_i32 s7, s7, s100
	s_lshl_b32 s100, s7, 1
	s_mul_i32 s7, s7, 52
	s_sub_i32 s98, s98, s7
	s_lshr_b32 s44, s98, 1
	s_and_b32 s98, s98, 1
	s_add_i32 s46, s100, s98
	s_ashr_i32 s47, s46, 31
	s_lshl_b64 s[100:101], s[46:47], 19
	s_add_u32 s48, s64, s100
	s_addc_u32 s49, s65, s101
	s_and_b64 s[100:101], s[2:3], exec
	s_cselect_b32 s7, s49, s65
	s_cselect_b32 s31, s48, s64
	s_ashr_i32 s45, s44, 31
	s_lshl_b64 s[100:101], s[44:45], 19
	s_add_u32 s50, s66, s100
	s_addc_u32 s51, s67, s101
	s_and_b64 s[100:101], s[2:3], exec
	s_cselect_b32 s45, s51, s67
	s_cselect_b32 s47, s50, s66
	s_waitcnt vmcnt(8) lgkmcnt(0)
	s_barrier
	s_setprio 1
	v_mfma_f32_16x16x32_bf16 v[42:45], v[162:165], v[212:215], 0
	v_mfma_f32_16x16x32_bf16 v[46:49], v[170:173], v[212:215], 0
	v_mfma_f32_16x16x32_bf16 v[50:53], v[162:165], v[222:225], 0
	v_mfma_f32_16x16x32_bf16 v[54:57], v[170:173], v[222:225], 0
	v_mfma_f32_16x16x32_bf16 v[110:113], v[162:165], v[230:233], 0
	v_mfma_f32_16x16x32_bf16 v[106:109], v[170:173], v[230:233], 0
	v_mfma_f32_16x16x32_bf16 v[94:97], v[162:165], v[238:241], 0
	v_mfma_f32_16x16x32_bf16 v[90:93], v[170:173], v[238:241], 0
	v_mfma_f32_16x16x32_bf16 v[42:45], v[166:169], v[216:219], v[42:45]
	v_mfma_f32_16x16x32_bf16 v[46:49], v[174:177], v[216:219], v[46:49]
	v_mfma_f32_16x16x32_bf16 v[50:53], v[166:169], v[226:229], v[50:53]
	v_mfma_f32_16x16x32_bf16 v[54:57], v[174:177], v[226:229], v[54:57]
	v_mfma_f32_16x16x32_bf16 v[110:113], v[166:169], v[234:237], v[110:113]
	v_mfma_f32_16x16x32_bf16 v[106:109], v[174:177], v[234:237], v[106:109]
	v_mfma_f32_16x16x32_bf16 v[94:97], v[166:169], v[242:245], v[94:97]
	v_mfma_f32_16x16x32_bf16 v[90:93], v[174:177], v[242:245], v[90:93]
	v_mfma_f32_16x16x32_bf16 v[122:125], v[146:149], v[212:215], 0
	v_mfma_f32_16x16x32_bf16 v[134:137], v[150:153], v[216:219], v[122:125]
	v_mfma_f32_16x16x32_bf16 v[122:125], v[154:157], v[212:215], 0
	v_mfma_f32_16x16x32_bf16 v[118:121], v[146:149], v[222:225], 0
	v_mfma_f32_16x16x32_bf16 v[114:117], v[154:157], v[222:225], 0
	v_mfma_f32_16x16x32_bf16 v[102:105], v[146:149], v[230:233], 0
	v_mfma_f32_16x16x32_bf16 v[98:101], v[154:157], v[230:233], 0
	v_mfma_f32_16x16x32_bf16 v[86:89], v[146:149], v[238:241], 0
	v_mfma_f32_16x16x32_bf16 v[82:85], v[154:157], v[238:241], 0
	v_mfma_f32_16x16x32_bf16 v[130:133], v[158:161], v[216:219], v[122:125]
	v_mfma_f32_16x16x32_bf16 v[118:121], v[150:153], v[226:229], v[118:121]
	v_mfma_f32_16x16x32_bf16 v[114:117], v[158:161], v[226:229], v[114:117]
	v_mfma_f32_16x16x32_bf16 v[102:105], v[150:153], v[234:237], v[102:105]
	v_mfma_f32_16x16x32_bf16 v[98:101], v[158:161], v[234:237], v[98:101]
	v_mfma_f32_16x16x32_bf16 v[86:89], v[150:153], v[242:245], v[86:89]
	v_mfma_f32_16x16x32_bf16 v[82:85], v[158:161], v[242:245], v[82:85]
	s_barrier
	s_setprio 0
	s_cmp_lg_u32 s63, s28
	s_cbranch_scc1 .Lpz3_a
	v_mov_b32_e32 v186, v207
	s_add_i32 m0, s62, 0x20000
	v_lshl_add_u64 v[122:123], s[52:53], 0, v[186:187]
	s_mov_b64 s[58:59], 0x400
	global_load_lds_dwordx4 v186, s[52:53]
	v_lshl_add_u64 v[122:123], v[122:123], 0, s[58:59]
	s_add_i32 m0, s62, 0x20400
	s_andn2_b64 vcc, exec, s[40:41]
	global_load_lds_dwordx4 v[122:123], off
	s_cbranch_vccnz .Lpz3_a
	v_lshl_add_u64 v[122:123], s[54:55], 0, v[186:187]
	s_mov_b32 m0, s30
	s_nop 0
	global_load_lds_dwordx4 v[122:123], off
	s_branch .Lpz3_a
; #define PG8_STAGE(bufoff, gbase, voff) do { _Pragma("unroll") for (int _i = 0; _i < 2; ++_i) \
;         __builtin_amdgcn_global_load_lds((const unsigned*)((const char*)(gbase) + (voff)[_i]), (PG8_LAS unsigned*)(lds + (bufoff) + ldsw + _i * 8192), 16, 0, 0); } while (0)
; #define PG8_LDA(dst, b, h) do { _Pragma("unroll") for (int m = 0; m < 4; ++m) _Pragma("unroll") for (int k = 0; k < 2; ++k) dst[m][k] = *(const PG8_LAS bf16x8*)(lds + PG8_SA(b, h) + aoff + m * 2048 + k * 1024); } while (0)
; #define PG8_MMA(ai, bj, At, Bt) do { __builtin_amdgcn_s_setprio(1); _Pragma("unroll") for (int m = 0; m < 4; ++m) _Pragma("unroll") for (int n = 0; n < 2; ++n) _Pragma("unroll") for (int k = 0; k < 2; ++k) \
;         acc[ai][bj][m][n] = __builtin_amdgcn_mfma_f32_16x16x32_bf16(Bt[n][k], At[m][k], acc[ai][bj][m][n], 0, 0, 0); __builtin_amdgcn_s_setprio(0); } while (0)
; #define PG8_WAIT_V(n) asm volatile("s_waitcnt vmcnt(" #n ")" ::: "memory")
; #define PG8_WAIT_L(n) asm volatile("s_waitcnt lgkmcnt(" #n ")" ::: "memory")
; #define PG8_BAR __builtin_amdgcn_s_barrier()
; #define PG8_SCHED __builtin_amdgcn_sched_barrier(0)
; template <class Epi, class Sched, bool ALIGN_EPI = false, bool SP2 = false>
; __device__ __forceinline__ void gemm_phase(PG8_LAS unsigned char* lds, const Gemm g, const Sched& S, const Epi& E) {
;     ...
;             PG8_LDA(At, 0, 1); PG8_STAGE(PG8_SB(0, 0), b2, voffB); PG8_STAGE(PG8_SB(0, 1), b2 + hstep, voffB); PG8_STAGE(PG8_SA(0, 0), a2, voffA);
;             PG8_WAIT_V(8); PG8_WAIT_L(0); PG8_BAR; PG8_MMA(1, 0, At, B0); PG8_MMA(1, 1, At, B1); PG8_BAR; PG8_SCHED;
.Lpz3_a:
	s_add_u32 s29, s10, s56
	s_addc_u32 s58, s11, s57
	s_add_u32 s29, s29, 0x100
	s_addc_u32 s58, s58, 0
	s_add_u32 vcc_lo, s5, s56
	s_addc_u32 s59, s9, s57
	s_cmpk_eq_i32 s56, 0x700
	s_cselect_b32 s61, s7, s58
	s_cselect_b32 s59, s45, s59
	s_cselect_b32 s58, s47, vcc_lo
	s_mov_b32 m0, s70
	s_cselect_b32 s60, s31, s29
	v_lshl_add_u64 v[204:205], s[58:59], 0, v[180:181]
	s_add_u32 vcc_lo, s58, 0x40000
	ds_read_b128 v[122:125], v210 offset:16384
	ds_read_b128 v[126:129], v210 offset:17408
	ds_read_b128 v[138:141], v210 offset:18432
	ds_read_b128 v[142:145], v210 offset:19456
	ds_read_b128 v[212:215], v210 offset:20480
	ds_read_b128 v[216:219], v210 offset:21504
	ds_read_b128 v[222:225], v210 offset:22528
	ds_read_b128 v[226:229], v210 offset:23552
	global_load_lds_dwordx4 v[204:205], off
	v_lshl_add_u64 v[246:247], s[58:59], 0, v[184:185]
	s_mov_b32 m0, s71
	s_addc_u32 vcc_hi, s59, 0
	global_load_lds_dwordx4 v[246:247], off
	v_lshl_add_u64 v[230:231], vcc, 0, v[180:181]
	s_mov_b32 m0, s72
	v_lshl_add_u64 v[248:249], s[60:61], 0, v[178:179]
	global_load_lds_dwordx4 v[230:231], off
	v_lshl_add_u64 v[230:231], vcc, 0, v[184:185]
	s_mov_b32 m0, s73
	v_lshl_add_u64 v[250:251], s[60:61], 0, v[182:183]
	global_load_lds_dwordx4 v[230:231], off
	s_mov_b32 m0, s69
	s_nop 0
	global_load_lds_dwordx4 v[248:249], off
	s_mov_b32 m0, s74
	s_nop 0
	global_load_lds_dwordx4 v[250:251], off
	s_waitcnt vmcnt(8) lgkmcnt(0)
	s_barrier
	s_setprio 1
	v_mfma_f32_16x16x32_bf16 v[78:81], v[162:165], v[122:125], 0
	v_mfma_f32_16x16x32_bf16 v[74:77], v[170:173], v[122:125], 0
	v_mfma_f32_16x16x32_bf16 v[62:65], v[162:165], v[138:141], 0
	v_mfma_f32_16x16x32_bf16 v[58:61], v[170:173], v[138:141], 0
	v_mfma_f32_16x16x32_bf16 v[30:33], v[162:165], v[212:215], 0
	v_mfma_f32_16x16x32_bf16 v[26:29], v[170:173], v[212:215], 0
	v_mfma_f32_16x16x32_bf16 v[14:17], v[162:165], v[222:225], 0
	v_mfma_f32_16x16x32_bf16 v[10:13], v[170:173], v[222:225], 0
	v_mfma_f32_16x16x32_bf16 v[78:81], v[166:169], v[126:129], v[78:81]
	v_mfma_f32_16x16x32_bf16 v[74:77], v[174:177], v[126:129], v[74:77]
	v_mfma_f32_16x16x32_bf16 v[62:65], v[166:169], v[142:145], v[62:65]
	v_mfma_f32_16x16x32_bf16 v[58:61], v[174:177], v[142:145], v[58:61]
	v_mfma_f32_16x16x32_bf16 v[30:33], v[166:169], v[216:219], v[30:33]
	v_mfma_f32_16x16x32_bf16 v[26:29], v[174:177], v[216:219], v[26:29]
	v_mfma_f32_16x16x32_bf16 v[14:17], v[166:169], v[226:229], v[14:17]
	v_mfma_f32_16x16x32_bf16 v[10:13], v[174:177], v[226:229], v[10:13]
	v_mfma_f32_16x16x32_bf16 v[70:73], v[146:149], v[122:125], 0
	v_mfma_f32_16x16x32_bf16 v[66:69], v[154:157], v[122:125], 0
	v_mfma_f32_16x16x32_bf16 v[38:41], v[146:149], v[138:141], 0
	v_mfma_f32_16x16x32_bf16 v[34:37], v[154:157], v[138:141], 0
	v_mfma_f32_16x16x32_bf16 v[22:25], v[146:149], v[212:215], 0
	v_mfma_f32_16x16x32_bf16 v[18:21], v[154:157], v[212:215], 0
	v_mfma_f32_16x16x32_bf16 v[6:9], v[146:149], v[222:225], 0
	v_mfma_f32_16x16x32_bf16 v[2:5], v[154:157], v[222:225], 0
	v_mfma_f32_16x16x32_bf16 v[70:73], v[150:153], v[126:129], v[70:73]
	v_mfma_f32_16x16x32_bf16 v[66:69], v[158:161], v[126:129], v[66:69]
	v_mfma_f32_16x16x32_bf16 v[38:41], v[150:153], v[142:145], v[38:41]
	v_mfma_f32_16x16x32_bf16 v[34:37], v[158:161], v[142:145], v[34:37]
	v_mfma_f32_16x16x32_bf16 v[22:25], v[150:153], v[216:219], v[22:25]
	v_mfma_f32_16x16x32_bf16 v[18:21], v[158:161], v[216:219], v[18:21]
	v_mfma_f32_16x16x32_bf16 v[6:9], v[150:153], v[226:229], v[6:9]
	v_mfma_f32_16x16x32_bf16 v[2:5], v[158:161], v[226:229], v[2:5]
	s_barrier
	s_setprio 0
	s_branch .Lpz3_mid
.LBB0_438:
	s_add_u32 s29, s10, s56
	s_addc_u32 s58, s11, s57
	s_add_u32 s29, s29, 0x100
	s_addc_u32 s58, s58, 0
	s_add_u32 vcc_lo, s5, s56
	s_addc_u32 s59, s9, s57
	s_cmpk_eq_i32 s56, 0x700
	s_cselect_b32 s61, s7, s58
	s_cselect_b32 s59, s45, s59
	s_cselect_b32 s58, s47, vcc_lo
	s_mov_b32 m0, s70
	s_cselect_b32 s60, s31, s29
	v_lshl_add_u64 v[204:205], s[58:59], 0, v[180:181]
	s_add_u32 vcc_lo, s58, 0x40000
	ds_read_b128 v[122:125], v210 offset:16384
	ds_read_b128 v[126:129], v210 offset:17408
	ds_read_b128 v[138:141], v210 offset:18432
	ds_read_b128 v[142:145], v210 offset:19456
	ds_read_b128 v[212:215], v210 offset:20480
	ds_read_b128 v[216:219], v210 offset:21504
	ds_read_b128 v[222:225], v210 offset:22528
	ds_read_b128 v[226:229], v210 offset:23552
	global_load_lds_dwordx4 v[204:205], off
	v_lshl_add_u64 v[246:247], s[58:59], 0, v[184:185]
	s_mov_b32 m0, s71
	s_addc_u32 vcc_hi, s59, 0
	global_load_lds_dwordx4 v[246:247], off
	v_lshl_add_u64 v[230:231], vcc, 0, v[180:181]
	s_mov_b32 m0, s72
	v_lshl_add_u64 v[248:249], s[60:61], 0, v[178:179]
	global_load_lds_dwordx4 v[230:231], off
	v_lshl_add_u64 v[230:231], vcc, 0, v[184:185]
	s_mov_b32 m0, s73
	v_lshl_add_u64 v[250:251], s[60:61], 0, v[182:183]
	global_load_lds_dwordx4 v[230:231], off
	s_mov_b32 m0, s69
	s_nop 0
	global_load_lds_dwordx4 v[248:249], off
	s_mov_b32 m0, s74
	s_nop 0
	global_load_lds_dwordx4 v[250:251], off
	s_waitcnt vmcnt(8) lgkmcnt(0)
	s_barrier
; #define PG8_STAGE(bufoff, gbase, voff) do { _Pragma("unroll") for (int _i = 0; _i < 2; ++_i) \
;         __builtin_amdgcn_global_load_lds((const unsigned*)((const char*)(gbase) + (voff)[_i]), (PG8_LAS unsigned*)(lds + (bufoff) + ldsw + _i * 8192), 16, 0, 0); } while (0)
; #define PG8_LDA(dst, b, h) do { _Pragma("unroll") for (int m = 0; m < 4; ++m) _Pragma("unroll") for (int k = 0; k < 2; ++k) dst[m][k] = *(const PG8_LAS bf16x8*)(lds + PG8_SA(b, h) + aoff + m * 2048 + k * 1024); } while (0)
; #define PG8_LDB(dst, b, h) do { _Pragma("unroll") for (int n = 0; n < 2; ++n) _Pragma("unroll") for (int k = 0; k < 2; ++k) dst[n][k] = *(const PG8_LAS bf16x8*)(lds + PG8_SB(b, h) + boff + n * 2048 + k * 1024); } while (0)
; #define PG8_MMA(ai, bj, At, Bt) do { __builtin_amdgcn_s_setprio(1); _Pragma("unroll") for (int m = 0; m < 4; ++m) _Pragma("unroll") for (int n = 0; n < 2; ++n) _Pragma("unroll") for (int k = 0; k < 2; ++k) \
;         acc[ai][bj][m][n] = __builtin_amdgcn_mfma_f32_16x16x32_bf16(Bt[n][k], At[m][k], acc[ai][bj][m][n], 0, 0, 0); __builtin_amdgcn_s_setprio(0); } while (0)
; #define PG8_WAIT_V(n) asm volatile("s_waitcnt vmcnt(" #n ")" ::: "memory")
; #define PG8_WAIT_L(n) asm volatile("s_waitcnt lgkmcnt(" #n ")" ::: "memory")
; #define PG8_BAR __builtin_amdgcn_s_barrier()
; #define PG8_SCHED __builtin_amdgcn_sched_barrier(0)
; template <class Epi, class Sched, bool ALIGN_EPI = false, bool SP2 = false>
; __device__ __forceinline__ void gemm_phase(PG8_LAS unsigned char* lds, const Gemm g, const Sched& S, const Epi& E) {
;     ...
;             PG8_WAIT_V(8); PG8_WAIT_L(0); PG8_BAR; PG8_MMA(1, 0, At, B0); PG8_MMA(1, 1, At, B1); PG8_BAR; PG8_SCHED;
;             PG8_LDB(B0, 1, 0); PG8_LDB(B1, 1, 1); PG8_SCHED; PG8_LDA(At, 1, 0); PG8_STAGE(PG8_SA(0, 1), a2 + hstep, voffA);
;             PG8_WAIT_V(8); PG8_WAIT_L(0); PG8_BAR; PG8_MMA(0, 0, At, B0); PG8_MMA(0, 1, At, B1); PG8_BAR; PG8_SCHED;
	s_setprio 1
	v_mfma_f32_16x16x32_bf16 v[78:81], v[162:165], v[122:125], v[78:81]
	v_mfma_f32_16x16x32_bf16 v[74:77], v[170:173], v[122:125], v[74:77]
	v_mfma_f32_16x16x32_bf16 v[62:65], v[162:165], v[138:141], v[62:65]
	v_mfma_f32_16x16x32_bf16 v[58:61], v[170:173], v[138:141], v[58:61]
	v_mfma_f32_16x16x32_bf16 v[30:33], v[162:165], v[212:215], v[30:33]
	v_mfma_f32_16x16x32_bf16 v[26:29], v[170:173], v[212:215], v[26:29]
	v_mfma_f32_16x16x32_bf16 v[14:17], v[162:165], v[222:225], v[14:17]
	v_mfma_f32_16x16x32_bf16 v[10:13], v[170:173], v[222:225], v[10:13]
	v_mfma_f32_16x16x32_bf16 v[78:81], v[166:169], v[126:129], v[78:81]
	v_mfma_f32_16x16x32_bf16 v[74:77], v[174:177], v[126:129], v[74:77]
	v_mfma_f32_16x16x32_bf16 v[62:65], v[166:169], v[142:145], v[62:65]
	v_mfma_f32_16x16x32_bf16 v[58:61], v[174:177], v[142:145], v[58:61]
	v_mfma_f32_16x16x32_bf16 v[30:33], v[166:169], v[216:219], v[30:33]
	v_mfma_f32_16x16x32_bf16 v[26:29], v[174:177], v[216:219], v[26:29]
	v_mfma_f32_16x16x32_bf16 v[14:17], v[166:169], v[226:229], v[14:17]
	v_mfma_f32_16x16x32_bf16 v[10:13], v[174:177], v[226:229], v[10:13]
	v_mfma_f32_16x16x32_bf16 v[70:73], v[146:149], v[122:125], v[70:73]
	v_mfma_f32_16x16x32_bf16 v[66:69], v[154:157], v[122:125], v[66:69]
	v_mfma_f32_16x16x32_bf16 v[38:41], v[146:149], v[138:141], v[38:41]
	v_mfma_f32_16x16x32_bf16 v[34:37], v[154:157], v[138:141], v[34:37]
	v_mfma_f32_16x16x32_bf16 v[22:25], v[146:149], v[212:215], v[22:25]
	v_mfma_f32_16x16x32_bf16 v[18:21], v[154:157], v[212:215], v[18:21]
	v_mfma_f32_16x16x32_bf16 v[6:9], v[146:149], v[222:225], v[6:9]
	v_mfma_f32_16x16x32_bf16 v[2:5], v[154:157], v[222:225], v[2:5]
	v_mfma_f32_16x16x32_bf16 v[70:73], v[150:153], v[126:129], v[70:73]
	v_mfma_f32_16x16x32_bf16 v[66:69], v[158:161], v[126:129], v[66:69]
	v_mfma_f32_16x16x32_bf16 v[38:41], v[150:153], v[142:145], v[38:41]
	v_mfma_f32_16x16x32_bf16 v[34:37], v[158:161], v[142:145], v[34:37]
	v_mfma_f32_16x16x32_bf16 v[22:25], v[150:153], v[216:219], v[22:25]
	v_mfma_f32_16x16x32_bf16 v[18:21], v[158:161], v[216:219], v[18:21]
	v_mfma_f32_16x16x32_bf16 v[6:9], v[150:153], v[226:229], v[6:9]
	v_mfma_f32_16x16x32_bf16 v[2:5], v[158:161], v[226:229], v[2:5]
	s_barrier
	s_setprio 0
.Lpz3_mid:
	s_add_i32 s29, 0, 0x18000
	v_add_u32_e32 v122, s29, v203
	s_add_i32 vcc_lo, 0, 0x1c000
	ds_read_b128 v[146:149], v122
	ds_read_b128 v[150:153], v122 offset:1024
	ds_read_b128 v[154:157], v122 offset:2048
	ds_read_b128 v[158:161], v122 offset:3072
	v_add_u32_e32 v122, vcc_lo, v203
	ds_read_b128 v[162:165], v122
	ds_read_b128 v[166:169], v122 offset:1024
	ds_read_b128 v[170:173], v122 offset:2048
	ds_read_b128 v[174:177], v122 offset:3072
	s_add_u32 s60, s60, 0x40000
	s_addc_u32 s61, s61, 0
	s_mov_b32 m0, s75
	v_lshl_add_u64 v[122:123], s[60:61], 0, v[178:179]
	ds_read_b128 v[212:215], v210 offset:32768
	ds_read_b128 v[216:219], v210 offset:33792
	ds_read_b128 v[222:225], v210 offset:34816
	ds_read_b128 v[226:229], v210 offset:35840
	ds_read_b128 v[230:233], v210 offset:36864
	ds_read_b128 v[234:237], v210 offset:37888
	ds_read_b128 v[238:241], v210 offset:38912
	ds_read_b128 v[242:245], v210 offset:39936
	global_load_lds_dwordx4 v[122:123], off
	v_lshl_add_u64 v[122:123], s[60:61], 0, v[182:183]
	s_mov_b32 m0, s76
	s_nop 0
	global_load_lds_dwordx4 v[122:123], off
	s_waitcnt vmcnt(8) lgkmcnt(0)
	s_barrier
	s_setprio 1
	v_mfma_f32_16x16x32_bf16 v[42:45], v[146:149], v[212:215], v[42:45]
	v_mfma_f32_16x16x32_bf16 v[142:145], v[150:153], v[216:219], v[42:45]
	v_mfma_f32_16x16x32_bf16 v[42:45], v[154:157], v[212:215], v[46:49]
	v_mfma_f32_16x16x32_bf16 v[138:141], v[158:161], v[216:219], v[42:45]
	v_mfma_f32_16x16x32_bf16 v[42:45], v[146:149], v[222:225], v[50:53]
	v_mfma_f32_16x16x32_bf16 v[126:129], v[150:153], v[226:229], v[42:45]
	v_mfma_f32_16x16x32_bf16 v[42:45], v[154:157], v[222:225], v[54:57]
	v_mfma_f32_16x16x32_bf16 v[122:125], v[158:161], v[226:229], v[42:45]
	v_mfma_f32_16x16x32_bf16 v[42:45], v[146:149], v[230:233], v[110:113]
	v_mfma_f32_16x16x32_bf16 v[110:113], v[150:153], v[234:237], v[42:45]
	v_mfma_f32_16x16x32_bf16 v[42:45], v[154:157], v[230:233], v[106:109]
	v_mfma_f32_16x16x32_bf16 v[106:109], v[158:161], v[234:237], v[42:45]
	v_mfma_f32_16x16x32_bf16 v[42:45], v[146:149], v[238:241], v[94:97]
	v_mfma_f32_16x16x32_bf16 v[94:97], v[150:153], v[242:245], v[42:45]
	v_mfma_f32_16x16x32_bf16 v[42:45], v[154:157], v[238:241], v[90:93]
	v_mfma_f32_16x16x32_bf16 v[90:93], v[158:161], v[242:245], v[42:45]
	v_mfma_f32_16x16x32_bf16 v[42:45], v[162:165], v[212:215], v[134:137]
	v_mfma_f32_16x16x32_bf16 v[134:137], v[166:169], v[216:219], v[42:45]
	v_mfma_f32_16x16x32_bf16 v[42:45], v[170:173], v[212:215], v[130:133]
	v_mfma_f32_16x16x32_bf16 v[130:133], v[174:177], v[216:219], v[42:45]
	v_mfma_f32_16x16x32_bf16 v[42:45], v[162:165], v[222:225], v[118:121]
	v_mfma_f32_16x16x32_bf16 v[118:121], v[166:169], v[226:229], v[42:45]
	v_mfma_f32_16x16x32_bf16 v[42:45], v[170:173], v[222:225], v[114:117]
	v_mfma_f32_16x16x32_bf16 v[114:117], v[174:177], v[226:229], v[42:45]
	v_mfma_f32_16x16x32_bf16 v[42:45], v[162:165], v[230:233], v[102:105]
	v_mfma_f32_16x16x32_bf16 v[102:105], v[166:169], v[234:237], v[42:45]
	v_mfma_f32_16x16x32_bf16 v[42:45], v[170:173], v[230:233], v[98:101]
	v_mfma_f32_16x16x32_bf16 v[98:101], v[174:177], v[234:237], v[42:45]
	v_mfma_f32_16x16x32_bf16 v[42:45], v[162:165], v[238:241], v[86:89]
	v_mfma_f32_16x16x32_bf16 v[86:89], v[166:169], v[242:245], v[42:45]
	v_mfma_f32_16x16x32_bf16 v[42:45], v[170:173], v[238:241], v[82:85]
	v_mfma_f32_16x16x32_bf16 v[82:85], v[174:177], v[242:245], v[42:45]
	s_barrier
; #define PG8_STAGE(bufoff, gbase, voff) do { _Pragma("unroll") for (int _i = 0; _i < 2; ++_i) \
;         __builtin_amdgcn_global_load_lds((const unsigned*)((const char*)(gbase) + (voff)[_i]), (PG8_LAS unsigned*)(lds + (bufoff) + ldsw + _i * 8192), 16, 0, 0); } while (0)
; #define PG8_LDA(dst, b, h) do { _Pragma("unroll") for (int m = 0; m < 4; ++m) _Pragma("unroll") for (int k = 0; k < 2; ++k) dst[m][k] = *(const PG8_LAS bf16x8*)(lds + PG8_SA(b, h) + aoff + m * 2048 + k * 1024); } while (0)
; #define PG8_MMA(ai, bj, At, Bt) do { __builtin_amdgcn_s_setprio(1); _Pragma("unroll") for (int m = 0; m < 4; ++m) _Pragma("unroll") for (int n = 0; n < 2; ++n) _Pragma("unroll") for (int k = 0; k < 2; ++k) \
;         acc[ai][bj][m][n] = __builtin_amdgcn_mfma_f32_16x16x32_bf16(Bt[n][k], At[m][k], acc[ai][bj][m][n], 0, 0, 0); __builtin_amdgcn_s_setprio(0); } while (0)
; #define PG8_WAIT_V(n) asm volatile("s_waitcnt vmcnt(" #n ")" ::: "memory")
; #define PG8_WAIT_L(n) asm volatile("s_waitcnt lgkmcnt(" #n ")" ::: "memory")
; #define PG8_BAR __builtin_amdgcn_s_barrier()
; #define PG8_SCHED __builtin_amdgcn_sched_barrier(0)
; template <class Epi, class Sched, bool ALIGN_EPI = false, bool SP2 = false>
; __device__ __forceinline__ void gemm_phase(PG8_LAS unsigned char* lds, const Gemm g, const Sched& S, const Epi& E) {
;     ...
;             PG8_LDA(At, 1, 1); PG8_STAGE(PG8_SB(1, 0), b3, voffB); PG8_STAGE(PG8_SB(1, 1), b3 + hstep, voffB); PG8_STAGE(PG8_SA(1, 0), a3, voffA);
;             PG8_WAIT_V(8); PG8_WAIT_L(0); PG8_BAR; PG8_MMA(1, 0, At, B0); PG8_MMA(1, 1, At, B1); PG8_BAR; PG8_SCHED;
	s_setprio 0
	s_add_i32 s29, s29, s68
	v_lshl_add_u64 v[204:205], v[204:205], 0, s[38:39]
	s_mov_b32 m0, s29
	s_nop 1
	ds_read_b128 v[42:45], v210 offset:49152
	ds_read_b128 v[46:49], v210 offset:50176
	ds_read_b128 v[50:53], v210 offset:51200
	ds_read_b128 v[54:57], v210 offset:52224
	ds_read_b128 v[212:215], v210 offset:53248
	ds_read_b128 v[216:219], v210 offset:54272
	ds_read_b128 v[222:225], v210 offset:55296
	ds_read_b128 v[226:229], v210 offset:56320
	global_load_lds_dwordx4 v[204:205], off
	s_add_i32 m0, s29, 0x2000
	s_add_u32 s58, s58, 0x40080
	v_lshl_add_u64 v[204:205], v[246:247], 0, s[38:39]
	s_addc_u32 s59, s59, 0
	s_add_i32 s29, vcc_lo, s68
	global_load_lds_dwordx4 v[204:205], off
	v_lshl_add_u64 v[204:205], s[58:59], 0, v[180:181]
	s_mov_b32 m0, s29
	s_nop 0
	global_load_lds_dwordx4 v[204:205], off
	v_lshl_add_u64 v[204:205], s[58:59], 0, v[184:185]
	s_add_i32 m0, s29, 0x2000
	s_nop 0
	global_load_lds_dwordx4 v[204:205], off
	v_lshl_add_u64 v[204:205], v[248:249], 0, s[38:39]
	s_mov_b32 m0, s81
	s_nop 0
	global_load_lds_dwordx4 v[204:205], off
	v_lshl_add_u64 v[204:205], v[250:251], 0, s[38:39]
	s_mov_b32 m0, s82
	s_nop 0
	global_load_lds_dwordx4 v[204:205], off
	s_waitcnt vmcnt(8) lgkmcnt(0)
	s_barrier
	s_setprio 1
	v_mfma_f32_16x16x32_bf16 v[78:81], v[146:149], v[42:45], v[78:81]
	v_mfma_f32_16x16x32_bf16 v[74:77], v[154:157], v[42:45], v[74:77]
	v_mfma_f32_16x16x32_bf16 v[62:65], v[146:149], v[50:53], v[62:65]
	v_mfma_f32_16x16x32_bf16 v[58:61], v[154:157], v[50:53], v[58:61]
	v_mfma_f32_16x16x32_bf16 v[30:33], v[146:149], v[212:215], v[30:33]
	v_mfma_f32_16x16x32_bf16 v[26:29], v[154:157], v[212:215], v[26:29]
	v_mfma_f32_16x16x32_bf16 v[14:17], v[146:149], v[222:225], v[14:17]
	v_mfma_f32_16x16x32_bf16 v[10:13], v[154:157], v[222:225], v[10:13]
	v_mfma_f32_16x16x32_bf16 v[78:81], v[150:153], v[46:49], v[78:81]
	v_mfma_f32_16x16x32_bf16 v[74:77], v[158:161], v[46:49], v[74:77]
	v_mfma_f32_16x16x32_bf16 v[62:65], v[150:153], v[54:57], v[62:65]
	v_mfma_f32_16x16x32_bf16 v[58:61], v[158:161], v[54:57], v[58:61]
	v_mfma_f32_16x16x32_bf16 v[30:33], v[150:153], v[216:219], v[30:33]
	v_mfma_f32_16x16x32_bf16 v[26:29], v[158:161], v[216:219], v[26:29]
	v_mfma_f32_16x16x32_bf16 v[14:17], v[150:153], v[226:229], v[14:17]
	v_mfma_f32_16x16x32_bf16 v[10:13], v[158:161], v[226:229], v[10:13]
	v_mfma_f32_16x16x32_bf16 v[70:73], v[162:165], v[42:45], v[70:73]
	v_mfma_f32_16x16x32_bf16 v[42:45], v[170:173], v[42:45], v[66:69]
	v_mfma_f32_16x16x32_bf16 v[38:41], v[162:165], v[50:53], v[38:41]
	v_mfma_f32_16x16x32_bf16 v[34:37], v[170:173], v[50:53], v[34:37]
	v_mfma_f32_16x16x32_bf16 v[22:25], v[162:165], v[212:215], v[22:25]
	v_mfma_f32_16x16x32_bf16 v[18:21], v[170:173], v[212:215], v[18:21]
	v_mfma_f32_16x16x32_bf16 v[6:9], v[162:165], v[222:225], v[6:9]
	v_mfma_f32_16x16x32_bf16 v[2:5], v[170:173], v[222:225], v[2:5]
	v_mfma_f32_16x16x32_bf16 v[70:73], v[166:169], v[46:49], v[70:73]
	v_mfma_f32_16x16x32_bf16 v[66:69], v[174:177], v[46:49], v[42:45]
	v_mfma_f32_16x16x32_bf16 v[38:41], v[166:169], v[54:57], v[38:41]
	v_mfma_f32_16x16x32_bf16 v[34:37], v[174:177], v[54:57], v[34:37]
	v_mfma_f32_16x16x32_bf16 v[22:25], v[166:169], v[216:219], v[22:25]
	v_mfma_f32_16x16x32_bf16 v[18:21], v[174:177], v[216:219], v[18:21]
	v_mfma_f32_16x16x32_bf16 v[6:9], v[166:169], v[226:229], v[6:9]
	v_mfma_f32_16x16x32_bf16 v[2:5], v[174:177], v[226:229], v[2:5]
	s_barrier
	s_setprio 0
	s_add_i32 s29, s28, 2
	s_add_u32 s56, s56, 0x100
	s_addc_u32 s57, s57, 0
	s_cmp_gt_u32 s28, 13
	s_mov_b32 s28, s29
	s_cbranch_scc1 .LBB0_442
; #define PG8_LAS __attribute__((address_space(3)))
; #define PG8_STAGE(bufoff, gbase, voff) do { _Pragma("unroll") for (int _i = 0; _i < 2; ++_i) \
;         __builtin_amdgcn_global_load_lds((const unsigned*)((const char*)(gbase) + (voff)[_i]), (PG8_LAS unsigned*)(lds + (bufoff) + ldsw + _i * 8192), 16, 0, 0); } while (0)
; #define PG8_LDA(dst, b, h) do { _Pragma("unroll") for (int m = 0; m < 4; ++m) _Pragma("unroll") for (int k = 0; k < 2; ++k) dst[m][k] = *(const PG8_LAS bf16x8*)(lds + PG8_SA(b, h) + aoff + m * 2048 + k * 1024); } while (0)
; #define PG8_LDB(dst, b, h) do { _Pragma("unroll") for (int n = 0; n < 2; ++n) _Pragma("unroll") for (int k = 0; k < 2; ++k) dst[n][k] = *(const PG8_LAS bf16x8*)(lds + PG8_SB(b, h) + boff + n * 2048 + k * 1024); } while (0)
; #define PG8_MMA(ai, bj, At, Bt) do { __builtin_amdgcn_s_setprio(1); _Pragma("unroll") for (int m = 0; m < 4; ++m) _Pragma("unroll") for (int n = 0; n < 2; ++n) _Pragma("unroll") for (int k = 0; k < 2; ++k) \
;         acc[ai][bj][m][n] = __builtin_amdgcn_mfma_f32_16x16x32_bf16(Bt[n][k], At[m][k], acc[ai][bj][m][n], 0, 0, 0); __builtin_amdgcn_s_setprio(0); } while (0)
; #define PG8_WAIT_V(n) asm volatile("s_waitcnt vmcnt(" #n ")" ::: "memory")
; template <class Epi, class Sched, bool ALIGN_EPI = false, bool SP2 = false>
; __device__ __forceinline__ void gemm_phase(PG8_LAS unsigned char* lds, const Gemm g, const Sched& S, const Epi& E) {
;     ...
;             PG8_LDB(B0, 0, 0); PG8_LDB(B1, 0, 1); PG8_SCHED; PG8_LDA(At, 0, 0); PG8_STAGE(PG8_SA(1, 1), a1 + hstep, voffA);
;             PG8_WAIT_V(8); PG8_WAIT_L(0); PG8_BAR; PG8_MMA(0, 0, At, B0); PG8_MMA(0, 1, At, B1); PG8_BAR; PG8_SCHED;
;             if constexpr (Epi::PREFETCH) { if (t == tpf) E.prefetch(cur, wid, lane); }
; __device__ __forceinline__ void epi_prefetch(PG8_LAS unsigned char* scr, const float* ssq, const float* bias_tile, const Unit& u, int wid, int lane) {
;     unsigned lo = (unsigned)lane * 16u; asm volatile("" : "+v"(lo));
;     const char* src = (const char*)(ssq + (size_t)u.pm * BM * 16 + wid * 512);
; #pragma unroll
;     for (int j = 0; j < 2; ++j) __builtin_amdgcn_global_load_lds((const unsigned*)(src + j * 1024 + lo), (PG8_LAS unsigned*)(scr + (wid * 2 + j) * 1024), 16, 0, 0);
;     if (wid == 0) __builtin_amdgcn_global_load_lds((const unsigned*)((const char*)bias_tile + lo), (PG8_LAS unsigned*)(scr + 16384), 16, 0, 0);
; }
.LBB0_439:
	ds_read_b128 v[162:165], v208
	ds_read_b128 v[166:169], v208 offset:1024
	ds_read_b128 v[170:173], v208 offset:2048
	ds_read_b128 v[174:177], v208 offset:3072
	ds_read_b128 v[146:149], v209
	ds_read_b128 v[150:153], v209 offset:1024
	ds_read_b128 v[154:157], v209 offset:2048
	ds_read_b128 v[158:161], v209 offset:3072
	v_lshl_add_u64 v[42:43], v[196:197], 0, s[56:57]
	s_add_i32 m0, s69, 0xc000
	ds_read_b128 v[212:215], v210
	ds_read_b128 v[216:219], v210 offset:1024
	ds_read_b128 v[222:225], v210 offset:2048
	ds_read_b128 v[226:229], v210 offset:3072
	ds_read_b128 v[230:233], v210 offset:4096
	ds_read_b128 v[234:237], v210 offset:5120
	ds_read_b128 v[238:241], v210 offset:6144
	ds_read_b128 v[242:245], v210 offset:7168
	global_load_lds_dwordx4 v[42:43], off
	v_lshl_add_u64 v[42:43], v[198:199], 0, s[56:57]
	s_add_i32 m0, s69, 0xe000
	s_nop 0
	global_load_lds_dwordx4 v[42:43], off
	s_waitcnt vmcnt(8) lgkmcnt(0)
	s_barrier
	s_setprio 1
	v_mfma_f32_16x16x32_bf16 v[42:45], v[162:165], v[212:215], v[142:145]
	v_mfma_f32_16x16x32_bf16 v[46:49], v[170:173], v[212:215], v[138:141]
	v_mfma_f32_16x16x32_bf16 v[50:53], v[162:165], v[222:225], v[126:129]
	v_mfma_f32_16x16x32_bf16 v[54:57], v[170:173], v[222:225], v[122:125]
	v_mfma_f32_16x16x32_bf16 v[110:113], v[162:165], v[230:233], v[110:113]
	v_mfma_f32_16x16x32_bf16 v[106:109], v[170:173], v[230:233], v[106:109]
	v_mfma_f32_16x16x32_bf16 v[94:97], v[162:165], v[238:241], v[94:97]
	v_mfma_f32_16x16x32_bf16 v[90:93], v[170:173], v[238:241], v[90:93]
	v_mfma_f32_16x16x32_bf16 v[42:45], v[166:169], v[216:219], v[42:45]
	v_mfma_f32_16x16x32_bf16 v[46:49], v[174:177], v[216:219], v[46:49]
	v_mfma_f32_16x16x32_bf16 v[50:53], v[166:169], v[226:229], v[50:53]
	v_mfma_f32_16x16x32_bf16 v[54:57], v[174:177], v[226:229], v[54:57]
	v_mfma_f32_16x16x32_bf16 v[110:113], v[166:169], v[234:237], v[110:113]
	v_mfma_f32_16x16x32_bf16 v[106:109], v[174:177], v[234:237], v[106:109]
	v_mfma_f32_16x16x32_bf16 v[94:97], v[166:169], v[242:245], v[94:97]
	v_mfma_f32_16x16x32_bf16 v[90:93], v[174:177], v[242:245], v[90:93]
	v_mfma_f32_16x16x32_bf16 v[122:125], v[146:149], v[212:215], v[134:137]
	v_mfma_f32_16x16x32_bf16 v[134:137], v[150:153], v[216:219], v[122:125]
	v_mfma_f32_16x16x32_bf16 v[122:125], v[154:157], v[212:215], v[130:133]
	v_mfma_f32_16x16x32_bf16 v[118:121], v[146:149], v[222:225], v[118:121]
	v_mfma_f32_16x16x32_bf16 v[114:117], v[154:157], v[222:225], v[114:117]
	v_mfma_f32_16x16x32_bf16 v[102:105], v[146:149], v[230:233], v[102:105]
	v_mfma_f32_16x16x32_bf16 v[98:101], v[154:157], v[230:233], v[98:101]
	v_mfma_f32_16x16x32_bf16 v[86:89], v[146:149], v[238:241], v[86:89]
	v_mfma_f32_16x16x32_bf16 v[82:85], v[154:157], v[238:241], v[82:85]
	v_mfma_f32_16x16x32_bf16 v[130:133], v[158:161], v[216:219], v[122:125]
	v_mfma_f32_16x16x32_bf16 v[118:121], v[150:153], v[226:229], v[118:121]
	v_mfma_f32_16x16x32_bf16 v[114:117], v[158:161], v[226:229], v[114:117]
	v_mfma_f32_16x16x32_bf16 v[102:105], v[150:153], v[234:237], v[102:105]
	v_mfma_f32_16x16x32_bf16 v[98:101], v[158:161], v[234:237], v[98:101]
	v_mfma_f32_16x16x32_bf16 v[86:89], v[150:153], v[242:245], v[86:89]
	v_mfma_f32_16x16x32_bf16 v[82:85], v[158:161], v[242:245], v[82:85]
	s_barrier
	s_setprio 0
	s_cmp_lg_u32 s63, s28
	s_cbranch_scc1 .LBB0_438
	v_mov_b32_e32 v186, v207
	s_add_i32 m0, s62, 0x20000
	v_lshl_add_u64 v[122:123], s[52:53], 0, v[186:187]
	s_mov_b64 s[58:59], 0x400
	global_load_lds_dwordx4 v186, s[52:53]
	v_lshl_add_u64 v[122:123], v[122:123], 0, s[58:59]
	s_add_i32 m0, s62, 0x20400
	s_andn2_b64 vcc, exec, s[40:41]
	global_load_lds_dwordx4 v[122:123], off
	s_cbranch_vccnz .LBB0_438
	v_lshl_add_u64 v[122:123], s[54:55], 0, v[186:187]
	s_mov_b32 m0, s30
	s_nop 0
	global_load_lds_dwordx4 v[122:123], off
	s_branch .LBB0_438

; #define PG8_STAGE(bufoff, gbase, voff) do { _Pragma("unroll") for (int _i = 0; _i < 2; ++_i) \
;         __builtin_amdgcn_global_load_lds((const unsigned*)((const char*)(gbase) + (voff)[_i]), (PG8_LAS unsigned*)(lds + (bufoff) + ldsw + _i * 8192), 16, 0, 0); } while (0)
; #define PG8_LDA(dst, b, h) do { _Pragma("unroll") for (int m = 0; m < 4; ++m) _Pragma("unroll") for (int k = 0; k < 2; ++k) dst[m][k] = *(const PG8_LAS bf16x8*)(lds + PG8_SA(b, h) + aoff + m * 2048 + k * 1024); } while (0)
; #define PG8_LDB(dst, b, h) do { _Pragma("unroll") for (int n = 0; n < 2; ++n) _Pragma("unroll") for (int k = 0; k < 2; ++k) dst[n][k] = *(const PG8_LAS bf16x8*)(lds + PG8_SB(b, h) + boff + n * 2048 + k * 1024); } while (0)
; #define PG8_MMA(ai, bj, At, Bt) do { __builtin_amdgcn_s_setprio(1); _Pragma("unroll") for (int m = 0; m < 4; ++m) _Pragma("unroll") for (int n = 0; n < 2; ++n) _Pragma("unroll") for (int k = 0; k < 2; ++k) \
;         acc[ai][bj][m][n] = __builtin_amdgcn_mfma_f32_16x16x32_bf16(Bt[n][k], At[m][k], acc[ai][bj][m][n], 0, 0, 0); __builtin_amdgcn_s_setprio(0); } while (0)
; #define PG8_WAIT_V(n) asm volatile("s_waitcnt vmcnt(" #n ")" ::: "memory")
; #define PG8_WAIT_L(n) asm volatile("s_waitcnt lgkmcnt(" #n ")" ::: "memory")
; #define PG8_BAR __builtin_amdgcn_s_barrier()
; #define PG8_SCHED __builtin_amdgcn_sched_barrier(0)
;     __device__ __forceinline__ void prefetch(const Unit& u, int wid, int lane) const { epi_prefetch(scr, ssq, bias + (size_t)(u.pm >> 5) * NGU + u.pn * BM, u, wid, lane); }
;     __device__ __forceinline__ void prefetch(const Unit& u, int wid, int lane) const { epi_prefetch(scr, ssq, bias + (size_t)(u.pm >> 5) * DIN + u.pn * BM, u, wid, lane); }
; template <class Epi, class Sched, bool ALIGN_EPI = false, bool SP2 = false>
; __device__ __forceinline__ void gemm_phase(PG8_LAS unsigned char* lds, const Gemm g, const Sched& S, const Epi& E) {
;     ...
;             PG8_LDB(B0, 0, 0); PG8_LDB(B1, 0, 1); PG8_SCHED; PG8_LDA(At, 0, 0); PG8_STAGE(PG8_SA(1, 1), a1 + hstep, voffA);
;             PG8_WAIT_V(8); PG8_WAIT_L(0); PG8_BAR; PG8_MMA(0, 0, At, B0); PG8_MMA(0, 1, At, B1); PG8_BAR; PG8_SCHED;
;             if constexpr (Epi::PREFETCH) { if (t == tpf) E.prefetch(cur, wid, lane); }
;             PG8_LDA(At, 0, 1); PG8_STAGE(PG8_SB(0, 0), b2, voffB); PG8_STAGE(PG8_SB(0, 1), b2 + hstep, voffB); PG8_STAGE(PG8_SA(0, 0), a2, voffA);
.LBB0_723:
	v_add_u32_e32 v2, s67, v177
	ds_read_b128 v[134:137], v2
	ds_read_b128 v[138:141], v2 offset:1024
	ds_read_b128 v[142:145], v2 offset:2048
	ds_read_b128 v[146:149], v2 offset:3072
	v_add_u32_e32 v2, s68, v177
	ds_read_b128 v[150:153], v2
	ds_read_b128 v[170:173], v2 offset:1024
	ds_read_b128 v[180:183], v2 offset:2048
	ds_read_b128 v[184:187], v2 offset:3072
	s_add_u32 s28, s0, 0xfffc0080
	s_addc_u32 s29, s1, -1
	s_cmp_eq_u32 s43, 12
	s_cselect_b32 s37, s23, s29
	s_cselect_b32 s36, s39, s28
	s_cselect_b32 s29, s21, s42
	s_cselect_b32 s28, s40, s41
	v_lshl_add_u64 v[4:5], s[0:1], 0, v[162:163]
	s_add_i32 m0, s31, 0xc000
	ds_read_b128 v[188:191], v178
	ds_read_b128 v[192:195], v178 offset:1024
	ds_read_b128 v[196:199], v178 offset:2048
	ds_read_b128 v[200:203], v178 offset:3072
	ds_read_b128 v[204:207], v178 offset:4096
	ds_read_b128 v[208:211], v178 offset:5120
	ds_read_b128 v[212:215], v178 offset:6144
	ds_read_b128 v[216:219], v178 offset:7168
	global_load_lds_dwordx4 v[4:5], off
	v_lshl_add_u64 v[4:5], s[0:1], 0, v[164:165]
	s_add_i32 m0, s31, 0xe000
	s_nop 0
	global_load_lds_dwordx4 v[4:5], off
	s_waitcnt vmcnt(8) lgkmcnt(0)
	s_barrier
	s_setprio 1
	v_mfma_f32_16x16x32_bf16 v[130:133], v[134:137], v[188:191], v[130:133]
	v_mfma_f32_16x16x32_bf16 v[126:129], v[142:145], v[188:191], v[126:129]
	v_mfma_f32_16x16x32_bf16 v[122:125], v[134:137], v[196:199], v[122:125]
	v_mfma_f32_16x16x32_bf16 v[118:121], v[142:145], v[196:199], v[118:121]
	v_mfma_f32_16x16x32_bf16 v[114:117], v[134:137], v[204:207], v[114:117]
	v_mfma_f32_16x16x32_bf16 v[110:113], v[142:145], v[204:207], v[110:113]
	v_mfma_f32_16x16x32_bf16 v[106:109], v[134:137], v[212:215], v[106:109]
	v_mfma_f32_16x16x32_bf16 v[102:105], v[142:145], v[212:215], v[102:105]
	v_mfma_f32_16x16x32_bf16 v[130:133], v[138:141], v[192:195], v[130:133]
	v_mfma_f32_16x16x32_bf16 v[126:129], v[146:149], v[192:195], v[126:129]
	v_mfma_f32_16x16x32_bf16 v[122:125], v[138:141], v[200:203], v[122:125]
	v_mfma_f32_16x16x32_bf16 v[118:121], v[146:149], v[200:203], v[118:121]
	v_mfma_f32_16x16x32_bf16 v[114:117], v[138:141], v[208:211], v[114:117]
	v_mfma_f32_16x16x32_bf16 v[110:113], v[146:149], v[208:211], v[110:113]
	v_mfma_f32_16x16x32_bf16 v[106:109], v[138:141], v[216:219], v[106:109]
	v_mfma_f32_16x16x32_bf16 v[102:105], v[146:149], v[216:219], v[102:105]
	v_mfma_f32_16x16x32_bf16 v[98:101], v[150:153], v[188:191], v[98:101]
	v_mfma_f32_16x16x32_bf16 v[94:97], v[180:183], v[188:191], v[94:97]
	v_mfma_f32_16x16x32_bf16 v[90:93], v[150:153], v[196:199], v[90:93]
	v_mfma_f32_16x16x32_bf16 v[86:89], v[180:183], v[196:199], v[86:89]
	v_mfma_f32_16x16x32_bf16 v[82:85], v[150:153], v[204:207], v[82:85]
	v_mfma_f32_16x16x32_bf16 v[78:81], v[180:183], v[204:207], v[78:81]
	v_mfma_f32_16x16x32_bf16 v[74:77], v[150:153], v[212:215], v[74:77]
	v_mfma_f32_16x16x32_bf16 v[70:73], v[180:183], v[212:215], v[70:73]
	v_mfma_f32_16x16x32_bf16 v[98:101], v[170:173], v[192:195], v[98:101]
	v_mfma_f32_16x16x32_bf16 v[94:97], v[184:187], v[192:195], v[94:97]
	v_mfma_f32_16x16x32_bf16 v[90:93], v[170:173], v[200:203], v[90:93]
	v_mfma_f32_16x16x32_bf16 v[86:89], v[184:187], v[200:203], v[86:89]
	v_mfma_f32_16x16x32_bf16 v[82:85], v[170:173], v[208:211], v[82:85]
	v_mfma_f32_16x16x32_bf16 v[78:81], v[184:187], v[208:211], v[78:81]
	v_mfma_f32_16x16x32_bf16 v[74:77], v[170:173], v[216:219], v[74:77]
	v_mfma_f32_16x16x32_bf16 v[70:73], v[184:187], v[216:219], v[70:73]
	s_barrier
	s_setprio 0
	s_add_i32 s71, s67, s48
	v_lshl_add_u64 v[174:175], s[28:29], 0, v[156:157]
	s_mov_b32 m0, s71
	ds_read_b128 v[188:191], v178 offset:16384
	ds_read_b128 v[192:195], v178 offset:17408
	ds_read_b128 v[196:199], v178 offset:18432
	ds_read_b128 v[200:203], v178 offset:19456
	ds_read_b128 v[204:207], v178 offset:20480
	ds_read_b128 v[208:211], v178 offset:21504
	ds_read_b128 v[212:215], v178 offset:22528
	ds_read_b128 v[216:219], v178 offset:23552
	global_load_lds_dwordx4 v[174:175], off
	s_add_i32 m0, s71, 0x2000
	s_add_u32 s72, s28, 0x40000
	v_lshl_add_u64 v[222:223], s[28:29], 0, v[160:161]
	s_addc_u32 s73, s29, 0
	s_add_i32 s71, s68, s48
	global_load_lds_dwordx4 v[222:223], off
	v_lshl_add_u64 v[4:5], s[72:73], 0, v[156:157]
	s_mov_b32 m0, s71
	v_lshl_add_u64 v[224:225], s[36:37], 0, v[154:155]
	global_load_lds_dwordx4 v[4:5], off
	v_lshl_add_u64 v[4:5], s[72:73], 0, v[160:161]
	s_add_i32 m0, s71, 0x2000
	v_lshl_add_u64 v[226:227], s[36:37], 0, v[158:159]
	global_load_lds_dwordx4 v[4:5], off
	s_mov_b32 m0, s31
	s_nop 0
	global_load_lds_dwordx4 v[224:225], off
	s_mov_b32 m0, s35
	s_nop 0
	global_load_lds_dwordx4 v[226:227], off
	s_waitcnt vmcnt(8) lgkmcnt(0)
	s_barrier
; #define PG8_STAGE(bufoff, gbase, voff) do { _Pragma("unroll") for (int _i = 0; _i < 2; ++_i) \
;         __builtin_amdgcn_global_load_lds((const unsigned*)((const char*)(gbase) + (voff)[_i]), (PG8_LAS unsigned*)(lds + (bufoff) + ldsw + _i * 8192), 16, 0, 0); } while (0)
; #define PG8_LDA(dst, b, h) do { _Pragma("unroll") for (int m = 0; m < 4; ++m) _Pragma("unroll") for (int k = 0; k < 2; ++k) dst[m][k] = *(const PG8_LAS bf16x8*)(lds + PG8_SA(b, h) + aoff + m * 2048 + k * 1024); } while (0)
; #define PG8_LDB(dst, b, h) do { _Pragma("unroll") for (int n = 0; n < 2; ++n) _Pragma("unroll") for (int k = 0; k < 2; ++k) dst[n][k] = *(const PG8_LAS bf16x8*)(lds + PG8_SB(b, h) + boff + n * 2048 + k * 1024); } while (0)
; #define PG8_MMA(ai, bj, At, Bt) do { __builtin_amdgcn_s_setprio(1); _Pragma("unroll") for (int m = 0; m < 4; ++m) _Pragma("unroll") for (int n = 0; n < 2; ++n) _Pragma("unroll") for (int k = 0; k < 2; ++k) \
;         acc[ai][bj][m][n] = __builtin_amdgcn_mfma_f32_16x16x32_bf16(Bt[n][k], At[m][k], acc[ai][bj][m][n], 0, 0, 0); __builtin_amdgcn_s_setprio(0); } while (0)
; #define PG8_WAIT_V(n) asm volatile("s_waitcnt vmcnt(" #n ")" ::: "memory")
; #define PG8_WAIT_L(n) asm volatile("s_waitcnt lgkmcnt(" #n ")" ::: "memory")
; #define PG8_BAR __builtin_amdgcn_s_barrier()
; #define PG8_SCHED __builtin_amdgcn_sched_barrier(0)
; template <class Epi, class Sched, bool ALIGN_EPI = false, bool SP2 = false>
; __device__ __forceinline__ void gemm_phase(PG8_LAS unsigned char* lds, const Gemm g, const Sched& S, const Epi& E) {
;     ...
;             PG8_WAIT_V(8); PG8_WAIT_L(0); PG8_BAR; PG8_MMA(1, 0, At, B0); PG8_MMA(1, 1, At, B1); PG8_BAR; PG8_SCHED;
;             PG8_LDB(B0, 1, 0); PG8_LDB(B1, 1, 1); PG8_SCHED; PG8_LDA(At, 1, 0); PG8_STAGE(PG8_SA(0, 1), a2 + hstep, voffA);
;             PG8_WAIT_V(8); PG8_WAIT_L(0); PG8_BAR; PG8_MMA(0, 0, At, B0); PG8_MMA(0, 1, At, B1); PG8_BAR; PG8_SCHED;
	s_setprio 1
	v_mfma_f32_16x16x32_bf16 v[66:69], v[134:137], v[188:191], v[66:69]
	v_mfma_f32_16x16x32_bf16 v[62:65], v[142:145], v[188:191], v[62:65]
	v_mfma_f32_16x16x32_bf16 v[58:61], v[134:137], v[196:199], v[58:61]
	v_mfma_f32_16x16x32_bf16 v[54:57], v[142:145], v[196:199], v[54:57]
	v_mfma_f32_16x16x32_bf16 v[50:53], v[134:137], v[204:207], v[50:53]
	v_mfma_f32_16x16x32_bf16 v[46:49], v[142:145], v[204:207], v[46:49]
	v_mfma_f32_16x16x32_bf16 v[42:45], v[134:137], v[212:215], v[42:45]
	v_mfma_f32_16x16x32_bf16 v[38:41], v[142:145], v[212:215], v[38:41]
	v_mfma_f32_16x16x32_bf16 v[66:69], v[138:141], v[192:195], v[66:69]
	v_mfma_f32_16x16x32_bf16 v[62:65], v[146:149], v[192:195], v[62:65]
	v_mfma_f32_16x16x32_bf16 v[58:61], v[138:141], v[200:203], v[58:61]
	v_mfma_f32_16x16x32_bf16 v[54:57], v[146:149], v[200:203], v[54:57]
	v_mfma_f32_16x16x32_bf16 v[50:53], v[138:141], v[208:211], v[50:53]
	v_mfma_f32_16x16x32_bf16 v[46:49], v[146:149], v[208:211], v[46:49]
	v_mfma_f32_16x16x32_bf16 v[42:45], v[138:141], v[216:219], v[42:45]
	v_mfma_f32_16x16x32_bf16 v[38:41], v[146:149], v[216:219], v[38:41]
	v_mfma_f32_16x16x32_bf16 v[34:37], v[150:153], v[188:191], v[34:37]
	v_mfma_f32_16x16x32_bf16 v[30:33], v[180:183], v[188:191], v[30:33]
	v_mfma_f32_16x16x32_bf16 v[26:29], v[150:153], v[196:199], v[26:29]
	v_mfma_f32_16x16x32_bf16 v[22:25], v[180:183], v[196:199], v[22:25]
	v_mfma_f32_16x16x32_bf16 v[18:21], v[150:153], v[204:207], v[18:21]
	v_mfma_f32_16x16x32_bf16 v[14:17], v[180:183], v[204:207], v[14:17]
	v_mfma_f32_16x16x32_bf16 v[10:13], v[150:153], v[212:215], v[10:13]
	v_mfma_f32_16x16x32_bf16 v[4:7], v[180:183], v[212:215], v[6:9]
	v_mfma_f32_16x16x32_bf16 v[34:37], v[170:173], v[192:195], v[34:37]
	v_mfma_f32_16x16x32_bf16 v[30:33], v[184:187], v[192:195], v[30:33]
	v_mfma_f32_16x16x32_bf16 v[26:29], v[170:173], v[200:203], v[26:29]
	v_mfma_f32_16x16x32_bf16 v[22:25], v[184:187], v[200:203], v[22:25]
	v_mfma_f32_16x16x32_bf16 v[18:21], v[170:173], v[208:211], v[18:21]
	v_mfma_f32_16x16x32_bf16 v[14:17], v[184:187], v[208:211], v[14:17]
	v_mfma_f32_16x16x32_bf16 v[10:13], v[170:173], v[216:219], v[10:13]
	v_mfma_f32_16x16x32_bf16 v[4:7], v[184:187], v[216:219], v[4:7]
	s_barrier
	s_setprio 0
	s_add_i32 s71, 0, 0x18000
	v_add_u32_e32 v2, s71, v177
	s_add_i32 s72, 0, 0x1c000
	ds_read_b128 v[134:137], v2
	ds_read_b128 v[138:141], v2 offset:1024
	ds_read_b128 v[142:145], v2 offset:2048
	ds_read_b128 v[146:149], v2 offset:3072
	v_add_u32_e32 v2, s72, v177
	ds_read_b128 v[150:153], v2
	ds_read_b128 v[170:173], v2 offset:1024
	ds_read_b128 v[180:183], v2 offset:2048
	ds_read_b128 v[184:187], v2 offset:3072
	s_add_u32 s36, s36, 0x40000
	s_addc_u32 s37, s37, 0
	s_mov_b32 m0, s49
	v_lshl_add_u64 v[8:9], s[36:37], 0, v[154:155]
	ds_read_b128 v[188:191], v178 offset:32768
	ds_read_b128 v[192:195], v178 offset:33792
	ds_read_b128 v[196:199], v178 offset:34816
	ds_read_b128 v[200:203], v178 offset:35840
	ds_read_b128 v[204:207], v178 offset:36864
	ds_read_b128 v[208:211], v178 offset:37888
	ds_read_b128 v[212:215], v178 offset:38912
	ds_read_b128 v[216:219], v178 offset:39936
	global_load_lds_dwordx4 v[8:9], off
	v_lshl_add_u64 v[8:9], s[36:37], 0, v[158:159]
	s_mov_b32 m0, s50
	s_nop 0
	global_load_lds_dwordx4 v[8:9], off
	s_waitcnt vmcnt(8) lgkmcnt(0)
	s_barrier
	s_setprio 1
	v_mfma_f32_16x16x32_bf16 v[130:133], v[134:137], v[188:191], v[130:133]
	v_mfma_f32_16x16x32_bf16 v[126:129], v[142:145], v[188:191], v[126:129]
	v_mfma_f32_16x16x32_bf16 v[122:125], v[134:137], v[196:199], v[122:125]
	v_mfma_f32_16x16x32_bf16 v[118:121], v[142:145], v[196:199], v[118:121]
	v_mfma_f32_16x16x32_bf16 v[114:117], v[134:137], v[204:207], v[114:117]
	v_mfma_f32_16x16x32_bf16 v[110:113], v[142:145], v[204:207], v[110:113]
	v_mfma_f32_16x16x32_bf16 v[106:109], v[134:137], v[212:215], v[106:109]
	v_mfma_f32_16x16x32_bf16 v[102:105], v[142:145], v[212:215], v[102:105]
	v_mfma_f32_16x16x32_bf16 v[130:133], v[138:141], v[192:195], v[130:133]
	v_mfma_f32_16x16x32_bf16 v[126:129], v[146:149], v[192:195], v[126:129]
	v_mfma_f32_16x16x32_bf16 v[122:125], v[138:141], v[200:203], v[122:125]
	v_mfma_f32_16x16x32_bf16 v[118:121], v[146:149], v[200:203], v[118:121]
	v_mfma_f32_16x16x32_bf16 v[114:117], v[138:141], v[208:211], v[114:117]
	v_mfma_f32_16x16x32_bf16 v[110:113], v[146:149], v[208:211], v[110:113]
	v_mfma_f32_16x16x32_bf16 v[106:109], v[138:141], v[216:219], v[106:109]
	v_mfma_f32_16x16x32_bf16 v[102:105], v[146:149], v[216:219], v[102:105]
	v_mfma_f32_16x16x32_bf16 v[98:101], v[150:153], v[188:191], v[98:101]
	v_mfma_f32_16x16x32_bf16 v[94:97], v[180:183], v[188:191], v[94:97]
	v_mfma_f32_16x16x32_bf16 v[90:93], v[150:153], v[196:199], v[90:93]
	v_mfma_f32_16x16x32_bf16 v[86:89], v[180:183], v[196:199], v[86:89]
	v_mfma_f32_16x16x32_bf16 v[82:85], v[150:153], v[204:207], v[82:85]
	v_mfma_f32_16x16x32_bf16 v[78:81], v[180:183], v[204:207], v[78:81]
	v_mfma_f32_16x16x32_bf16 v[74:77], v[150:153], v[212:215], v[74:77]
	v_mfma_f32_16x16x32_bf16 v[70:73], v[180:183], v[212:215], v[70:73]
	v_mfma_f32_16x16x32_bf16 v[98:101], v[170:173], v[192:195], v[98:101]
	v_mfma_f32_16x16x32_bf16 v[94:97], v[184:187], v[192:195], v[94:97]
	v_mfma_f32_16x16x32_bf16 v[90:93], v[170:173], v[200:203], v[90:93]
	v_mfma_f32_16x16x32_bf16 v[86:89], v[184:187], v[200:203], v[86:89]
	v_mfma_f32_16x16x32_bf16 v[82:85], v[170:173], v[208:211], v[82:85]
	v_mfma_f32_16x16x32_bf16 v[78:81], v[184:187], v[208:211], v[78:81]
	v_mfma_f32_16x16x32_bf16 v[74:77], v[170:173], v[216:219], v[74:77]
	v_mfma_f32_16x16x32_bf16 v[70:73], v[184:187], v[216:219], v[70:73]
	s_barrier
; #define PG8_STAGE(bufoff, gbase, voff) do { _Pragma("unroll") for (int _i = 0; _i < 2; ++_i) \
;         __builtin_amdgcn_global_load_lds((const unsigned*)((const char*)(gbase) + (voff)[_i]), (PG8_LAS unsigned*)(lds + (bufoff) + ldsw + _i * 8192), 16, 0, 0); } while (0)
; #define PG8_LDA(dst, b, h) do { _Pragma("unroll") for (int m = 0; m < 4; ++m) _Pragma("unroll") for (int k = 0; k < 2; ++k) dst[m][k] = *(const PG8_LAS bf16x8*)(lds + PG8_SA(b, h) + aoff + m * 2048 + k * 1024); } while (0)
; #define PG8_MMA(ai, bj, At, Bt) do { __builtin_amdgcn_s_setprio(1); _Pragma("unroll") for (int m = 0; m < 4; ++m) _Pragma("unroll") for (int n = 0; n < 2; ++n) _Pragma("unroll") for (int k = 0; k < 2; ++k) \
;         acc[ai][bj][m][n] = __builtin_amdgcn_mfma_f32_16x16x32_bf16(Bt[n][k], At[m][k], acc[ai][bj][m][n], 0, 0, 0); __builtin_amdgcn_s_setprio(0); } while (0)
; #define PG8_WAIT_V(n) asm volatile("s_waitcnt vmcnt(" #n ")" ::: "memory")
; #define PG8_WAIT_L(n) asm volatile("s_waitcnt lgkmcnt(" #n ")" ::: "memory")
; #define PG8_BAR __builtin_amdgcn_s_barrier()
; #define PG8_SCHED __builtin_amdgcn_sched_barrier(0)
; template <class Epi, class Sched, bool ALIGN_EPI = false, bool SP2 = false>
; __device__ __forceinline__ void gemm_phase(PG8_LAS unsigned char* lds, const Gemm g, const Sched& S, const Epi& E) {
;     ...
;             PG8_LDA(At, 1, 1); PG8_STAGE(PG8_SB(1, 0), b3, voffB); PG8_STAGE(PG8_SB(1, 1), b3 + hstep, voffB); PG8_STAGE(PG8_SA(1, 0), a3, voffA);
;             PG8_WAIT_V(8); PG8_WAIT_L(0); PG8_BAR; PG8_MMA(1, 0, At, B0); PG8_MMA(1, 1, At, B1); PG8_BAR; PG8_SCHED;
;     ...
;         if constexpr (ALIGN_EPI) { if (wr == 0) PG8_BAR; }
	s_setprio 0
	s_add_i32 s36, s71, s48
	v_lshl_add_u64 v[8:9], v[174:175], 0, s[14:15]
	s_mov_b32 m0, s36
	ds_read_b128 v[188:191], v178 offset:49152
	ds_read_b128 v[192:195], v178 offset:50176
	ds_read_b128 v[196:199], v178 offset:51200
	ds_read_b128 v[200:203], v178 offset:52224
	ds_read_b128 v[204:207], v178 offset:53248
	ds_read_b128 v[208:211], v178 offset:54272
	ds_read_b128 v[212:215], v178 offset:55296
	ds_read_b128 v[216:219], v178 offset:56320
	global_load_lds_dwordx4 v[8:9], off
	s_add_i32 m0, s36, 0x2000
	s_add_u32 s28, s28, 0x40080
	v_lshl_add_u64 v[8:9], v[222:223], 0, s[14:15]
	s_addc_u32 s29, s29, 0
	s_add_i32 s36, s72, s48
	global_load_lds_dwordx4 v[8:9], off
	v_lshl_add_u64 v[8:9], s[28:29], 0, v[156:157]
	s_mov_b32 m0, s36
	s_nop 0
	global_load_lds_dwordx4 v[8:9], off
	v_lshl_add_u64 v[8:9], s[28:29], 0, v[160:161]
	s_add_i32 m0, s36, 0x2000
	s_nop 0
	global_load_lds_dwordx4 v[8:9], off
	v_lshl_add_u64 v[8:9], v[224:225], 0, s[14:15]
	s_mov_b32 m0, s58
	s_nop 0
	global_load_lds_dwordx4 v[8:9], off
	v_lshl_add_u64 v[8:9], v[226:227], 0, s[14:15]
	s_mov_b32 m0, s59
	s_nop 0
	global_load_lds_dwordx4 v[8:9], off
	s_waitcnt vmcnt(8) lgkmcnt(0)
	s_barrier
	s_setprio 1
	v_mfma_f32_16x16x32_bf16 v[66:69], v[134:137], v[188:191], v[66:69]
	v_mfma_f32_16x16x32_bf16 v[62:65], v[142:145], v[188:191], v[62:65]
	v_mfma_f32_16x16x32_bf16 v[58:61], v[134:137], v[196:199], v[58:61]
	v_mfma_f32_16x16x32_bf16 v[54:57], v[142:145], v[196:199], v[54:57]
	v_mfma_f32_16x16x32_bf16 v[50:53], v[134:137], v[204:207], v[50:53]
	v_mfma_f32_16x16x32_bf16 v[46:49], v[142:145], v[204:207], v[46:49]
	v_mfma_f32_16x16x32_bf16 v[42:45], v[134:137], v[212:215], v[42:45]
	v_mfma_f32_16x16x32_bf16 v[38:41], v[142:145], v[212:215], v[38:41]
	v_mfma_f32_16x16x32_bf16 v[66:69], v[138:141], v[192:195], v[66:69]
	v_mfma_f32_16x16x32_bf16 v[62:65], v[146:149], v[192:195], v[62:65]
	v_mfma_f32_16x16x32_bf16 v[58:61], v[138:141], v[200:203], v[58:61]
	v_mfma_f32_16x16x32_bf16 v[54:57], v[146:149], v[200:203], v[54:57]
	v_mfma_f32_16x16x32_bf16 v[50:53], v[138:141], v[208:211], v[50:53]
	v_mfma_f32_16x16x32_bf16 v[46:49], v[146:149], v[208:211], v[46:49]
	v_mfma_f32_16x16x32_bf16 v[42:45], v[138:141], v[216:219], v[42:45]
	v_mfma_f32_16x16x32_bf16 v[38:41], v[146:149], v[216:219], v[38:41]
	v_mfma_f32_16x16x32_bf16 v[34:37], v[150:153], v[188:191], v[34:37]
	v_mfma_f32_16x16x32_bf16 v[30:33], v[180:183], v[188:191], v[30:33]
	v_mfma_f32_16x16x32_bf16 v[26:29], v[150:153], v[196:199], v[26:29]
	v_mfma_f32_16x16x32_bf16 v[22:25], v[180:183], v[196:199], v[22:25]
	v_mfma_f32_16x16x32_bf16 v[18:21], v[150:153], v[204:207], v[18:21]
	v_mfma_f32_16x16x32_bf16 v[14:17], v[180:183], v[204:207], v[14:17]
	v_mfma_f32_16x16x32_bf16 v[8:11], v[150:153], v[212:215], v[10:13]
	v_mfma_f32_16x16x32_bf16 v[4:7], v[180:183], v[212:215], v[4:7]
	v_mfma_f32_16x16x32_bf16 v[34:37], v[170:173], v[192:195], v[34:37]
	v_mfma_f32_16x16x32_bf16 v[30:33], v[184:187], v[192:195], v[30:33]
	v_mfma_f32_16x16x32_bf16 v[26:29], v[170:173], v[200:203], v[26:29]
	v_mfma_f32_16x16x32_bf16 v[22:25], v[184:187], v[200:203], v[22:25]
	v_mfma_f32_16x16x32_bf16 v[18:21], v[170:173], v[208:211], v[18:21]
	v_mfma_f32_16x16x32_bf16 v[14:17], v[184:187], v[208:211], v[14:17]
	v_mfma_f32_16x16x32_bf16 v[10:13], v[170:173], v[216:219], v[8:11]
	v_mfma_f32_16x16x32_bf16 v[6:9], v[184:187], v[216:219], v[4:7]
	s_barrier
	s_setprio 0
	s_add_i32 s43, s43, 2
	s_add_u32 s0, s0, 0x100
	s_addc_u32 s1, s1, 0
	s_add_u32 s41, s41, 0x100
	s_addc_u32 s42, s42, 0
	s_cmp_gt_u32 s43, 13
	s_cbranch_scc0 .LBB0_723
	s_and_b64 vcc, exec, s[16:17]
	s_cbranch_vccz .LBB0_726
	s_barrier

; #define PG8_STAGE(bufoff, gbase, voff) do { _Pragma("unroll") for (int _i = 0; _i < 2; ++_i) \
;         __builtin_amdgcn_global_load_lds((const unsigned*)((const char*)(gbase) + (voff)[_i]), (PG8_LAS unsigned*)(lds + (bufoff) + ldsw + _i * 8192), 16, 0, 0); } while (0)
; #define PG8_LDA(dst, b, h) do { _Pragma("unroll") for (int m = 0; m < 4; ++m) _Pragma("unroll") for (int k = 0; k < 2; ++k) dst[m][k] = *(const PG8_LAS bf16x8*)(lds + PG8_SA(b, h) + aoff + m * 2048 + k * 1024); } while (0)
; #define PG8_LDB(dst, b, h) do { _Pragma("unroll") for (int n = 0; n < 2; ++n) _Pragma("unroll") for (int k = 0; k < 2; ++k) dst[n][k] = *(const PG8_LAS bf16x8*)(lds + PG8_SB(b, h) + boff + n * 2048 + k * 1024); } while (0)
; #define PG8_MMA(ai, bj, At, Bt) do { __builtin_amdgcn_s_setprio(1); _Pragma("unroll") for (int m = 0; m < 4; ++m) _Pragma("unroll") for (int n = 0; n < 2; ++n) _Pragma("unroll") for (int k = 0; k < 2; ++k) \
;         acc[ai][bj][m][n] = __builtin_amdgcn_mfma_f32_16x16x32_bf16(Bt[n][k], At[m][k], acc[ai][bj][m][n], 0, 0, 0); __builtin_amdgcn_s_setprio(0); } while (0)
; #define PG8_BAR __builtin_amdgcn_s_barrier()
; template <class Epi, class Sched, bool ALIGN_EPI = false, bool SP2 = false>
; __device__ __forceinline__ void gemm_phase(PG8_LAS unsigned char* lds, const Gemm g, const Sched& S, const Epi& E) {
;     ...
;         const char* nA = has_next ? PG8_ABASE(nxt) : cA; const char* nB = has_next ? PG8_BBASE(nxt) : cB;
;         for (int t = 0; t < nt; t += 2) {
;             const bool last = (t == nt - 2);
;             const char* a1 = cA + (size_t)(t + 1) * kstepA;
;             const char* a2 = last ? nA : cA + (size_t)(t + 2) * kstepA; const char* b2 = last ? nB : cB + (size_t)(t + 2) * kstep;
;             const char* a3 = a2 + kstepA; const char* b3 = b2 + kstep;
;             if (last && has_next) S.a_ready(nxt);
;             if constexpr (SP2) {
;             PG8_LDB(B0, 0, 0); PG8_LDB(B1, 0, 1); PG8_SCHED; PG8_LDA(At, 0, 0); PG8_STAGE(PG8_SA(1, 1), a1 + hstep, voffA);
;             PG8_WAIT_V(8); PG8_WAIT_L(0); PG8_BAR; PG8_MMA(0, 0, At, B0); PG8_MMA(0, 1, At, B1); PG8_BAR; PG8_SCHED;
;             if constexpr (Epi::PREFETCH) { if (t == tpf) E.prefetch(cur, wid, lane); }
;             PG8_LDA(At, 0, 1); PG8_STAGE(PG8_SB(0, 0), b2, voffB); PG8_STAGE(PG8_SB(0, 1), b2 + hstep, voffB); PG8_STAGE(PG8_SA(0, 0), a2, voffA);
.LBB0_837:
	s_ashr_i32 s29, s28, 31
	s_lshl_b64 s[30:31], s[28:29], 19
	s_add_u32 s30, s46, s30
	s_addc_u32 s31, s47, s31
	s_and_b64 s[34:35], s[2:3], exec
	s_cselect_b32 s1, s31, s5
	s_cselect_b32 s29, s30, s4
	s_ashr_i32 s27, s26, 31
	s_lshl_b64 s[34:35], s[26:27], 19
	s_add_u32 s34, s48, s34
	s_addc_u32 s35, s49, s35
	s_and_b64 s[36:37], s[2:3], exec
	s_cselect_b32 s27, s35, s7
	s_cselect_b32 s38, s34, s6
	s_add_u32 s4, s4, 0x40080
	s_addc_u32 s5, s5, 0
	s_add_u32 s39, s6, 0x100
	s_addc_u32 s40, s7, 0
	s_mov_b32 s41, -2
	s_waitcnt lgkmcnt(0)
	ds_read_b128 v[50:53], v214
	ds_read_b128 v[54:57], v214 offset:1024
	ds_read_b128 v[66:69], v214 offset:2048
	ds_read_b128 v[70:73], v214 offset:3072
	ds_read_b128 v[146:149], v215
	ds_read_b128 v[150:153], v215 offset:1024
	ds_read_b128 v[172:175], v215 offset:2048
	ds_read_b128 v[176:179], v215 offset:3072
	s_add_u32 s6, s4, 0xfffc0080
	s_addc_u32 s7, s5, -1
	s_cmp_eq_u32 s41, 12
	s_cselect_b32 s37, s1, s7
	s_cselect_b32 s36, s29, s6
	s_cselect_b32 s7, s27, s40
	s_cselect_b32 s6, s38, s39
	v_lshl_add_u64 v[218:219], s[4:5], 0, v[164:165]
	s_add_i32 m0, s51, 0xc000
	ds_read_b128 v[180:183], v216
	ds_read_b128 v[184:187], v216 offset:1024
	ds_read_b128 v[188:191], v216 offset:2048
	ds_read_b128 v[192:195], v216 offset:3072
	ds_read_b128 v[196:199], v216 offset:4096
	ds_read_b128 v[200:203], v216 offset:5120
	ds_read_b128 v[204:207], v216 offset:6144
	ds_read_b128 v[208:211], v216 offset:7168
	global_load_lds_dwordx4 v[218:219], off
	v_lshl_add_u64 v[218:219], s[4:5], 0, v[166:167]
	s_add_i32 m0, s51, 0xe000
	s_nop 0
	global_load_lds_dwordx4 v[218:219], off
	s_waitcnt vmcnt(8) lgkmcnt(0)
	s_barrier
	s_setprio 1
	v_mfma_f32_16x16x32_bf16 v[142:145], v[50:53], v[180:183], 0
	v_mfma_f32_16x16x32_bf16 v[138:141], v[66:69], v[180:183], 0
	v_mfma_f32_16x16x32_bf16 v[126:129], v[50:53], v[188:191], 0
	v_mfma_f32_16x16x32_bf16 v[122:125], v[66:69], v[188:191], 0
	v_mfma_f32_16x16x32_bf16 v[110:113], v[50:53], v[196:199], 0
	v_mfma_f32_16x16x32_bf16 v[106:109], v[66:69], v[196:199], 0
	v_mfma_f32_16x16x32_bf16 v[94:97], v[50:53], v[204:207], 0
	v_mfma_f32_16x16x32_bf16 v[90:93], v[66:69], v[204:207], 0
	v_mfma_f32_16x16x32_bf16 v[142:145], v[54:57], v[184:187], v[142:145]
	v_mfma_f32_16x16x32_bf16 v[138:141], v[70:73], v[184:187], v[138:141]
	v_mfma_f32_16x16x32_bf16 v[126:129], v[54:57], v[192:195], v[126:129]
	v_mfma_f32_16x16x32_bf16 v[122:125], v[70:73], v[192:195], v[122:125]
	v_mfma_f32_16x16x32_bf16 v[110:113], v[54:57], v[200:203], v[110:113]
	v_mfma_f32_16x16x32_bf16 v[106:109], v[70:73], v[200:203], v[106:109]
	v_mfma_f32_16x16x32_bf16 v[94:97], v[54:57], v[208:211], v[94:97]
	v_mfma_f32_16x16x32_bf16 v[90:93], v[70:73], v[208:211], v[90:93]
	v_mfma_f32_16x16x32_bf16 v[134:137], v[146:149], v[180:183], 0
	v_mfma_f32_16x16x32_bf16 v[130:133], v[172:175], v[180:183], 0
	v_mfma_f32_16x16x32_bf16 v[118:121], v[146:149], v[188:191], 0
	v_mfma_f32_16x16x32_bf16 v[114:117], v[172:175], v[188:191], 0
	v_mfma_f32_16x16x32_bf16 v[102:105], v[146:149], v[196:199], 0
	v_mfma_f32_16x16x32_bf16 v[98:101], v[172:175], v[196:199], 0
	v_mfma_f32_16x16x32_bf16 v[86:89], v[146:149], v[204:207], 0
	v_mfma_f32_16x16x32_bf16 v[82:85], v[172:175], v[204:207], 0
	v_mfma_f32_16x16x32_bf16 v[134:137], v[150:153], v[184:187], v[134:137]
	v_mfma_f32_16x16x32_bf16 v[130:133], v[176:179], v[184:187], v[130:133]
	v_mfma_f32_16x16x32_bf16 v[118:121], v[150:153], v[192:195], v[118:121]
	v_mfma_f32_16x16x32_bf16 v[114:117], v[176:179], v[192:195], v[114:117]
	v_mfma_f32_16x16x32_bf16 v[102:105], v[150:153], v[200:203], v[102:105]
	v_mfma_f32_16x16x32_bf16 v[98:101], v[176:179], v[200:203], v[98:101]
	v_mfma_f32_16x16x32_bf16 v[86:89], v[150:153], v[208:211], v[86:89]
	v_mfma_f32_16x16x32_bf16 v[82:85], v[176:179], v[208:211], v[82:85]
	s_barrier
	s_setprio 0
	s_add_i32 s42, s68, s50
	v_lshl_add_u64 v[218:219], s[6:7], 0, v[156:157]
	s_mov_b32 m0, s42
	ds_read_b128 v[180:183], v216 offset:16384
	ds_read_b128 v[184:187], v216 offset:17408
	ds_read_b128 v[188:191], v216 offset:18432
	ds_read_b128 v[192:195], v216 offset:19456
	ds_read_b128 v[196:199], v216 offset:20480
	ds_read_b128 v[200:203], v216 offset:21504
	ds_read_b128 v[204:207], v216 offset:22528
	ds_read_b128 v[208:211], v216 offset:23552
	global_load_lds_dwordx4 v[218:219], off
	s_add_i32 m0, s42, 0x2000
	s_add_u32 s42, s6, 0x40000
	v_lshl_add_u64 v[222:223], s[6:7], 0, v[160:161]
	s_addc_u32 s43, s7, 0
	s_add_i32 s44, s69, s50
	global_load_lds_dwordx4 v[222:223], off
	v_lshl_add_u64 v[224:225], s[42:43], 0, v[156:157]
	s_mov_b32 m0, s44
	v_lshl_add_u64 v[226:227], s[36:37], 0, v[158:159]
	global_load_lds_dwordx4 v[224:225], off
	v_lshl_add_u64 v[224:225], s[42:43], 0, v[160:161]
	s_add_i32 m0, s44, 0x2000
	s_nop 0
	global_load_lds_dwordx4 v[224:225], off
	v_lshl_add_u64 v[224:225], s[36:37], 0, v[154:155]
	s_mov_b32 m0, s51
	s_nop 0
	global_load_lds_dwordx4 v[224:225], off
	s_mov_b32 m0, s52
	s_nop 0
	global_load_lds_dwordx4 v[226:227], off
	s_waitcnt vmcnt(8) lgkmcnt(0)
	s_barrier
; #define PG8_STAGE(bufoff, gbase, voff) do { _Pragma("unroll") for (int _i = 0; _i < 2; ++_i) \
;         __builtin_amdgcn_global_load_lds((const unsigned*)((const char*)(gbase) + (voff)[_i]), (PG8_LAS unsigned*)(lds + (bufoff) + ldsw + _i * 8192), 16, 0, 0); } while (0)
; #define PG8_LDA(dst, b, h) do { _Pragma("unroll") for (int m = 0; m < 4; ++m) _Pragma("unroll") for (int k = 0; k < 2; ++k) dst[m][k] = *(const PG8_LAS bf16x8*)(lds + PG8_SA(b, h) + aoff + m * 2048 + k * 1024); } while (0)
; #define PG8_LDB(dst, b, h) do { _Pragma("unroll") for (int n = 0; n < 2; ++n) _Pragma("unroll") for (int k = 0; k < 2; ++k) dst[n][k] = *(const PG8_LAS bf16x8*)(lds + PG8_SB(b, h) + boff + n * 2048 + k * 1024); } while (0)
; #define PG8_MMA(ai, bj, At, Bt) do { __builtin_amdgcn_s_setprio(1); _Pragma("unroll") for (int m = 0; m < 4; ++m) _Pragma("unroll") for (int n = 0; n < 2; ++n) _Pragma("unroll") for (int k = 0; k < 2; ++k) \
;         acc[ai][bj][m][n] = __builtin_amdgcn_mfma_f32_16x16x32_bf16(Bt[n][k], At[m][k], acc[ai][bj][m][n], 0, 0, 0); __builtin_amdgcn_s_setprio(0); } while (0)
; #define PG8_WAIT_V(n) asm volatile("s_waitcnt vmcnt(" #n ")" ::: "memory")
; #define PG8_WAIT_L(n) asm volatile("s_waitcnt lgkmcnt(" #n ")" ::: "memory")
; #define PG8_BAR __builtin_amdgcn_s_barrier()
; #define PG8_SCHED __builtin_amdgcn_sched_barrier(0)
;     __device__ __forceinline__ void prefetch(const Unit& u, int wid, int lane) const { epi_prefetch(scr, ssq, bias + (size_t)(u.pm >> 5) * NGU + u.pn * BM, u, wid, lane); }
; template <class Epi, class Sched, bool ALIGN_EPI = false, bool SP2 = false>
; __device__ __forceinline__ void gemm_phase(PG8_LAS unsigned char* lds, const Gemm g, const Sched& S, const Epi& E) {
;     ...
;             PG8_LDB(B0, 0, 0); PG8_LDB(B1, 0, 1); PG8_SCHED; PG8_LDA(At, 0, 0); PG8_STAGE(PG8_SA(1, 1), a1 + hstep, voffA);
;             PG8_WAIT_V(8); PG8_WAIT_L(0); PG8_BAR; PG8_MMA(0, 0, At, B0); PG8_MMA(0, 1, At, B1); PG8_BAR; PG8_SCHED;
;             if constexpr (Epi::PREFETCH) { if (t == tpf) E.prefetch(cur, wid, lane); }
;             PG8_LDA(At, 0, 1); PG8_STAGE(PG8_SB(0, 0), b2, voffB); PG8_STAGE(PG8_SB(0, 1), b2 + hstep, voffB); PG8_STAGE(PG8_SA(0, 0), a2, voffA);
;             PG8_WAIT_V(8); PG8_WAIT_L(0); PG8_BAR; PG8_MMA(1, 0, At, B0); PG8_MMA(1, 1, At, B1); PG8_BAR; PG8_SCHED;
	s_setprio 1
	v_mfma_f32_16x16x32_bf16 v[78:81], v[50:53], v[180:183], 0
	v_mfma_f32_16x16x32_bf16 v[74:77], v[66:69], v[180:183], 0
	v_mfma_f32_16x16x32_bf16 v[46:49], v[50:53], v[188:191], 0
	v_mfma_f32_16x16x32_bf16 v[42:45], v[66:69], v[188:191], 0
	v_mfma_f32_16x16x32_bf16 v[30:33], v[50:53], v[196:199], 0
	v_mfma_f32_16x16x32_bf16 v[26:29], v[66:69], v[196:199], 0
	v_mfma_f32_16x16x32_bf16 v[14:17], v[50:53], v[204:207], 0
	v_mfma_f32_16x16x32_bf16 v[10:13], v[66:69], v[204:207], 0
	v_mfma_f32_16x16x32_bf16 v[78:81], v[54:57], v[184:187], v[78:81]
	v_mfma_f32_16x16x32_bf16 v[74:77], v[70:73], v[184:187], v[74:77]
	v_mfma_f32_16x16x32_bf16 v[46:49], v[54:57], v[192:195], v[46:49]
	v_mfma_f32_16x16x32_bf16 v[42:45], v[70:73], v[192:195], v[42:45]
	v_mfma_f32_16x16x32_bf16 v[30:33], v[54:57], v[200:203], v[30:33]
	v_mfma_f32_16x16x32_bf16 v[26:29], v[70:73], v[200:203], v[26:29]
	v_mfma_f32_16x16x32_bf16 v[14:17], v[54:57], v[208:211], v[14:17]
	v_mfma_f32_16x16x32_bf16 v[10:13], v[70:73], v[208:211], v[10:13]
	v_mfma_f32_16x16x32_bf16 v[38:41], v[146:149], v[188:191], 0
	v_mfma_f32_16x16x32_bf16 v[34:37], v[172:175], v[188:191], 0
	v_mfma_f32_16x16x32_bf16 v[22:25], v[146:149], v[196:199], 0
	v_mfma_f32_16x16x32_bf16 v[18:21], v[172:175], v[196:199], 0
	v_mfma_f32_16x16x32_bf16 v[6:9], v[146:149], v[204:207], 0
	v_mfma_f32_16x16x32_bf16 v[2:5], v[172:175], v[204:207], 0
	v_mfma_f32_16x16x32_bf16 v[50:53], v[146:149], v[180:183], 0
	v_mfma_f32_16x16x32_bf16 v[54:57], v[172:175], v[180:183], 0
	v_mfma_f32_16x16x32_bf16 v[38:41], v[150:153], v[192:195], v[38:41]
	v_mfma_f32_16x16x32_bf16 v[34:37], v[176:179], v[192:195], v[34:37]
	v_mfma_f32_16x16x32_bf16 v[22:25], v[150:153], v[200:203], v[22:25]
	v_mfma_f32_16x16x32_bf16 v[18:21], v[176:179], v[200:203], v[18:21]
	v_mfma_f32_16x16x32_bf16 v[6:9], v[150:153], v[208:211], v[6:9]
	v_mfma_f32_16x16x32_bf16 v[2:5], v[176:179], v[208:211], v[2:5]
	v_mfma_f32_16x16x32_bf16 v[50:53], v[150:153], v[184:187], v[50:53]
	v_mfma_f32_16x16x32_bf16 v[54:57], v[176:179], v[184:187], v[54:57]
	s_barrier
	s_setprio 0
	s_branch .Lpz4_mid
.LBB0_838:
	ds_read_b128 v[50:53], v214
	ds_read_b128 v[54:57], v214 offset:1024
	ds_read_b128 v[66:69], v214 offset:2048
	ds_read_b128 v[70:73], v214 offset:3072
	ds_read_b128 v[146:149], v215
	ds_read_b128 v[150:153], v215 offset:1024
	ds_read_b128 v[172:175], v215 offset:2048
	ds_read_b128 v[176:179], v215 offset:3072
	s_add_u32 s6, s4, 0xfffc0080
	s_addc_u32 s7, s5, -1
	s_cmp_eq_u32 s41, 12
	s_cselect_b32 s37, s1, s7
	s_cselect_b32 s36, s29, s6
	s_cselect_b32 s7, s27, s40
	s_cselect_b32 s6, s38, s39
	v_lshl_add_u64 v[218:219], s[4:5], 0, v[164:165]
	s_add_i32 m0, s51, 0xc000
	ds_read_b128 v[180:183], v216
	ds_read_b128 v[184:187], v216 offset:1024
	ds_read_b128 v[188:191], v216 offset:2048
	ds_read_b128 v[192:195], v216 offset:3072
	ds_read_b128 v[196:199], v216 offset:4096
	ds_read_b128 v[200:203], v216 offset:5120
	ds_read_b128 v[204:207], v216 offset:6144
	ds_read_b128 v[208:211], v216 offset:7168
	global_load_lds_dwordx4 v[218:219], off
	v_lshl_add_u64 v[218:219], s[4:5], 0, v[166:167]
	s_add_i32 m0, s51, 0xe000
	s_nop 0
	global_load_lds_dwordx4 v[218:219], off
	s_waitcnt vmcnt(8) lgkmcnt(0)
	s_barrier
	s_setprio 1
	v_mfma_f32_16x16x32_bf16 v[142:145], v[50:53], v[180:183], v[142:145]
	v_mfma_f32_16x16x32_bf16 v[138:141], v[66:69], v[180:183], v[138:141]
	v_mfma_f32_16x16x32_bf16 v[126:129], v[50:53], v[188:191], v[126:129]
	v_mfma_f32_16x16x32_bf16 v[122:125], v[66:69], v[188:191], v[122:125]
	v_mfma_f32_16x16x32_bf16 v[110:113], v[50:53], v[196:199], v[110:113]
	v_mfma_f32_16x16x32_bf16 v[106:109], v[66:69], v[196:199], v[106:109]
	v_mfma_f32_16x16x32_bf16 v[94:97], v[50:53], v[204:207], v[94:97]
	v_mfma_f32_16x16x32_bf16 v[90:93], v[66:69], v[204:207], v[90:93]
	v_mfma_f32_16x16x32_bf16 v[142:145], v[54:57], v[184:187], v[142:145]
	v_mfma_f32_16x16x32_bf16 v[138:141], v[70:73], v[184:187], v[138:141]
	v_mfma_f32_16x16x32_bf16 v[126:129], v[54:57], v[192:195], v[126:129]
	v_mfma_f32_16x16x32_bf16 v[122:125], v[70:73], v[192:195], v[122:125]
	v_mfma_f32_16x16x32_bf16 v[110:113], v[54:57], v[200:203], v[110:113]
	v_mfma_f32_16x16x32_bf16 v[106:109], v[70:73], v[200:203], v[106:109]
	v_mfma_f32_16x16x32_bf16 v[94:97], v[54:57], v[208:211], v[94:97]
	v_mfma_f32_16x16x32_bf16 v[90:93], v[70:73], v[208:211], v[90:93]
	v_mfma_f32_16x16x32_bf16 v[134:137], v[146:149], v[180:183], v[134:137]
	v_mfma_f32_16x16x32_bf16 v[130:133], v[172:175], v[180:183], v[130:133]
	v_mfma_f32_16x16x32_bf16 v[118:121], v[146:149], v[188:191], v[118:121]
	v_mfma_f32_16x16x32_bf16 v[114:117], v[172:175], v[188:191], v[114:117]
	v_mfma_f32_16x16x32_bf16 v[102:105], v[146:149], v[196:199], v[102:105]
	v_mfma_f32_16x16x32_bf16 v[98:101], v[172:175], v[196:199], v[98:101]
	v_mfma_f32_16x16x32_bf16 v[86:89], v[146:149], v[204:207], v[86:89]
	v_mfma_f32_16x16x32_bf16 v[82:85], v[172:175], v[204:207], v[82:85]
	v_mfma_f32_16x16x32_bf16 v[134:137], v[150:153], v[184:187], v[134:137]
	v_mfma_f32_16x16x32_bf16 v[130:133], v[176:179], v[184:187], v[130:133]
	v_mfma_f32_16x16x32_bf16 v[118:121], v[150:153], v[192:195], v[118:121]
	v_mfma_f32_16x16x32_bf16 v[114:117], v[176:179], v[192:195], v[114:117]
	v_mfma_f32_16x16x32_bf16 v[102:105], v[150:153], v[200:203], v[102:105]
	v_mfma_f32_16x16x32_bf16 v[98:101], v[176:179], v[200:203], v[98:101]
	v_mfma_f32_16x16x32_bf16 v[86:89], v[150:153], v[208:211], v[86:89]
	v_mfma_f32_16x16x32_bf16 v[82:85], v[176:179], v[208:211], v[82:85]
	s_barrier
; #define PG8_STAGE(bufoff, gbase, voff) do { _Pragma("unroll") for (int _i = 0; _i < 2; ++_i) \
;         __builtin_amdgcn_global_load_lds((const unsigned*)((const char*)(gbase) + (voff)[_i]), (PG8_LAS unsigned*)(lds + (bufoff) + ldsw + _i * 8192), 16, 0, 0); } while (0)
; #define PG8_LDA(dst, b, h) do { _Pragma("unroll") for (int m = 0; m < 4; ++m) _Pragma("unroll") for (int k = 0; k < 2; ++k) dst[m][k] = *(const PG8_LAS bf16x8*)(lds + PG8_SA(b, h) + aoff + m * 2048 + k * 1024); } while (0)
; #define PG8_LDB(dst, b, h) do { _Pragma("unroll") for (int n = 0; n < 2; ++n) _Pragma("unroll") for (int k = 0; k < 2; ++k) dst[n][k] = *(const PG8_LAS bf16x8*)(lds + PG8_SB(b, h) + boff + n * 2048 + k * 1024); } while (0)
; #define PG8_MMA(ai, bj, At, Bt) do { __builtin_amdgcn_s_setprio(1); _Pragma("unroll") for (int m = 0; m < 4; ++m) _Pragma("unroll") for (int n = 0; n < 2; ++n) _Pragma("unroll") for (int k = 0; k < 2; ++k) \
;         acc[ai][bj][m][n] = __builtin_amdgcn_mfma_f32_16x16x32_bf16(Bt[n][k], At[m][k], acc[ai][bj][m][n], 0, 0, 0); __builtin_amdgcn_s_setprio(0); } while (0)
; #define PG8_WAIT_V(n) asm volatile("s_waitcnt vmcnt(" #n ")" ::: "memory")
; #define PG8_WAIT_L(n) asm volatile("s_waitcnt lgkmcnt(" #n ")" ::: "memory")
; #define PG8_BAR __builtin_amdgcn_s_barrier()
; #define PG8_SCHED __builtin_amdgcn_sched_barrier(0)
; template <class Epi, class Sched, bool ALIGN_EPI = false, bool SP2 = false>
; __device__ __forceinline__ void gemm_phase(PG8_LAS unsigned char* lds, const Gemm g, const Sched& S, const Epi& E) {
;     ...
;             PG8_LDA(At, 0, 1); PG8_STAGE(PG8_SB(0, 0), b2, voffB); PG8_STAGE(PG8_SB(0, 1), b2 + hstep, voffB); PG8_STAGE(PG8_SA(0, 0), a2, voffA);
;             PG8_WAIT_V(8); PG8_WAIT_L(0); PG8_BAR; PG8_MMA(1, 0, At, B0); PG8_MMA(1, 1, At, B1); PG8_BAR; PG8_SCHED;
;             PG8_LDB(B0, 1, 0); PG8_LDB(B1, 1, 1); PG8_SCHED; PG8_LDA(At, 1, 0); PG8_STAGE(PG8_SA(0, 1), a2 + hstep, voffA);
;             PG8_WAIT_V(8); PG8_WAIT_L(0); PG8_BAR; PG8_MMA(0, 0, At, B0); PG8_MMA(0, 1, At, B1); PG8_BAR; PG8_SCHED;
	s_setprio 0
	s_add_i32 s42, s68, s50
	v_lshl_add_u64 v[218:219], s[6:7], 0, v[156:157]
	s_mov_b32 m0, s42
	ds_read_b128 v[180:183], v216 offset:16384
	ds_read_b128 v[184:187], v216 offset:17408
	ds_read_b128 v[188:191], v216 offset:18432
	ds_read_b128 v[192:195], v216 offset:19456
	ds_read_b128 v[196:199], v216 offset:20480
	ds_read_b128 v[200:203], v216 offset:21504
	ds_read_b128 v[204:207], v216 offset:22528
	ds_read_b128 v[208:211], v216 offset:23552
	global_load_lds_dwordx4 v[218:219], off
	s_add_i32 m0, s42, 0x2000
	s_add_u32 s42, s6, 0x40000
	v_lshl_add_u64 v[222:223], s[6:7], 0, v[160:161]
	s_addc_u32 s43, s7, 0
	s_add_i32 s44, s69, s50
	global_load_lds_dwordx4 v[222:223], off
	v_lshl_add_u64 v[224:225], s[42:43], 0, v[156:157]
	s_mov_b32 m0, s44
	v_lshl_add_u64 v[226:227], s[36:37], 0, v[158:159]
	global_load_lds_dwordx4 v[224:225], off
	v_lshl_add_u64 v[224:225], s[42:43], 0, v[160:161]
	s_add_i32 m0, s44, 0x2000
	s_nop 0
	global_load_lds_dwordx4 v[224:225], off
	v_lshl_add_u64 v[224:225], s[36:37], 0, v[154:155]
	s_mov_b32 m0, s51
	s_nop 0
	global_load_lds_dwordx4 v[224:225], off
	s_mov_b32 m0, s52
	s_nop 0
	global_load_lds_dwordx4 v[226:227], off
	s_waitcnt vmcnt(8) lgkmcnt(0)
	s_barrier
	s_setprio 1
	v_mfma_f32_16x16x32_bf16 v[78:81], v[50:53], v[180:183], v[78:81]
	v_mfma_f32_16x16x32_bf16 v[74:77], v[66:69], v[180:183], v[74:77]
	v_mfma_f32_16x16x32_bf16 v[46:49], v[50:53], v[188:191], v[46:49]
	v_mfma_f32_16x16x32_bf16 v[42:45], v[66:69], v[188:191], v[42:45]
	v_mfma_f32_16x16x32_bf16 v[30:33], v[50:53], v[196:199], v[30:33]
	v_mfma_f32_16x16x32_bf16 v[26:29], v[66:69], v[196:199], v[26:29]
	v_mfma_f32_16x16x32_bf16 v[14:17], v[50:53], v[204:207], v[14:17]
	v_mfma_f32_16x16x32_bf16 v[10:13], v[66:69], v[204:207], v[10:13]
	v_mfma_f32_16x16x32_bf16 v[78:81], v[54:57], v[184:187], v[78:81]
	v_mfma_f32_16x16x32_bf16 v[74:77], v[70:73], v[184:187], v[74:77]
	v_mfma_f32_16x16x32_bf16 v[46:49], v[54:57], v[192:195], v[46:49]
	v_mfma_f32_16x16x32_bf16 v[42:45], v[70:73], v[192:195], v[42:45]
	v_mfma_f32_16x16x32_bf16 v[30:33], v[54:57], v[200:203], v[30:33]
	v_mfma_f32_16x16x32_bf16 v[26:29], v[70:73], v[200:203], v[26:29]
	v_mfma_f32_16x16x32_bf16 v[14:17], v[54:57], v[208:211], v[14:17]
	v_mfma_f32_16x16x32_bf16 v[10:13], v[70:73], v[208:211], v[10:13]
	v_mfma_f32_16x16x32_bf16 v[38:41], v[146:149], v[188:191], v[38:41]
	v_mfma_f32_16x16x32_bf16 v[34:37], v[172:175], v[188:191], v[34:37]
	v_mfma_f32_16x16x32_bf16 v[22:25], v[146:149], v[196:199], v[22:25]
	v_mfma_f32_16x16x32_bf16 v[18:21], v[172:175], v[196:199], v[18:21]
	v_mfma_f32_16x16x32_bf16 v[6:9], v[146:149], v[204:207], v[6:9]
	v_mfma_f32_16x16x32_bf16 v[2:5], v[172:175], v[204:207], v[2:5]
	v_mfma_f32_16x16x32_bf16 v[50:53], v[146:149], v[180:183], v[62:65]
	v_mfma_f32_16x16x32_bf16 v[54:57], v[172:175], v[180:183], v[58:61]
	v_mfma_f32_16x16x32_bf16 v[38:41], v[150:153], v[192:195], v[38:41]
	v_mfma_f32_16x16x32_bf16 v[34:37], v[176:179], v[192:195], v[34:37]
	v_mfma_f32_16x16x32_bf16 v[22:25], v[150:153], v[200:203], v[22:25]
	v_mfma_f32_16x16x32_bf16 v[18:21], v[176:179], v[200:203], v[18:21]
	v_mfma_f32_16x16x32_bf16 v[6:9], v[150:153], v[208:211], v[6:9]
	v_mfma_f32_16x16x32_bf16 v[2:5], v[176:179], v[208:211], v[2:5]
	v_mfma_f32_16x16x32_bf16 v[50:53], v[150:153], v[184:187], v[50:53]
	v_mfma_f32_16x16x32_bf16 v[54:57], v[176:179], v[184:187], v[54:57]
	s_barrier
	s_setprio 0
.Lpz4_mid:
	s_add_i32 s42, 0, 0x18000
	s_add_i32 s43, 0, 0x1c000
	v_add_u32_e32 v70, s42, v213
	v_add_u32_e32 v162, s43, v213
	ds_read_b128 v[58:61], v70
	ds_read_b128 v[62:65], v70 offset:1024
	ds_read_b128 v[66:69], v70 offset:2048
	ds_read_b128 v[70:73], v70 offset:3072
	ds_read_b128 v[146:149], v162
	ds_read_b128 v[150:153], v162 offset:1024
	ds_read_b128 v[172:175], v162 offset:2048
	ds_read_b128 v[176:179], v162 offset:3072
	s_add_u32 s36, s36, 0x40000
	s_addc_u32 s37, s37, 0
	s_mov_b32 m0, s53
	v_lshl_add_u64 v[228:229], s[36:37], 0, v[154:155]
	ds_read_b128 v[180:183], v216 offset:32768
	ds_read_b128 v[184:187], v216 offset:33792
	ds_read_b128 v[188:191], v216 offset:34816
	ds_read_b128 v[192:195], v216 offset:35840
	ds_read_b128 v[196:199], v216 offset:36864
	ds_read_b128 v[200:203], v216 offset:37888
	ds_read_b128 v[204:207], v216 offset:38912
	ds_read_b128 v[208:211], v216 offset:39936
	global_load_lds_dwordx4 v[228:229], off
	v_lshl_add_u64 v[228:229], s[36:37], 0, v[158:159]
	s_mov_b32 m0, s54
	s_nop 0
	global_load_lds_dwordx4 v[228:229], off
	s_waitcnt vmcnt(8) lgkmcnt(0)
	s_barrier
; #define PG8_STAGE(bufoff, gbase, voff) do { _Pragma("unroll") for (int _i = 0; _i < 2; ++_i) \
;         __builtin_amdgcn_global_load_lds((const unsigned*)((const char*)(gbase) + (voff)[_i]), (PG8_LAS unsigned*)(lds + (bufoff) + ldsw + _i * 8192), 16, 0, 0); } while (0)
; #define PG8_LDA(dst, b, h) do { _Pragma("unroll") for (int m = 0; m < 4; ++m) _Pragma("unroll") for (int k = 0; k < 2; ++k) dst[m][k] = *(const PG8_LAS bf16x8*)(lds + PG8_SA(b, h) + aoff + m * 2048 + k * 1024); } while (0)
; #define PG8_MMA(ai, bj, At, Bt) do { __builtin_amdgcn_s_setprio(1); _Pragma("unroll") for (int m = 0; m < 4; ++m) _Pragma("unroll") for (int n = 0; n < 2; ++n) _Pragma("unroll") for (int k = 0; k < 2; ++k) \
;         acc[ai][bj][m][n] = __builtin_amdgcn_mfma_f32_16x16x32_bf16(Bt[n][k], At[m][k], acc[ai][bj][m][n], 0, 0, 0); __builtin_amdgcn_s_setprio(0); } while (0)
; #define PG8_WAIT_V(n) asm volatile("s_waitcnt vmcnt(" #n ")" ::: "memory")
; #define PG8_WAIT_L(n) asm volatile("s_waitcnt lgkmcnt(" #n ")" ::: "memory")
; #define PG8_BAR __builtin_amdgcn_s_barrier()
; #define PG8_SCHED __builtin_amdgcn_sched_barrier(0)
; template <class Epi, class Sched, bool ALIGN_EPI = false, bool SP2 = false>
; __device__ __forceinline__ void gemm_phase(PG8_LAS unsigned char* lds, const Gemm g, const Sched& S, const Epi& E) {
;     ...
;             PG8_WAIT_V(8); PG8_WAIT_L(0); PG8_BAR; PG8_MMA(0, 0, At, B0); PG8_MMA(0, 1, At, B1); PG8_BAR; PG8_SCHED;
;             PG8_LDA(At, 1, 1); PG8_STAGE(PG8_SB(1, 0), b3, voffB); PG8_STAGE(PG8_SB(1, 1), b3 + hstep, voffB); PG8_STAGE(PG8_SA(1, 0), a3, voffA);
;             PG8_WAIT_V(8); PG8_WAIT_L(0); PG8_BAR; PG8_MMA(1, 0, At, B0); PG8_MMA(1, 1, At, B1); PG8_BAR; PG8_SCHED;
;     ...
;         if constexpr (ALIGN_EPI) { if (wr == 0) PG8_BAR; }
	s_setprio 1
	v_mfma_f32_16x16x32_bf16 v[142:145], v[58:61], v[180:183], v[142:145]
	v_mfma_f32_16x16x32_bf16 v[138:141], v[66:69], v[180:183], v[138:141]
	v_mfma_f32_16x16x32_bf16 v[126:129], v[58:61], v[188:191], v[126:129]
	v_mfma_f32_16x16x32_bf16 v[122:125], v[66:69], v[188:191], v[122:125]
	v_mfma_f32_16x16x32_bf16 v[110:113], v[58:61], v[196:199], v[110:113]
	v_mfma_f32_16x16x32_bf16 v[106:109], v[66:69], v[196:199], v[106:109]
	v_mfma_f32_16x16x32_bf16 v[94:97], v[58:61], v[204:207], v[94:97]
	v_mfma_f32_16x16x32_bf16 v[90:93], v[66:69], v[204:207], v[90:93]
	v_mfma_f32_16x16x32_bf16 v[142:145], v[62:65], v[184:187], v[142:145]
	v_mfma_f32_16x16x32_bf16 v[138:141], v[70:73], v[184:187], v[138:141]
	v_mfma_f32_16x16x32_bf16 v[126:129], v[62:65], v[192:195], v[126:129]
	v_mfma_f32_16x16x32_bf16 v[122:125], v[70:73], v[192:195], v[122:125]
	v_mfma_f32_16x16x32_bf16 v[110:113], v[62:65], v[200:203], v[110:113]
	v_mfma_f32_16x16x32_bf16 v[106:109], v[70:73], v[200:203], v[106:109]
	v_mfma_f32_16x16x32_bf16 v[94:97], v[62:65], v[208:211], v[94:97]
	v_mfma_f32_16x16x32_bf16 v[90:93], v[70:73], v[208:211], v[90:93]
	v_mfma_f32_16x16x32_bf16 v[134:137], v[146:149], v[180:183], v[134:137]
	v_mfma_f32_16x16x32_bf16 v[130:133], v[172:175], v[180:183], v[130:133]
	v_mfma_f32_16x16x32_bf16 v[118:121], v[146:149], v[188:191], v[118:121]
	v_mfma_f32_16x16x32_bf16 v[114:117], v[172:175], v[188:191], v[114:117]
	v_mfma_f32_16x16x32_bf16 v[102:105], v[146:149], v[196:199], v[102:105]
	v_mfma_f32_16x16x32_bf16 v[98:101], v[172:175], v[196:199], v[98:101]
	v_mfma_f32_16x16x32_bf16 v[86:89], v[146:149], v[204:207], v[86:89]
	v_mfma_f32_16x16x32_bf16 v[82:85], v[172:175], v[204:207], v[82:85]
	v_mfma_f32_16x16x32_bf16 v[134:137], v[150:153], v[184:187], v[134:137]
	v_mfma_f32_16x16x32_bf16 v[130:133], v[176:179], v[184:187], v[130:133]
	v_mfma_f32_16x16x32_bf16 v[118:121], v[150:153], v[192:195], v[118:121]
	v_mfma_f32_16x16x32_bf16 v[114:117], v[176:179], v[192:195], v[114:117]
	v_mfma_f32_16x16x32_bf16 v[102:105], v[150:153], v[200:203], v[102:105]
	v_mfma_f32_16x16x32_bf16 v[98:101], v[176:179], v[200:203], v[98:101]
	v_mfma_f32_16x16x32_bf16 v[86:89], v[150:153], v[208:211], v[86:89]
	v_mfma_f32_16x16x32_bf16 v[82:85], v[176:179], v[208:211], v[82:85]
	s_barrier
	s_setprio 0
	s_add_i32 s36, s42, s50
	v_lshl_add_u64 v[218:219], v[218:219], 0, s[20:21]
	s_mov_b32 m0, s36
	ds_read_b128 v[180:183], v216 offset:49152
	ds_read_b128 v[184:187], v216 offset:50176
	ds_read_b128 v[188:191], v216 offset:51200
	ds_read_b128 v[192:195], v216 offset:52224
	ds_read_b128 v[196:199], v216 offset:53248
	ds_read_b128 v[200:203], v216 offset:54272
	ds_read_b128 v[204:207], v216 offset:55296
	ds_read_b128 v[208:211], v216 offset:56320
	global_load_lds_dwordx4 v[218:219], off
	s_add_i32 m0, s36, 0x2000
	s_add_u32 s6, s6, 0x40080
	v_lshl_add_u64 v[218:219], v[222:223], 0, s[20:21]
	s_addc_u32 s7, s7, 0
	s_add_i32 s36, s43, s50
	global_load_lds_dwordx4 v[218:219], off
	v_lshl_add_u64 v[218:219], s[6:7], 0, v[156:157]
	s_mov_b32 m0, s36
	s_nop 0
	global_load_lds_dwordx4 v[218:219], off
	v_lshl_add_u64 v[218:219], s[6:7], 0, v[160:161]
	s_add_i32 m0, s36, 0x2000
	s_nop 0
	global_load_lds_dwordx4 v[218:219], off
	v_lshl_add_u64 v[218:219], v[224:225], 0, s[20:21]
	s_mov_b32 m0, s63
	s_nop 0
	global_load_lds_dwordx4 v[218:219], off
	v_lshl_add_u64 v[218:219], v[226:227], 0, s[20:21]
	s_mov_b32 m0, s64
	s_nop 0
	global_load_lds_dwordx4 v[218:219], off
	s_waitcnt vmcnt(8) lgkmcnt(0)
	s_barrier
	s_setprio 1
	v_mfma_f32_16x16x32_bf16 v[78:81], v[58:61], v[180:183], v[78:81]
	v_mfma_f32_16x16x32_bf16 v[74:77], v[66:69], v[180:183], v[74:77]
	v_mfma_f32_16x16x32_bf16 v[46:49], v[58:61], v[188:191], v[46:49]
	v_mfma_f32_16x16x32_bf16 v[42:45], v[66:69], v[188:191], v[42:45]
	v_mfma_f32_16x16x32_bf16 v[30:33], v[58:61], v[196:199], v[30:33]
	v_mfma_f32_16x16x32_bf16 v[26:29], v[66:69], v[196:199], v[26:29]
	v_mfma_f32_16x16x32_bf16 v[14:17], v[58:61], v[204:207], v[14:17]
	v_mfma_f32_16x16x32_bf16 v[10:13], v[66:69], v[204:207], v[10:13]
	v_mfma_f32_16x16x32_bf16 v[78:81], v[62:65], v[184:187], v[78:81]
	v_mfma_f32_16x16x32_bf16 v[74:77], v[70:73], v[184:187], v[74:77]
	v_mfma_f32_16x16x32_bf16 v[46:49], v[62:65], v[192:195], v[46:49]
	v_mfma_f32_16x16x32_bf16 v[42:45], v[70:73], v[192:195], v[42:45]
	v_mfma_f32_16x16x32_bf16 v[30:33], v[62:65], v[200:203], v[30:33]
	v_mfma_f32_16x16x32_bf16 v[26:29], v[70:73], v[200:203], v[26:29]
	v_mfma_f32_16x16x32_bf16 v[14:17], v[62:65], v[208:211], v[14:17]
	v_mfma_f32_16x16x32_bf16 v[10:13], v[70:73], v[208:211], v[10:13]
	v_mfma_f32_16x16x32_bf16 v[50:53], v[146:149], v[180:183], v[50:53]
	v_mfma_f32_16x16x32_bf16 v[62:65], v[150:153], v[184:187], v[50:53]
	v_mfma_f32_16x16x32_bf16 v[50:53], v[172:175], v[180:183], v[54:57]
	v_mfma_f32_16x16x32_bf16 v[38:41], v[146:149], v[188:191], v[38:41]
	v_mfma_f32_16x16x32_bf16 v[34:37], v[172:175], v[188:191], v[34:37]
	v_mfma_f32_16x16x32_bf16 v[22:25], v[146:149], v[196:199], v[22:25]
	v_mfma_f32_16x16x32_bf16 v[18:21], v[172:175], v[196:199], v[18:21]
	v_mfma_f32_16x16x32_bf16 v[6:9], v[146:149], v[204:207], v[6:9]
	v_mfma_f32_16x16x32_bf16 v[2:5], v[172:175], v[204:207], v[2:5]
	v_mfma_f32_16x16x32_bf16 v[58:61], v[176:179], v[184:187], v[50:53]
	v_mfma_f32_16x16x32_bf16 v[38:41], v[150:153], v[192:195], v[38:41]
	v_mfma_f32_16x16x32_bf16 v[34:37], v[176:179], v[192:195], v[34:37]
	v_mfma_f32_16x16x32_bf16 v[22:25], v[150:153], v[200:203], v[22:25]
	v_mfma_f32_16x16x32_bf16 v[18:21], v[176:179], v[200:203], v[18:21]
	v_mfma_f32_16x16x32_bf16 v[6:9], v[150:153], v[208:211], v[6:9]
	v_mfma_f32_16x16x32_bf16 v[2:5], v[176:179], v[208:211], v[2:5]
	s_barrier
	s_setprio 0
	s_add_i32 s41, s41, 2
	s_add_u32 s4, s4, 0x100
	s_addc_u32 s5, s5, 0
	s_add_u32 s39, s39, 0x100
	s_addc_u32 s40, s40, 0
	s_cmp_gt_u32 s41, 13
	s_cbranch_scc0 .LBB0_838
	s_and_b64 vcc, exec, s[22:23]
	s_cbranch_vccz .LBB0_841
	s_barrier

;     __host__ __device__ bool next(int i, Unit& u) const { if (!b.next(i >> 1, u)) return false; u.sel = i & 1; return true; }
; #define PG8_STAGE(bufoff, gbase, voff) do { _Pragma("unroll") for (int _i = 0; _i < 2; ++_i) \
;         __builtin_amdgcn_global_load_lds((const unsigned*)((const char*)(gbase) + (voff)[_i]), (PG8_LAS unsigned*)(lds + (bufoff) + ldsw + _i * 8192), 16, 0, 0); } while (0)
; #define PG8_LDA(dst, b, h) do { _Pragma("unroll") for (int m = 0; m < 4; ++m) _Pragma("unroll") for (int k = 0; k < 2; ++k) dst[m][k] = *(const PG8_LAS bf16x8*)(lds + PG8_SA(b, h) + aoff + m * 2048 + k * 1024); } while (0)
; #define PG8_WAIT_V(n) asm volatile("s_waitcnt vmcnt(" #n ")" ::: "memory")
;     __host__ __device__ bool next(int i, Unit& u) const {
;         const long L = (long)i * G + c; if (L >= nwg) return false;
;         int wgid = (int)L; { const int q = nwg / NXCD, r = nwg % NXCD, xcd = wgid % NXCD, off = wgid / NXCD; wgid = (xcd < r ? xcd * (q + 1) : r * (q + 1) + (xcd - r) * q) + off; }
;         const int nig = WGM * nN, gid = wgid / nig, fm = gid * WGM, gsz = (nM - fm) < WGM ? (nM - fm) : WGM;
;         u.pm = fm + ((wgid % nig) % gsz); u.pn = (wgid % nig) / gsz; u.sel = 0; return true;
; template <class Epi, class Sched, bool ALIGN_EPI = false, bool SP2 = false>
; __device__ __forceinline__ void gemm_phase(PG8_LAS unsigned char* lds, const Gemm g, const Sched& S, const Epi& E) {
;     ...
;         const bool has_next = S.next(ui + 1, nxt);
;         const char* nA = has_next ? PG8_ABASE(nxt) : cA; const char* nB = has_next ? PG8_BBASE(nxt) : cB;
;         for (int t = 0; t < nt; t += 2) {
;             const bool last = (t == nt - 2);
;             const char* a1 = cA + (size_t)(t + 1) * kstepA;
;             const char* a2 = last ? nA : cA + (size_t)(t + 2) * kstepA; const char* b2 = last ? nB : cB + (size_t)(t + 2) * kstep;
;             const char* a3 = a2 + kstepA; const char* b3 = b2 + kstep;
;             if (last && has_next) S.a_ready(nxt);
;             if constexpr (SP2) {
;             PG8_LDB(B0, 0, 0); PG8_LDB(B1, 0, 1); PG8_SCHED; PG8_LDA(At, 0, 0); PG8_STAGE(PG8_SA(1, 1), a1 + hstep, voffA);
;             PG8_WAIT_V(8); PG8_WAIT_L(0); PG8_BAR; PG8_MMA(0, 0, At, B0); PG8_MMA(0, 1, At, B1); PG8_BAR; PG8_SCHED;
;             if constexpr (Epi::PREFETCH) { if (t == tpf) E.prefetch(cur, wid, lane); }
.LBB0_982:
	s_ashr_i32 s29, s28, 31
	s_lshl_b32 s34, s34, 8
	s_lshl_b64 s[36:37], s[28:29], 14
	s_ashr_i32 s29, s28, 5
	s_ashr_i32 s35, s34, 31
	s_add_u32 s36, s10, s36
	s_mul_hi_i32 s38, s29, 0x5800
	s_mulk_i32 s29, 0x5800
	s_addc_u32 s37, s69, s37
	s_add_u32 s29, s62, s29
	s_addc_u32 s42, s63, s38
	s_lshl_b64 s[38:39], s[34:35], 2
	s_add_u32 s38, s29, s38
	s_addc_u32 s39, s42, s39
	s_add_u32 s29, s40, 0x100
	v_lshl_add_u64 v[188:189], s[30:31], 0, v[180:181]
	v_lshl_add_u64 v[190:191], s[30:31], 0, v[182:183]
	s_addc_u32 s35, s41, 0
	s_mov_b32 s83, 0
	s_mov_b64 s[40:41], 0
	ds_read_b128 v[154:157], v195
	ds_read_b128 v[158:161], v195 offset:1024
	ds_read_b128 v[162:165], v195 offset:2048
	ds_read_b128 v[166:169], v195 offset:3072
	ds_read_b128 v[138:141], v196
	ds_read_b128 v[142:145], v196 offset:1024
	ds_read_b128 v[146:149], v196 offset:2048
	ds_read_b128 v[150:153], v196 offset:3072
	v_lshl_add_u64 v[98:99], v[188:189], 0, s[40:41]
	s_add_i32 m0, s54, 0xc000
	ds_read_b128 v[200:203], v197
	ds_read_b128 v[204:207], v197 offset:1024
	ds_read_b128 v[208:211], v197 offset:2048
	ds_read_b128 v[212:215], v197 offset:3072
	ds_read_b128 v[216:219], v197 offset:4096
	ds_read_b128 v[220:223], v197 offset:5120
	ds_read_b128 v[224:227], v197 offset:6144
	ds_read_b128 v[228:231], v197 offset:7168
	global_load_lds_dwordx4 v[98:99], off
	v_lshl_add_u64 v[98:99], v[190:191], 0, s[40:41]
	s_add_i32 m0, s54, 0xe000
	s_nop 0
	global_load_lds_dwordx4 v[98:99], off
	s_add_i32 s11, s11, 1
	s_mul_i32 s2, s11, s68
	s_mul_hi_u32 s3, s11, s33
	s_add_i32 s3, s3, s2
	s_mul_i32 s2, s11, s33
	s_add_u32 s24, s2, s87
	s_addc_u32 s25, s3, s52
	v_cmp_lt_i64_e64 s[2:3], s[24:25], v[184:185]
	s_ashr_i32 s20, s24, 31
	s_lshr_b32 s20, s20, 29
	s_add_i32 s20, s24, s20
	s_ashr_i32 s21, s20, 3
	s_and_b32 s20, s20, -8
	s_sub_i32 s20, s24, s20
	s_cmp_lt_i32 s20, 0
	s_cselect_b32 s22, s53, 0x160
	s_mul_i32 s20, s20, s22
	s_add_i32 s20, s20, s21
	s_mul_hi_i32 s21, s20, 0x2e8ba2e9
	s_lshr_b32 s22, s21, 31
	s_ashr_i32 s21, s21, 3
	s_add_i32 s21, s21, s22
	s_lshl_b32 s22, s21, 1
	s_mul_i32 s21, s21, 44
	s_sub_i32 s21, s20, s21
	s_lshr_b32 s20, s21, 1
	s_and_b32 s21, s21, 1
	s_add_i32 s22, s22, s21
	s_ashr_i32 s23, s22, 31
	s_lshl_b64 s[24:25], s[22:23], 19
	s_add_u32 s24, s47, s24
	s_addc_u32 s25, s48, s25
	s_and_b64 s[26:27], s[2:3], exec
	s_cselect_b32 s23, s25, s48
	s_cselect_b32 s81, s24, s47
	s_ashr_i32 s21, s20, 31
	s_lshl_b64 s[26:27], s[20:21], 19
	s_add_u32 s26, s49, s26
	s_addc_u32 s27, s50, s27
	s_and_b64 s[98:99], s[2:3], exec
	s_cselect_b32 s21, s27, s50
	s_cselect_b32 s82, s26, s49
	s_waitcnt vmcnt(8) lgkmcnt(0)
	s_barrier
	s_setprio 1
	v_mfma_f32_16x16x32_bf16 v[98:101], v[154:157], v[200:203], 0
	v_mfma_f32_16x16x32_bf16 v[106:109], v[162:165], v[200:203], 0
	v_mfma_f32_16x16x32_bf16 v[118:121], v[154:157], v[208:211], 0
	v_mfma_f32_16x16x32_bf16 v[114:117], v[162:165], v[208:211], 0
	v_mfma_f32_16x16x32_bf16 v[94:97], v[154:157], v[216:219], 0
	v_mfma_f32_16x16x32_bf16 v[90:93], v[162:165], v[216:219], 0
	v_mfma_f32_16x16x32_bf16 v[78:81], v[154:157], v[224:227], 0
	v_mfma_f32_16x16x32_bf16 v[74:77], v[162:165], v[224:227], 0
	v_mfma_f32_16x16x32_bf16 v[98:101], v[158:161], v[204:207], v[98:101]
	v_mfma_f32_16x16x32_bf16 v[106:109], v[166:169], v[204:207], v[106:109]
	v_mfma_f32_16x16x32_bf16 v[118:121], v[158:161], v[212:215], v[118:121]
	v_mfma_f32_16x16x32_bf16 v[114:117], v[166:169], v[212:215], v[114:117]
	v_mfma_f32_16x16x32_bf16 v[94:97], v[158:161], v[220:223], v[94:97]
	v_mfma_f32_16x16x32_bf16 v[90:93], v[166:169], v[220:223], v[90:93]
	v_mfma_f32_16x16x32_bf16 v[78:81], v[158:161], v[228:231], v[78:81]
	v_mfma_f32_16x16x32_bf16 v[74:77], v[166:169], v[228:231], v[74:77]
	v_mfma_f32_16x16x32_bf16 v[126:129], v[138:141], v[200:203], 0
	v_mfma_f32_16x16x32_bf16 v[122:125], v[146:149], v[200:203], 0
	v_mfma_f32_16x16x32_bf16 v[110:113], v[138:141], v[208:211], 0
	v_mfma_f32_16x16x32_bf16 v[102:105], v[146:149], v[208:211], 0
	v_mfma_f32_16x16x32_bf16 v[86:89], v[138:141], v[216:219], 0
	v_mfma_f32_16x16x32_bf16 v[82:85], v[146:149], v[216:219], 0
	v_mfma_f32_16x16x32_bf16 v[70:73], v[138:141], v[224:227], 0
	v_mfma_f32_16x16x32_bf16 v[66:69], v[146:149], v[224:227], 0
	v_mfma_f32_16x16x32_bf16 v[126:129], v[142:145], v[204:207], v[126:129]
	v_mfma_f32_16x16x32_bf16 v[122:125], v[150:153], v[204:207], v[122:125]
	v_mfma_f32_16x16x32_bf16 v[110:113], v[142:145], v[212:215], v[110:113]
	v_mfma_f32_16x16x32_bf16 v[102:105], v[150:153], v[212:215], v[102:105]
	v_mfma_f32_16x16x32_bf16 v[86:89], v[142:145], v[220:223], v[86:89]
	v_mfma_f32_16x16x32_bf16 v[82:85], v[150:153], v[220:223], v[82:85]
	v_mfma_f32_16x16x32_bf16 v[70:73], v[142:145], v[228:231], v[70:73]
	v_mfma_f32_16x16x32_bf16 v[66:69], v[150:153], v[228:231], v[66:69]
	s_barrier
	s_setprio 0
	s_cmp_lg_u32 s46, s83
	s_cbranch_scc1 .Lpz5_a
	v_mov_b32_e32 v178, v194
	s_add_i32 m0, s79, 0x20000
	v_lshl_add_u64 v[130:131], s[36:37], 0, v[178:179]
	global_load_lds_dwordx4 v178, s[36:37]
	v_lshl_add_u64 v[130:131], v[130:131], 0, s[18:19]
	s_add_i32 m0, s79, 0x20400
	s_andn2_b64 vcc, exec, s[14:15]
	global_load_lds_dwordx4 v[130:131], off
	s_cbranch_vccnz .Lpz5_a
	v_lshl_add_u64 v[130:131], s[38:39], 0, v[178:179]
	s_add_i32 m0, 0, 0x24000
	s_nop 0
	global_load_lds_dwordx4 v[130:131], off
	s_branch .Lpz5_a
; #define PG8_STAGE(bufoff, gbase, voff) do { _Pragma("unroll") for (int _i = 0; _i < 2; ++_i) \
;         __builtin_amdgcn_global_load_lds((const unsigned*)((const char*)(gbase) + (voff)[_i]), (PG8_LAS unsigned*)(lds + (bufoff) + ldsw + _i * 8192), 16, 0, 0); } while (0)
; #define PG8_LDA(dst, b, h) do { _Pragma("unroll") for (int m = 0; m < 4; ++m) _Pragma("unroll") for (int k = 0; k < 2; ++k) dst[m][k] = *(const PG8_LAS bf16x8*)(lds + PG8_SA(b, h) + aoff + m * 2048 + k * 1024); } while (0)
; #define PG8_LDB(dst, b, h) do { _Pragma("unroll") for (int n = 0; n < 2; ++n) _Pragma("unroll") for (int k = 0; k < 2; ++k) dst[n][k] = *(const PG8_LAS bf16x8*)(lds + PG8_SB(b, h) + boff + n * 2048 + k * 1024); } while (0)
; #define PG8_MMA(ai, bj, At, Bt) do { __builtin_amdgcn_s_setprio(1); _Pragma("unroll") for (int m = 0; m < 4; ++m) _Pragma("unroll") for (int n = 0; n < 2; ++n) _Pragma("unroll") for (int k = 0; k < 2; ++k) \
;         acc[ai][bj][m][n] = __builtin_amdgcn_mfma_f32_16x16x32_bf16(Bt[n][k], At[m][k], acc[ai][bj][m][n], 0, 0, 0); __builtin_amdgcn_s_setprio(0); } while (0)
; #define PG8_WAIT_V(n) asm volatile("s_waitcnt vmcnt(" #n ")" ::: "memory")
; #define PG8_WAIT_L(n) asm volatile("s_waitcnt lgkmcnt(" #n ")" ::: "memory")
; #define PG8_BAR __builtin_amdgcn_s_barrier()
; #define PG8_SCHED __builtin_amdgcn_sched_barrier(0)
; template <class Epi, class Sched, bool ALIGN_EPI = false, bool SP2 = false>
; __device__ __forceinline__ void gemm_phase(PG8_LAS unsigned char* lds, const Gemm g, const Sched& S, const Epi& E) {
;     ...
;             PG8_LDA(At, 0, 1); PG8_STAGE(PG8_SB(0, 0), b2, voffB); PG8_STAGE(PG8_SB(0, 1), b2 + hstep, voffB); PG8_STAGE(PG8_SA(0, 0), a2, voffA);
;             PG8_WAIT_V(8); PG8_WAIT_L(0); PG8_BAR; PG8_MMA(1, 0, At, B0); PG8_MMA(1, 1, At, B1); PG8_BAR; PG8_SCHED;
;             PG8_LDB(B0, 1, 0); PG8_LDB(B1, 1, 1); PG8_SCHED; PG8_LDA(At, 1, 0); PG8_STAGE(PG8_SA(0, 1), a2 + hstep, voffA);
.Lpz5_a:
	s_add_u32 s42, s30, s40
	s_addc_u32 s43, s31, s41
	s_add_u32 s42, s42, 0x100
	s_addc_u32 s43, s43, 0
	s_add_u32 s84, s29, s40
	s_addc_u32 s85, s35, s41
	s_cmpk_eq_i32 s40, 0x700
	s_cselect_b32 s45, s23, s43
	s_cselect_b32 s44, s81, s42
	s_cselect_b32 s43, s21, s85
	s_cselect_b32 s42, s82, s84
	s_mov_b32 m0, s55
	v_lshl_add_u64 v[232:233], s[42:43], 0, v[174:175]
	s_add_u32 s84, s42, 0x40000
	ds_read_b128 v[130:133], v197 offset:16384
	ds_read_b128 v[134:137], v197 offset:17408
	ds_read_b128 v[200:203], v197 offset:18432
	ds_read_b128 v[204:207], v197 offset:19456
	ds_read_b128 v[208:211], v197 offset:20480
	ds_read_b128 v[212:215], v197 offset:21504
	ds_read_b128 v[216:219], v197 offset:22528
	ds_read_b128 v[220:223], v197 offset:23552
	global_load_lds_dwordx4 v[232:233], off
	v_lshl_add_u64 v[234:235], s[42:43], 0, v[170:171]
	s_mov_b32 m0, s56
	s_addc_u32 s85, s43, 0
	global_load_lds_dwordx4 v[234:235], off
	v_lshl_add_u64 v[224:225], s[84:85], 0, v[174:175]
	s_mov_b32 m0, s57
	v_lshl_add_u64 v[236:237], s[44:45], 0, v[176:177]
	global_load_lds_dwordx4 v[224:225], off
	v_lshl_add_u64 v[224:225], s[84:85], 0, v[170:171]
	s_mov_b32 m0, s58
	v_lshl_add_u64 v[238:239], s[44:45], 0, v[172:173]
	global_load_lds_dwordx4 v[224:225], off
	s_mov_b32 m0, s54
	s_nop 0
	global_load_lds_dwordx4 v[236:237], off
	s_mov_b32 m0, s59
	s_nop 0
	global_load_lds_dwordx4 v[238:239], off
	s_waitcnt vmcnt(8) lgkmcnt(0)
	s_barrier
	s_setprio 1
	v_mfma_f32_16x16x32_bf16 v[62:65], v[154:157], v[130:133], 0
	v_mfma_f32_16x16x32_bf16 v[58:61], v[162:165], v[130:133], 0
	v_mfma_f32_16x16x32_bf16 v[46:49], v[154:157], v[200:203], 0
	v_mfma_f32_16x16x32_bf16 v[42:45], v[162:165], v[200:203], 0
	v_mfma_f32_16x16x32_bf16 v[30:33], v[154:157], v[208:211], 0
	v_mfma_f32_16x16x32_bf16 v[26:29], v[162:165], v[208:211], 0
	v_mfma_f32_16x16x32_bf16 v[14:17], v[154:157], v[216:219], 0
	v_mfma_f32_16x16x32_bf16 v[10:13], v[162:165], v[216:219], 0
	v_mfma_f32_16x16x32_bf16 v[62:65], v[158:161], v[134:137], v[62:65]
	v_mfma_f32_16x16x32_bf16 v[58:61], v[166:169], v[134:137], v[58:61]
	v_mfma_f32_16x16x32_bf16 v[46:49], v[158:161], v[204:207], v[46:49]
	v_mfma_f32_16x16x32_bf16 v[42:45], v[166:169], v[204:207], v[42:45]
	v_mfma_f32_16x16x32_bf16 v[30:33], v[158:161], v[212:215], v[30:33]
	v_mfma_f32_16x16x32_bf16 v[26:29], v[166:169], v[212:215], v[26:29]
	v_mfma_f32_16x16x32_bf16 v[14:17], v[158:161], v[220:223], v[14:17]
	v_mfma_f32_16x16x32_bf16 v[10:13], v[166:169], v[220:223], v[10:13]
	v_mfma_f32_16x16x32_bf16 v[54:57], v[138:141], v[130:133], 0
	v_mfma_f32_16x16x32_bf16 v[50:53], v[146:149], v[130:133], 0
	v_mfma_f32_16x16x32_bf16 v[38:41], v[138:141], v[200:203], 0
	v_mfma_f32_16x16x32_bf16 v[34:37], v[146:149], v[200:203], 0
	v_mfma_f32_16x16x32_bf16 v[22:25], v[138:141], v[208:211], 0
	v_mfma_f32_16x16x32_bf16 v[18:21], v[146:149], v[208:211], 0
	v_mfma_f32_16x16x32_bf16 v[6:9], v[138:141], v[216:219], 0
	v_mfma_f32_16x16x32_bf16 v[2:5], v[146:149], v[216:219], 0
	v_mfma_f32_16x16x32_bf16 v[54:57], v[142:145], v[134:137], v[54:57]
	v_mfma_f32_16x16x32_bf16 v[50:53], v[150:153], v[134:137], v[50:53]
	v_mfma_f32_16x16x32_bf16 v[38:41], v[142:145], v[204:207], v[38:41]
	v_mfma_f32_16x16x32_bf16 v[34:37], v[150:153], v[204:207], v[34:37]
	v_mfma_f32_16x16x32_bf16 v[22:25], v[142:145], v[212:215], v[22:25]
	v_mfma_f32_16x16x32_bf16 v[18:21], v[150:153], v[212:215], v[18:21]
	v_mfma_f32_16x16x32_bf16 v[6:9], v[142:145], v[220:223], v[6:9]
	v_mfma_f32_16x16x32_bf16 v[2:5], v[150:153], v[220:223], v[2:5]
	s_barrier
	s_setprio 0
	s_branch .Lpz5_mid
.LBB0_985:
	s_add_u32 s42, s30, s40
	s_addc_u32 s43, s31, s41
	s_add_u32 s42, s42, 0x100
	s_addc_u32 s43, s43, 0
	s_add_u32 s84, s29, s40
	s_addc_u32 s85, s35, s41
	s_cmpk_eq_i32 s40, 0x700
	s_cselect_b32 s45, s23, s43
	s_cselect_b32 s44, s81, s42
	s_cselect_b32 s43, s21, s85
	s_cselect_b32 s42, s82, s84
	s_mov_b32 m0, s55
	v_lshl_add_u64 v[232:233], s[42:43], 0, v[174:175]
	s_add_u32 s84, s42, 0x40000
	ds_read_b128 v[130:133], v197 offset:16384
	ds_read_b128 v[134:137], v197 offset:17408
	ds_read_b128 v[200:203], v197 offset:18432
	ds_read_b128 v[204:207], v197 offset:19456
	ds_read_b128 v[208:211], v197 offset:20480
	ds_read_b128 v[212:215], v197 offset:21504
	ds_read_b128 v[216:219], v197 offset:22528
	ds_read_b128 v[220:223], v197 offset:23552
	global_load_lds_dwordx4 v[232:233], off
	v_lshl_add_u64 v[234:235], s[42:43], 0, v[170:171]
	s_mov_b32 m0, s56
	s_addc_u32 s85, s43, 0
	global_load_lds_dwordx4 v[234:235], off
	v_lshl_add_u64 v[224:225], s[84:85], 0, v[174:175]
	s_mov_b32 m0, s57
	v_lshl_add_u64 v[236:237], s[44:45], 0, v[176:177]
	global_load_lds_dwordx4 v[224:225], off
	v_lshl_add_u64 v[224:225], s[84:85], 0, v[170:171]
	s_mov_b32 m0, s58
	v_lshl_add_u64 v[238:239], s[44:45], 0, v[172:173]
	global_load_lds_dwordx4 v[224:225], off
	s_mov_b32 m0, s54
	s_nop 0
	global_load_lds_dwordx4 v[236:237], off
	s_mov_b32 m0, s59
	s_nop 0
	global_load_lds_dwordx4 v[238:239], off
	s_waitcnt vmcnt(8) lgkmcnt(0)
	s_barrier
; #define PG8_STAGE(bufoff, gbase, voff) do { _Pragma("unroll") for (int _i = 0; _i < 2; ++_i) \
;         __builtin_amdgcn_global_load_lds((const unsigned*)((const char*)(gbase) + (voff)[_i]), (PG8_LAS unsigned*)(lds + (bufoff) + ldsw + _i * 8192), 16, 0, 0); } while (0)
; #define PG8_LDA(dst, b, h) do { _Pragma("unroll") for (int m = 0; m < 4; ++m) _Pragma("unroll") for (int k = 0; k < 2; ++k) dst[m][k] = *(const PG8_LAS bf16x8*)(lds + PG8_SA(b, h) + aoff + m * 2048 + k * 1024); } while (0)
; #define PG8_LDB(dst, b, h) do { _Pragma("unroll") for (int n = 0; n < 2; ++n) _Pragma("unroll") for (int k = 0; k < 2; ++k) dst[n][k] = *(const PG8_LAS bf16x8*)(lds + PG8_SB(b, h) + boff + n * 2048 + k * 1024); } while (0)
; #define PG8_MMA(ai, bj, At, Bt) do { __builtin_amdgcn_s_setprio(1); _Pragma("unroll") for (int m = 0; m < 4; ++m) _Pragma("unroll") for (int n = 0; n < 2; ++n) _Pragma("unroll") for (int k = 0; k < 2; ++k) \
;         acc[ai][bj][m][n] = __builtin_amdgcn_mfma_f32_16x16x32_bf16(Bt[n][k], At[m][k], acc[ai][bj][m][n], 0, 0, 0); __builtin_amdgcn_s_setprio(0); } while (0)
; #define PG8_WAIT_V(n) asm volatile("s_waitcnt vmcnt(" #n ")" ::: "memory")
; #define PG8_WAIT_L(n) asm volatile("s_waitcnt lgkmcnt(" #n ")" ::: "memory")
; #define PG8_BAR __builtin_amdgcn_s_barrier()
; #define PG8_SCHED __builtin_amdgcn_sched_barrier(0)
; template <class Epi, class Sched, bool ALIGN_EPI = false, bool SP2 = false>
; __device__ __forceinline__ void gemm_phase(PG8_LAS unsigned char* lds, const Gemm g, const Sched& S, const Epi& E) {
;     ...
;             PG8_LDA(At, 0, 1); PG8_STAGE(PG8_SB(0, 0), b2, voffB); PG8_STAGE(PG8_SB(0, 1), b2 + hstep, voffB); PG8_STAGE(PG8_SA(0, 0), a2, voffA);
;             PG8_WAIT_V(8); PG8_WAIT_L(0); PG8_BAR; PG8_MMA(1, 0, At, B0); PG8_MMA(1, 1, At, B1); PG8_BAR; PG8_SCHED;
;             PG8_LDB(B0, 1, 0); PG8_LDB(B1, 1, 1); PG8_SCHED; PG8_LDA(At, 1, 0); PG8_STAGE(PG8_SA(0, 1), a2 + hstep, voffA);
;             PG8_WAIT_V(8); PG8_WAIT_L(0); PG8_BAR; PG8_MMA(0, 0, At, B0); PG8_MMA(0, 1, At, B1); PG8_BAR; PG8_SCHED;
	s_setprio 1
	v_mfma_f32_16x16x32_bf16 v[62:65], v[154:157], v[130:133], v[62:65]
	v_mfma_f32_16x16x32_bf16 v[58:61], v[162:165], v[130:133], v[58:61]
	v_mfma_f32_16x16x32_bf16 v[46:49], v[154:157], v[200:203], v[46:49]
	v_mfma_f32_16x16x32_bf16 v[42:45], v[162:165], v[200:203], v[42:45]
	v_mfma_f32_16x16x32_bf16 v[30:33], v[154:157], v[208:211], v[30:33]
	v_mfma_f32_16x16x32_bf16 v[26:29], v[162:165], v[208:211], v[26:29]
	v_mfma_f32_16x16x32_bf16 v[14:17], v[154:157], v[216:219], v[14:17]
	v_mfma_f32_16x16x32_bf16 v[10:13], v[162:165], v[216:219], v[10:13]
	v_mfma_f32_16x16x32_bf16 v[62:65], v[158:161], v[134:137], v[62:65]
	v_mfma_f32_16x16x32_bf16 v[58:61], v[166:169], v[134:137], v[58:61]
	v_mfma_f32_16x16x32_bf16 v[46:49], v[158:161], v[204:207], v[46:49]
	v_mfma_f32_16x16x32_bf16 v[42:45], v[166:169], v[204:207], v[42:45]
	v_mfma_f32_16x16x32_bf16 v[30:33], v[158:161], v[212:215], v[30:33]
	v_mfma_f32_16x16x32_bf16 v[26:29], v[166:169], v[212:215], v[26:29]
	v_mfma_f32_16x16x32_bf16 v[14:17], v[158:161], v[220:223], v[14:17]
	v_mfma_f32_16x16x32_bf16 v[10:13], v[166:169], v[220:223], v[10:13]
	v_mfma_f32_16x16x32_bf16 v[54:57], v[138:141], v[130:133], v[54:57]
	v_mfma_f32_16x16x32_bf16 v[50:53], v[146:149], v[130:133], v[50:53]
	v_mfma_f32_16x16x32_bf16 v[38:41], v[138:141], v[200:203], v[38:41]
	v_mfma_f32_16x16x32_bf16 v[34:37], v[146:149], v[200:203], v[34:37]
	v_mfma_f32_16x16x32_bf16 v[22:25], v[138:141], v[208:211], v[22:25]
	v_mfma_f32_16x16x32_bf16 v[18:21], v[146:149], v[208:211], v[18:21]
	v_mfma_f32_16x16x32_bf16 v[6:9], v[138:141], v[216:219], v[6:9]
	v_mfma_f32_16x16x32_bf16 v[2:5], v[146:149], v[216:219], v[2:5]
	v_mfma_f32_16x16x32_bf16 v[54:57], v[142:145], v[134:137], v[54:57]
	v_mfma_f32_16x16x32_bf16 v[50:53], v[150:153], v[134:137], v[50:53]
	v_mfma_f32_16x16x32_bf16 v[38:41], v[142:145], v[204:207], v[38:41]
	v_mfma_f32_16x16x32_bf16 v[34:37], v[150:153], v[204:207], v[34:37]
	v_mfma_f32_16x16x32_bf16 v[22:25], v[142:145], v[212:215], v[22:25]
	v_mfma_f32_16x16x32_bf16 v[18:21], v[150:153], v[212:215], v[18:21]
	v_mfma_f32_16x16x32_bf16 v[6:9], v[142:145], v[220:223], v[6:9]
	v_mfma_f32_16x16x32_bf16 v[2:5], v[150:153], v[220:223], v[2:5]
	s_barrier
	s_setprio 0
.Lpz5_mid:
	s_add_i32 s84, 0, 0x18000
	v_add_u32_e32 v130, s84, v193
	s_add_i32 s85, 0, 0x1c000
	ds_read_b128 v[138:141], v130
	ds_read_b128 v[142:145], v130 offset:1024
	ds_read_b128 v[146:149], v130 offset:2048
	ds_read_b128 v[150:153], v130 offset:3072
	v_add_u32_e32 v130, s85, v193
	ds_read_b128 v[154:157], v130
	ds_read_b128 v[158:161], v130 offset:1024
	ds_read_b128 v[162:165], v130 offset:2048
	ds_read_b128 v[166:169], v130 offset:3072
	s_add_u32 s44, s44, 0x40000
	s_addc_u32 s45, s45, 0
	s_mov_b32 m0, s60
	v_lshl_add_u64 v[130:131], s[44:45], 0, v[176:177]
	ds_read_b128 v[200:203], v197 offset:32768
	ds_read_b128 v[204:207], v197 offset:33792
	ds_read_b128 v[208:211], v197 offset:34816
	ds_read_b128 v[212:215], v197 offset:35840
	ds_read_b128 v[216:219], v197 offset:36864
	ds_read_b128 v[220:223], v197 offset:37888
	ds_read_b128 v[224:227], v197 offset:38912
	ds_read_b128 v[228:231], v197 offset:39936
	global_load_lds_dwordx4 v[130:131], off
	v_lshl_add_u64 v[130:131], s[44:45], 0, v[172:173]
	s_mov_b32 m0, s61
	s_nop 0
	global_load_lds_dwordx4 v[130:131], off
	s_waitcnt vmcnt(8) lgkmcnt(0)
	s_barrier
	s_setprio 1
	v_mfma_f32_16x16x32_bf16 v[98:101], v[138:141], v[200:203], v[98:101]
	v_mfma_f32_16x16x32_bf16 v[134:137], v[142:145], v[204:207], v[98:101]
	v_mfma_f32_16x16x32_bf16 v[98:101], v[146:149], v[200:203], v[106:109]
	v_mfma_f32_16x16x32_bf16 v[130:133], v[150:153], v[204:207], v[98:101]
	v_mfma_f32_16x16x32_bf16 v[98:101], v[138:141], v[208:211], v[118:121]
	v_mfma_f32_16x16x32_bf16 v[118:121], v[142:145], v[212:215], v[98:101]
	v_mfma_f32_16x16x32_bf16 v[98:101], v[146:149], v[208:211], v[114:117]
	v_mfma_f32_16x16x32_bf16 v[94:97], v[138:141], v[216:219], v[94:97]
	v_mfma_f32_16x16x32_bf16 v[90:93], v[146:149], v[216:219], v[90:93]
	v_mfma_f32_16x16x32_bf16 v[78:81], v[138:141], v[224:227], v[78:81]
	v_mfma_f32_16x16x32_bf16 v[74:77], v[146:149], v[224:227], v[74:77]
	v_mfma_f32_16x16x32_bf16 v[114:117], v[150:153], v[212:215], v[98:101]
	v_mfma_f32_16x16x32_bf16 v[94:97], v[142:145], v[220:223], v[94:97]
	v_mfma_f32_16x16x32_bf16 v[90:93], v[150:153], v[220:223], v[90:93]
	v_mfma_f32_16x16x32_bf16 v[78:81], v[142:145], v[228:231], v[78:81]
	v_mfma_f32_16x16x32_bf16 v[74:77], v[150:153], v[228:231], v[74:77]
	v_mfma_f32_16x16x32_bf16 v[98:101], v[154:157], v[200:203], v[126:129]
	v_mfma_f32_16x16x32_bf16 v[126:129], v[158:161], v[204:207], v[98:101]
	v_mfma_f32_16x16x32_bf16 v[98:101], v[162:165], v[200:203], v[122:125]
	v_mfma_f32_16x16x32_bf16 v[122:125], v[166:169], v[204:207], v[98:101]
	v_mfma_f32_16x16x32_bf16 v[98:101], v[154:157], v[208:211], v[110:113]
	v_mfma_f32_16x16x32_bf16 v[110:113], v[158:161], v[212:215], v[98:101]
	v_mfma_f32_16x16x32_bf16 v[98:101], v[162:165], v[208:211], v[102:105]
	v_mfma_f32_16x16x32_bf16 v[86:89], v[154:157], v[216:219], v[86:89]
	v_mfma_f32_16x16x32_bf16 v[82:85], v[162:165], v[216:219], v[82:85]
	v_mfma_f32_16x16x32_bf16 v[70:73], v[154:157], v[224:227], v[70:73]
	v_mfma_f32_16x16x32_bf16 v[66:69], v[162:165], v[224:227], v[66:69]
	v_mfma_f32_16x16x32_bf16 v[102:105], v[166:169], v[212:215], v[98:101]
	v_mfma_f32_16x16x32_bf16 v[86:89], v[158:161], v[220:223], v[86:89]
	v_mfma_f32_16x16x32_bf16 v[82:85], v[166:169], v[220:223], v[82:85]
	v_mfma_f32_16x16x32_bf16 v[70:73], v[158:161], v[228:231], v[70:73]
	v_mfma_f32_16x16x32_bf16 v[66:69], v[166:169], v[228:231], v[66:69]
	s_barrier
; #define PG8_STAGE(bufoff, gbase, voff) do { _Pragma("unroll") for (int _i = 0; _i < 2; ++_i) \
;         __builtin_amdgcn_global_load_lds((const unsigned*)((const char*)(gbase) + (voff)[_i]), (PG8_LAS unsigned*)(lds + (bufoff) + ldsw + _i * 8192), 16, 0, 0); } while (0)
; #define PG8_LDA(dst, b, h) do { _Pragma("unroll") for (int m = 0; m < 4; ++m) _Pragma("unroll") for (int k = 0; k < 2; ++k) dst[m][k] = *(const PG8_LAS bf16x8*)(lds + PG8_SA(b, h) + aoff + m * 2048 + k * 1024); } while (0)
; #define PG8_MMA(ai, bj, At, Bt) do { __builtin_amdgcn_s_setprio(1); _Pragma("unroll") for (int m = 0; m < 4; ++m) _Pragma("unroll") for (int n = 0; n < 2; ++n) _Pragma("unroll") for (int k = 0; k < 2; ++k) \
;         acc[ai][bj][m][n] = __builtin_amdgcn_mfma_f32_16x16x32_bf16(Bt[n][k], At[m][k], acc[ai][bj][m][n], 0, 0, 0); __builtin_amdgcn_s_setprio(0); } while (0)
; #define PG8_WAIT_V(n) asm volatile("s_waitcnt vmcnt(" #n ")" ::: "memory")
; #define PG8_WAIT_L(n) asm volatile("s_waitcnt lgkmcnt(" #n ")" ::: "memory")
; #define PG8_BAR __builtin_amdgcn_s_barrier()
; #define PG8_SCHED __builtin_amdgcn_sched_barrier(0)
; template <class Epi, class Sched, bool ALIGN_EPI = false, bool SP2 = false>
; __device__ __forceinline__ void gemm_phase(PG8_LAS unsigned char* lds, const Gemm g, const Sched& S, const Epi& E) {
;     ...
;         for (int t = 0; t < nt; t += 2) {
;             const bool last = (t == nt - 2);
;             const char* a1 = cA + (size_t)(t + 1) * kstepA;
;             const char* a2 = last ? nA : cA + (size_t)(t + 2) * kstepA; const char* b2 = last ? nB : cB + (size_t)(t + 2) * kstep;
;     ...
;             PG8_LDA(At, 1, 1); PG8_STAGE(PG8_SB(1, 0), b3, voffB); PG8_STAGE(PG8_SB(1, 1), b3 + hstep, voffB); PG8_STAGE(PG8_SA(1, 0), a3, voffA);
;             PG8_WAIT_V(8); PG8_WAIT_L(0); PG8_BAR; PG8_MMA(1, 0, At, B0); PG8_MMA(1, 1, At, B1); PG8_BAR; PG8_SCHED;
	s_setprio 0
	s_add_i32 s44, s84, s51
	v_lshl_add_u64 v[224:225], v[232:233], 0, s[8:9]
	s_mov_b32 m0, s44
	ds_read_b128 v[98:101], v197 offset:49152
	ds_read_b128 v[106:109], v197 offset:50176
	ds_read_b128 v[200:203], v197 offset:51200
	ds_read_b128 v[204:207], v197 offset:52224
	ds_read_b128 v[208:211], v197 offset:53248
	ds_read_b128 v[212:215], v197 offset:54272
	ds_read_b128 v[216:219], v197 offset:55296
	ds_read_b128 v[220:223], v197 offset:56320
	global_load_lds_dwordx4 v[224:225], off
	s_add_i32 m0, s44, 0x2000
	s_add_u32 s42, s42, 0x40080
	v_lshl_add_u64 v[224:225], v[234:235], 0, s[8:9]
	s_addc_u32 s43, s43, 0
	s_add_i32 s44, s85, s51
	global_load_lds_dwordx4 v[224:225], off
	v_lshl_add_u64 v[224:225], s[42:43], 0, v[174:175]
	s_mov_b32 m0, s44
	s_nop 0
	global_load_lds_dwordx4 v[224:225], off
	v_lshl_add_u64 v[224:225], s[42:43], 0, v[170:171]
	s_add_i32 m0, s44, 0x2000
	s_nop 0
	global_load_lds_dwordx4 v[224:225], off
	v_lshl_add_u64 v[224:225], v[236:237], 0, s[8:9]
	s_mov_b32 m0, s65
	s_nop 0
	global_load_lds_dwordx4 v[224:225], off
	v_lshl_add_u64 v[224:225], v[238:239], 0, s[8:9]
	s_mov_b32 m0, s66
	s_nop 0
	global_load_lds_dwordx4 v[224:225], off
	s_waitcnt vmcnt(8) lgkmcnt(0)
	s_barrier
	s_setprio 1
	v_mfma_f32_16x16x32_bf16 v[62:65], v[138:141], v[98:101], v[62:65]
	v_mfma_f32_16x16x32_bf16 v[58:61], v[146:149], v[98:101], v[58:61]
	v_mfma_f32_16x16x32_bf16 v[46:49], v[138:141], v[200:203], v[46:49]
	v_mfma_f32_16x16x32_bf16 v[42:45], v[146:149], v[200:203], v[42:45]
	v_mfma_f32_16x16x32_bf16 v[30:33], v[138:141], v[208:211], v[30:33]
	v_mfma_f32_16x16x32_bf16 v[26:29], v[146:149], v[208:211], v[26:29]
	v_mfma_f32_16x16x32_bf16 v[14:17], v[138:141], v[216:219], v[14:17]
	v_mfma_f32_16x16x32_bf16 v[10:13], v[146:149], v[216:219], v[10:13]
	v_mfma_f32_16x16x32_bf16 v[62:65], v[142:145], v[106:109], v[62:65]
	v_mfma_f32_16x16x32_bf16 v[58:61], v[150:153], v[106:109], v[58:61]
	v_mfma_f32_16x16x32_bf16 v[46:49], v[142:145], v[204:207], v[46:49]
	v_mfma_f32_16x16x32_bf16 v[42:45], v[150:153], v[204:207], v[42:45]
	v_mfma_f32_16x16x32_bf16 v[30:33], v[142:145], v[212:215], v[30:33]
	v_mfma_f32_16x16x32_bf16 v[26:29], v[150:153], v[212:215], v[26:29]
	v_mfma_f32_16x16x32_bf16 v[14:17], v[142:145], v[220:223], v[14:17]
	v_mfma_f32_16x16x32_bf16 v[10:13], v[150:153], v[220:223], v[10:13]
	v_mfma_f32_16x16x32_bf16 v[54:57], v[154:157], v[98:101], v[54:57]
	v_mfma_f32_16x16x32_bf16 v[50:53], v[162:165], v[98:101], v[50:53]
	v_mfma_f32_16x16x32_bf16 v[38:41], v[154:157], v[200:203], v[38:41]
	v_mfma_f32_16x16x32_bf16 v[34:37], v[162:165], v[200:203], v[34:37]
	v_mfma_f32_16x16x32_bf16 v[22:25], v[154:157], v[208:211], v[22:25]
	v_mfma_f32_16x16x32_bf16 v[18:21], v[162:165], v[208:211], v[18:21]
	v_mfma_f32_16x16x32_bf16 v[6:9], v[154:157], v[216:219], v[6:9]
	v_mfma_f32_16x16x32_bf16 v[2:5], v[162:165], v[216:219], v[2:5]
	v_mfma_f32_16x16x32_bf16 v[54:57], v[158:161], v[106:109], v[54:57]
	v_mfma_f32_16x16x32_bf16 v[50:53], v[166:169], v[106:109], v[50:53]
	v_mfma_f32_16x16x32_bf16 v[38:41], v[158:161], v[204:207], v[38:41]
	v_mfma_f32_16x16x32_bf16 v[34:37], v[166:169], v[204:207], v[34:37]
	v_mfma_f32_16x16x32_bf16 v[22:25], v[158:161], v[212:215], v[22:25]
	v_mfma_f32_16x16x32_bf16 v[18:21], v[166:169], v[212:215], v[18:21]
	v_mfma_f32_16x16x32_bf16 v[6:9], v[158:161], v[220:223], v[6:9]
	v_mfma_f32_16x16x32_bf16 v[2:5], v[166:169], v[220:223], v[2:5]
	s_barrier
	s_setprio 0
	s_add_i32 s42, s83, 2
	s_add_u32 s40, s40, 0x100
	s_addc_u32 s41, s41, 0
	s_cmp_gt_u32 s83, 13
	s_mov_b32 s83, s42
	s_cbranch_scc1 .LBB0_989
; #define PG8_LAS __attribute__((address_space(3)))
; #define PG8_STAGE(bufoff, gbase, voff) do { _Pragma("unroll") for (int _i = 0; _i < 2; ++_i) \
;         __builtin_amdgcn_global_load_lds((const unsigned*)((const char*)(gbase) + (voff)[_i]), (PG8_LAS unsigned*)(lds + (bufoff) + ldsw + _i * 8192), 16, 0, 0); } while (0)
; #define PG8_LDA(dst, b, h) do { _Pragma("unroll") for (int m = 0; m < 4; ++m) _Pragma("unroll") for (int k = 0; k < 2; ++k) dst[m][k] = *(const PG8_LAS bf16x8*)(lds + PG8_SA(b, h) + aoff + m * 2048 + k * 1024); } while (0)
; #define PG8_LDB(dst, b, h) do { _Pragma("unroll") for (int n = 0; n < 2; ++n) _Pragma("unroll") for (int k = 0; k < 2; ++k) dst[n][k] = *(const PG8_LAS bf16x8*)(lds + PG8_SB(b, h) + boff + n * 2048 + k * 1024); } while (0)
; #define PG8_MMA(ai, bj, At, Bt) do { __builtin_amdgcn_s_setprio(1); _Pragma("unroll") for (int m = 0; m < 4; ++m) _Pragma("unroll") for (int n = 0; n < 2; ++n) _Pragma("unroll") for (int k = 0; k < 2; ++k) \
;         acc[ai][bj][m][n] = __builtin_amdgcn_mfma_f32_16x16x32_bf16(Bt[n][k], At[m][k], acc[ai][bj][m][n], 0, 0, 0); __builtin_amdgcn_s_setprio(0); } while (0)
; #define PG8_WAIT_V(n) asm volatile("s_waitcnt vmcnt(" #n ")" ::: "memory")
; template <class Epi, class Sched, bool ALIGN_EPI = false, bool SP2 = false>
; __device__ __forceinline__ void gemm_phase(PG8_LAS unsigned char* lds, const Gemm g, const Sched& S, const Epi& E) {
;     ...
;             PG8_LDB(B0, 0, 0); PG8_LDB(B1, 0, 1); PG8_SCHED; PG8_LDA(At, 0, 0); PG8_STAGE(PG8_SA(1, 1), a1 + hstep, voffA);
;             PG8_WAIT_V(8); PG8_WAIT_L(0); PG8_BAR; PG8_MMA(0, 0, At, B0); PG8_MMA(0, 1, At, B1); PG8_BAR; PG8_SCHED;
;             if constexpr (Epi::PREFETCH) { if (t == tpf) E.prefetch(cur, wid, lane); }
; __device__ __forceinline__ void epi_prefetch(PG8_LAS unsigned char* scr, const float* ssq, const float* bias_tile, const Unit& u, int wid, int lane) {
;     unsigned lo = (unsigned)lane * 16u; asm volatile("" : "+v"(lo));
;     const char* src = (const char*)(ssq + (size_t)u.pm * BM * 16 + wid * 512);
; #pragma unroll
;     for (int j = 0; j < 2; ++j) __builtin_amdgcn_global_load_lds((const unsigned*)(src + j * 1024 + lo), (PG8_LAS unsigned*)(scr + (wid * 2 + j) * 1024), 16, 0, 0);
;     if (wid == 0) __builtin_amdgcn_global_load_lds((const unsigned*)((const char*)bias_tile + lo), (PG8_LAS unsigned*)(scr + 16384), 16, 0, 0);
; }
.LBB0_986:
	ds_read_b128 v[154:157], v195
	ds_read_b128 v[158:161], v195 offset:1024
	ds_read_b128 v[162:165], v195 offset:2048
	ds_read_b128 v[166:169], v195 offset:3072
	ds_read_b128 v[138:141], v196
	ds_read_b128 v[142:145], v196 offset:1024
	ds_read_b128 v[146:149], v196 offset:2048
	ds_read_b128 v[150:153], v196 offset:3072
	v_lshl_add_u64 v[98:99], v[188:189], 0, s[40:41]
	s_add_i32 m0, s54, 0xc000
	ds_read_b128 v[200:203], v197
	ds_read_b128 v[204:207], v197 offset:1024
	ds_read_b128 v[208:211], v197 offset:2048
	ds_read_b128 v[212:215], v197 offset:3072
	ds_read_b128 v[216:219], v197 offset:4096
	ds_read_b128 v[220:223], v197 offset:5120
	ds_read_b128 v[224:227], v197 offset:6144
	ds_read_b128 v[228:231], v197 offset:7168
	global_load_lds_dwordx4 v[98:99], off
	v_lshl_add_u64 v[98:99], v[190:191], 0, s[40:41]
	s_add_i32 m0, s54, 0xe000
	s_nop 0
	global_load_lds_dwordx4 v[98:99], off
	s_waitcnt vmcnt(8) lgkmcnt(0)
	s_barrier
	s_setprio 1
	v_mfma_f32_16x16x32_bf16 v[98:101], v[154:157], v[200:203], v[134:137]
	v_mfma_f32_16x16x32_bf16 v[106:109], v[162:165], v[200:203], v[130:133]
	v_mfma_f32_16x16x32_bf16 v[118:121], v[154:157], v[208:211], v[118:121]
	v_mfma_f32_16x16x32_bf16 v[114:117], v[162:165], v[208:211], v[114:117]
	v_mfma_f32_16x16x32_bf16 v[94:97], v[154:157], v[216:219], v[94:97]
	v_mfma_f32_16x16x32_bf16 v[90:93], v[162:165], v[216:219], v[90:93]
	v_mfma_f32_16x16x32_bf16 v[78:81], v[154:157], v[224:227], v[78:81]
	v_mfma_f32_16x16x32_bf16 v[74:77], v[162:165], v[224:227], v[74:77]
	v_mfma_f32_16x16x32_bf16 v[98:101], v[158:161], v[204:207], v[98:101]
	v_mfma_f32_16x16x32_bf16 v[106:109], v[166:169], v[204:207], v[106:109]
	v_mfma_f32_16x16x32_bf16 v[118:121], v[158:161], v[212:215], v[118:121]
	v_mfma_f32_16x16x32_bf16 v[114:117], v[166:169], v[212:215], v[114:117]
	v_mfma_f32_16x16x32_bf16 v[94:97], v[158:161], v[220:223], v[94:97]
	v_mfma_f32_16x16x32_bf16 v[90:93], v[166:169], v[220:223], v[90:93]
	v_mfma_f32_16x16x32_bf16 v[78:81], v[158:161], v[228:231], v[78:81]
	v_mfma_f32_16x16x32_bf16 v[74:77], v[166:169], v[228:231], v[74:77]
	v_mfma_f32_16x16x32_bf16 v[126:129], v[138:141], v[200:203], v[126:129]
	v_mfma_f32_16x16x32_bf16 v[122:125], v[146:149], v[200:203], v[122:125]
	v_mfma_f32_16x16x32_bf16 v[110:113], v[138:141], v[208:211], v[110:113]
	v_mfma_f32_16x16x32_bf16 v[102:105], v[146:149], v[208:211], v[102:105]
	v_mfma_f32_16x16x32_bf16 v[86:89], v[138:141], v[216:219], v[86:89]
	v_mfma_f32_16x16x32_bf16 v[82:85], v[146:149], v[216:219], v[82:85]
	v_mfma_f32_16x16x32_bf16 v[70:73], v[138:141], v[224:227], v[70:73]
	v_mfma_f32_16x16x32_bf16 v[66:69], v[146:149], v[224:227], v[66:69]
	v_mfma_f32_16x16x32_bf16 v[126:129], v[142:145], v[204:207], v[126:129]
	v_mfma_f32_16x16x32_bf16 v[122:125], v[150:153], v[204:207], v[122:125]
	v_mfma_f32_16x16x32_bf16 v[110:113], v[142:145], v[212:215], v[110:113]
	v_mfma_f32_16x16x32_bf16 v[102:105], v[150:153], v[212:215], v[102:105]
	v_mfma_f32_16x16x32_bf16 v[86:89], v[142:145], v[220:223], v[86:89]
	v_mfma_f32_16x16x32_bf16 v[82:85], v[150:153], v[220:223], v[82:85]
	v_mfma_f32_16x16x32_bf16 v[70:73], v[142:145], v[228:231], v[70:73]
	v_mfma_f32_16x16x32_bf16 v[66:69], v[150:153], v[228:231], v[66:69]
	s_barrier
	s_setprio 0
	s_cmp_lg_u32 s46, s83
	s_cbranch_scc1 .LBB0_985
	v_mov_b32_e32 v178, v194
	s_add_i32 m0, s79, 0x20000
	v_lshl_add_u64 v[130:131], s[36:37], 0, v[178:179]
	global_load_lds_dwordx4 v178, s[36:37]
	v_lshl_add_u64 v[130:131], v[130:131], 0, s[18:19]
	s_add_i32 m0, s79, 0x20400
	s_andn2_b64 vcc, exec, s[14:15]
	global_load_lds_dwordx4 v[130:131], off
	s_cbranch_vccnz .LBB0_985
	v_lshl_add_u64 v[130:131], s[38:39], 0, v[178:179]
	s_add_i32 m0, 0, 0x24000
	s_nop 0
	global_load_lds_dwordx4 v[130:131], off
	s_branch .LBB0_985

; #define PG8_STAGE(bufoff, gbase, voff) do { _Pragma("unroll") for (int _i = 0; _i < 2; ++_i) \
;         __builtin_amdgcn_global_load_lds((const unsigned*)((const char*)(gbase) + (voff)[_i]), (PG8_LAS unsigned*)(lds + (bufoff) + ldsw + _i * 8192), 16, 0, 0); } while (0)
; #define PG8_LDA(dst, b, h) do { _Pragma("unroll") for (int m = 0; m < 4; ++m) _Pragma("unroll") for (int k = 0; k < 2; ++k) dst[m][k] = *(const PG8_LAS bf16x8*)(lds + PG8_SA(b, h) + aoff + m * 2048 + k * 1024); } while (0)
; #define PG8_LDB(dst, b, h) do { _Pragma("unroll") for (int n = 0; n < 2; ++n) _Pragma("unroll") for (int k = 0; k < 2; ++k) dst[n][k] = *(const PG8_LAS bf16x8*)(lds + PG8_SB(b, h) + boff + n * 2048 + k * 1024); } while (0)
; #define PG8_MMA(ai, bj, At, Bt) do { __builtin_amdgcn_s_setprio(1); _Pragma("unroll") for (int m = 0; m < 4; ++m) _Pragma("unroll") for (int n = 0; n < 2; ++n) _Pragma("unroll") for (int k = 0; k < 2; ++k) \
;         acc[ai][bj][m][n] = __builtin_amdgcn_mfma_f32_16x16x32_bf16(Bt[n][k], At[m][k], acc[ai][bj][m][n], 0, 0, 0); __builtin_amdgcn_s_setprio(0); } while (0)
; #define PG8_BAR __builtin_amdgcn_s_barrier()
; template <class Epi, class Sched, bool ALIGN_EPI = false, bool SP2 = false>
; __device__ __forceinline__ void gemm_phase(PG8_LAS unsigned char* lds, const Gemm g, const Sched& S, const Epi& E) {
;     ...
;         for (int t = 0; t < nt; t += 2) {
;             const bool last = (t == nt - 2);
;             const char* a1 = cA + (size_t)(t + 1) * kstepA;
;             const char* a2 = last ? nA : cA + (size_t)(t + 2) * kstepA; const char* b2 = last ? nB : cB + (size_t)(t + 2) * kstep;
;             const char* a3 = a2 + kstepA; const char* b3 = b2 + kstep;
;             if (last && has_next) S.a_ready(nxt);
;             if constexpr (SP2) {
;             PG8_LDB(B0, 0, 0); PG8_LDB(B1, 0, 1); PG8_SCHED; PG8_LDA(At, 0, 0); PG8_STAGE(PG8_SA(1, 1), a1 + hstep, voffA);
;             PG8_WAIT_V(8); PG8_WAIT_L(0); PG8_BAR; PG8_MMA(0, 0, At, B0); PG8_MMA(0, 1, At, B1); PG8_BAR; PG8_SCHED;
;             if constexpr (Epi::PREFETCH) { if (t == tpf) E.prefetch(cur, wid, lane); }
;             PG8_LDA(At, 0, 1); PG8_STAGE(PG8_SB(0, 0), b2, voffB); PG8_STAGE(PG8_SB(0, 1), b2 + hstep, voffB); PG8_STAGE(PG8_SA(0, 0), a2, voffA);
;             PG8_WAIT_V(8); PG8_WAIT_L(0); PG8_BAR; PG8_MMA(1, 0, At, B0); PG8_MMA(1, 1, At, B1); PG8_BAR; PG8_SCHED;
.LBB0_1068:
	s_add_u32 s35, s6, 0x100
	s_addc_u32 s36, s7, 0
	s_mov_b32 s37, -2
	s_waitcnt lgkmcnt(0)
	ds_read_b128 v[130:133], v192
	ds_read_b128 v[134:137], v192 offset:1024
	ds_read_b128 v[156:159], v192 offset:2048
	ds_read_b128 v[160:163], v192 offset:3072
	ds_read_b128 v[164:167], v193
	ds_read_b128 v[168:171], v193 offset:1024
	ds_read_b128 v[172:175], v193 offset:2048
	ds_read_b128 v[176:179], v193 offset:3072
	s_add_u32 s0, s4, 0x200
	s_addc_u32 s1, s5, 0
	s_cmp_eq_u32 s37, 40
	s_cselect_b32 s31, s27, s1
	s_cselect_b32 s30, s26, s0
	s_cselect_b32 s7, s29, s36
	s_cselect_b32 s6, s28, s35
	v_lshl_add_u64 v[188:189], s[4:5], 0, v[148:149]
	s_add_i32 m0, s45, 0xc000
	ds_read_b128 v[180:183], v194
	ds_read_b128 v[184:187], v194 offset:1024
	ds_read_b128 v[196:199], v194 offset:2048
	ds_read_b128 v[200:203], v194 offset:3072
	ds_read_b128 v[204:207], v194 offset:4096
	ds_read_b128 v[208:211], v194 offset:5120
	ds_read_b128 v[212:215], v194 offset:6144
	ds_read_b128 v[216:219], v194 offset:7168
	global_load_lds_dwordx4 v[188:189], off
	v_lshl_add_u64 v[188:189], s[4:5], 0, v[150:151]
	s_add_i32 m0, s45, 0xe000
	s_nop 0
	global_load_lds_dwordx4 v[188:189], off
	s_waitcnt vmcnt(8) lgkmcnt(0)
	s_barrier
	s_setprio 1
	v_mfma_f32_16x16x32_bf16 v[126:129], v[130:133], v[180:183], 0
	v_mfma_f32_16x16x32_bf16 v[122:125], v[156:159], v[180:183], 0
	v_mfma_f32_16x16x32_bf16 v[110:113], v[130:133], v[196:199], 0
	v_mfma_f32_16x16x32_bf16 v[106:109], v[156:159], v[196:199], 0
	v_mfma_f32_16x16x32_bf16 v[94:97], v[130:133], v[204:207], 0
	v_mfma_f32_16x16x32_bf16 v[90:93], v[156:159], v[204:207], 0
	v_mfma_f32_16x16x32_bf16 v[78:81], v[130:133], v[212:215], 0
	v_mfma_f32_16x16x32_bf16 v[74:77], v[156:159], v[212:215], 0
	v_mfma_f32_16x16x32_bf16 v[126:129], v[134:137], v[184:187], v[126:129]
	v_mfma_f32_16x16x32_bf16 v[122:125], v[160:163], v[184:187], v[122:125]
	v_mfma_f32_16x16x32_bf16 v[110:113], v[134:137], v[200:203], v[110:113]
	v_mfma_f32_16x16x32_bf16 v[106:109], v[160:163], v[200:203], v[106:109]
	v_mfma_f32_16x16x32_bf16 v[94:97], v[134:137], v[208:211], v[94:97]
	v_mfma_f32_16x16x32_bf16 v[90:93], v[160:163], v[208:211], v[90:93]
	v_mfma_f32_16x16x32_bf16 v[78:81], v[134:137], v[216:219], v[78:81]
	v_mfma_f32_16x16x32_bf16 v[74:77], v[160:163], v[216:219], v[74:77]
	v_mfma_f32_16x16x32_bf16 v[118:121], v[164:167], v[180:183], 0
	v_mfma_f32_16x16x32_bf16 v[114:117], v[172:175], v[180:183], 0
	v_mfma_f32_16x16x32_bf16 v[102:105], v[164:167], v[196:199], 0
	v_mfma_f32_16x16x32_bf16 v[98:101], v[172:175], v[196:199], 0
	v_mfma_f32_16x16x32_bf16 v[86:89], v[164:167], v[204:207], 0
	v_mfma_f32_16x16x32_bf16 v[82:85], v[172:175], v[204:207], 0
	v_mfma_f32_16x16x32_bf16 v[70:73], v[164:167], v[212:215], 0
	v_mfma_f32_16x16x32_bf16 v[66:69], v[172:175], v[212:215], 0
	v_mfma_f32_16x16x32_bf16 v[118:121], v[168:171], v[184:187], v[118:121]
	v_mfma_f32_16x16x32_bf16 v[114:117], v[176:179], v[184:187], v[114:117]
	v_mfma_f32_16x16x32_bf16 v[102:105], v[168:171], v[200:203], v[102:105]
	v_mfma_f32_16x16x32_bf16 v[98:101], v[176:179], v[200:203], v[98:101]
	v_mfma_f32_16x16x32_bf16 v[86:89], v[168:171], v[208:211], v[86:89]
	v_mfma_f32_16x16x32_bf16 v[82:85], v[176:179], v[208:211], v[82:85]
	v_mfma_f32_16x16x32_bf16 v[70:73], v[168:171], v[216:219], v[70:73]
	v_mfma_f32_16x16x32_bf16 v[66:69], v[176:179], v[216:219], v[66:69]
	s_barrier
	s_setprio 0
	s_add_i32 s4, s61, s44
	v_lshl_add_u64 v[188:189], s[6:7], 0, v[140:141]
	s_mov_b32 m0, s4
	ds_read_b128 v[180:183], v194 offset:16384
	ds_read_b128 v[184:187], v194 offset:17408
	ds_read_b128 v[196:199], v194 offset:18432
	ds_read_b128 v[200:203], v194 offset:19456
	ds_read_b128 v[204:207], v194 offset:20480
	ds_read_b128 v[208:211], v194 offset:21504
	ds_read_b128 v[212:215], v194 offset:22528
	ds_read_b128 v[216:219], v194 offset:23552
	global_load_lds_dwordx4 v[188:189], off
	s_add_i32 m0, s4, 0x2000
	s_add_u32 s4, s6, 0xb0000
	v_lshl_add_u64 v[220:221], s[6:7], 0, v[144:145]
	s_addc_u32 s5, s7, 0
	s_add_i32 s38, s62, s44
	global_load_lds_dwordx4 v[220:221], off
	v_lshl_add_u64 v[222:223], s[4:5], 0, v[140:141]
	s_mov_b32 m0, s38
	v_lshl_add_u64 v[224:225], s[30:31], 0, v[142:143]
	global_load_lds_dwordx4 v[222:223], off
	v_lshl_add_u64 v[222:223], s[4:5], 0, v[144:145]
	s_add_i32 m0, s38, 0x2000
	s_nop 0
	global_load_lds_dwordx4 v[222:223], off
	v_lshl_add_u64 v[222:223], s[30:31], 0, v[138:139]
	s_mov_b32 m0, s45
	s_nop 0
	global_load_lds_dwordx4 v[222:223], off
	s_mov_b32 m0, s46
	s_nop 0
	global_load_lds_dwordx4 v[224:225], off
	s_waitcnt vmcnt(8) lgkmcnt(0)
	s_barrier
	s_setprio 1
	v_mfma_f32_16x16x32_bf16 v[62:65], v[130:133], v[180:183], 0
	v_mfma_f32_16x16x32_bf16 v[58:61], v[156:159], v[180:183], 0
	v_mfma_f32_16x16x32_bf16 v[46:49], v[130:133], v[196:199], 0
	v_mfma_f32_16x16x32_bf16 v[42:45], v[156:159], v[196:199], 0
	v_mfma_f32_16x16x32_bf16 v[30:33], v[130:133], v[204:207], 0
	v_mfma_f32_16x16x32_bf16 v[26:29], v[156:159], v[204:207], 0
	v_mfma_f32_16x16x32_bf16 v[14:17], v[130:133], v[212:215], 0
	v_mfma_f32_16x16x32_bf16 v[10:13], v[156:159], v[212:215], 0
	v_mfma_f32_16x16x32_bf16 v[62:65], v[134:137], v[184:187], v[62:65]
	v_mfma_f32_16x16x32_bf16 v[58:61], v[160:163], v[184:187], v[58:61]
	v_mfma_f32_16x16x32_bf16 v[46:49], v[134:137], v[200:203], v[46:49]
	v_mfma_f32_16x16x32_bf16 v[42:45], v[160:163], v[200:203], v[42:45]
	v_mfma_f32_16x16x32_bf16 v[30:33], v[134:137], v[208:211], v[30:33]
	v_mfma_f32_16x16x32_bf16 v[26:29], v[160:163], v[208:211], v[26:29]
	v_mfma_f32_16x16x32_bf16 v[14:17], v[134:137], v[216:219], v[14:17]
	v_mfma_f32_16x16x32_bf16 v[10:13], v[160:163], v[216:219], v[10:13]
	v_mfma_f32_16x16x32_bf16 v[54:57], v[164:167], v[180:183], 0
	v_mfma_f32_16x16x32_bf16 v[50:53], v[172:175], v[180:183], 0
	v_mfma_f32_16x16x32_bf16 v[38:41], v[164:167], v[196:199], 0
	v_mfma_f32_16x16x32_bf16 v[34:37], v[172:175], v[196:199], 0
	v_mfma_f32_16x16x32_bf16 v[22:25], v[164:167], v[204:207], 0
	v_mfma_f32_16x16x32_bf16 v[18:21], v[172:175], v[204:207], 0
	v_mfma_f32_16x16x32_bf16 v[6:9], v[164:167], v[212:215], 0
	v_mfma_f32_16x16x32_bf16 v[2:5], v[172:175], v[212:215], 0
	v_mfma_f32_16x16x32_bf16 v[54:57], v[168:171], v[184:187], v[54:57]
	v_mfma_f32_16x16x32_bf16 v[50:53], v[176:179], v[184:187], v[50:53]
	v_mfma_f32_16x16x32_bf16 v[38:41], v[168:171], v[200:203], v[38:41]
	v_mfma_f32_16x16x32_bf16 v[34:37], v[176:179], v[200:203], v[34:37]
	v_mfma_f32_16x16x32_bf16 v[22:25], v[168:171], v[208:211], v[22:25]
	v_mfma_f32_16x16x32_bf16 v[18:21], v[176:179], v[208:211], v[18:21]
	v_mfma_f32_16x16x32_bf16 v[6:9], v[168:171], v[216:219], v[6:9]
	v_mfma_f32_16x16x32_bf16 v[2:5], v[176:179], v[216:219], v[2:5]
	s_barrier
	s_setprio 0
	s_branch .Lpz6_mid
; #define PG8_STAGE(bufoff, gbase, voff) do { _Pragma("unroll") for (int _i = 0; _i < 2; ++_i) \
;         __builtin_amdgcn_global_load_lds((const unsigned*)((const char*)(gbase) + (voff)[_i]), (PG8_LAS unsigned*)(lds + (bufoff) + ldsw + _i * 8192), 16, 0, 0); } while (0)
; #define PG8_LDA(dst, b, h) do { _Pragma("unroll") for (int m = 0; m < 4; ++m) _Pragma("unroll") for (int k = 0; k < 2; ++k) dst[m][k] = *(const PG8_LAS bf16x8*)(lds + PG8_SA(b, h) + aoff + m * 2048 + k * 1024); } while (0)
; #define PG8_LDB(dst, b, h) do { _Pragma("unroll") for (int n = 0; n < 2; ++n) _Pragma("unroll") for (int k = 0; k < 2; ++k) dst[n][k] = *(const PG8_LAS bf16x8*)(lds + PG8_SB(b, h) + boff + n * 2048 + k * 1024); } while (0)
; #define PG8_MMA(ai, bj, At, Bt) do { __builtin_amdgcn_s_setprio(1); _Pragma("unroll") for (int m = 0; m < 4; ++m) _Pragma("unroll") for (int n = 0; n < 2; ++n) _Pragma("unroll") for (int k = 0; k < 2; ++k) \
;         acc[ai][bj][m][n] = __builtin_amdgcn_mfma_f32_16x16x32_bf16(Bt[n][k], At[m][k], acc[ai][bj][m][n], 0, 0, 0); __builtin_amdgcn_s_setprio(0); } while (0)
; #define PG8_WAIT_V(n) asm volatile("s_waitcnt vmcnt(" #n ")" ::: "memory")
; #define PG8_WAIT_L(n) asm volatile("s_waitcnt lgkmcnt(" #n ")" ::: "memory")
; #define PG8_BAR __builtin_amdgcn_s_barrier()
; template <class Epi, class Sched, bool ALIGN_EPI = false, bool SP2 = false>
; __device__ __forceinline__ void gemm_phase(PG8_LAS unsigned char* lds, const Gemm g, const Sched& S, const Epi& E) {
;     ...
;             const char* a2 = last ? nA : cA + (size_t)(t + 2) * kstepA; const char* b2 = last ? nB : cB + (size_t)(t + 2) * kstep;
;             const char* a3 = a2 + kstepA; const char* b3 = b2 + kstep;
;             if (last && has_next) S.a_ready(nxt);
;             if constexpr (SP2) {
;             PG8_LDB(B0, 0, 0); PG8_LDB(B1, 0, 1); PG8_SCHED; PG8_LDA(At, 0, 0); PG8_STAGE(PG8_SA(1, 1), a1 + hstep, voffA);
;             PG8_WAIT_V(8); PG8_WAIT_L(0); PG8_BAR; PG8_MMA(0, 0, At, B0); PG8_MMA(0, 1, At, B1); PG8_BAR; PG8_SCHED;
;             if constexpr (Epi::PREFETCH) { if (t == tpf) E.prefetch(cur, wid, lane); }
;             PG8_LDA(At, 0, 1); PG8_STAGE(PG8_SB(0, 0), b2, voffB); PG8_STAGE(PG8_SB(0, 1), b2 + hstep, voffB); PG8_STAGE(PG8_SA(0, 0), a2, voffA);
;             PG8_WAIT_V(8); PG8_WAIT_L(0); PG8_BAR; PG8_MMA(1, 0, At, B0); PG8_MMA(1, 1, At, B1); PG8_BAR; PG8_SCHED;
.LBB0_1069:
	ds_read_b128 v[130:133], v192
	ds_read_b128 v[134:137], v192 offset:1024
	ds_read_b128 v[156:159], v192 offset:2048
	ds_read_b128 v[160:163], v192 offset:3072
	ds_read_b128 v[164:167], v193
	ds_read_b128 v[168:171], v193 offset:1024
	ds_read_b128 v[172:175], v193 offset:2048
	ds_read_b128 v[176:179], v193 offset:3072
	s_add_u32 s0, s4, 0x200
	s_addc_u32 s1, s5, 0
	s_cmp_eq_u32 s37, 40
	s_cselect_b32 s31, s27, s1
	s_cselect_b32 s30, s26, s0
	s_cselect_b32 s7, s29, s36
	s_cselect_b32 s6, s28, s35
	v_lshl_add_u64 v[188:189], s[4:5], 0, v[148:149]
	s_add_i32 m0, s45, 0xc000
	ds_read_b128 v[180:183], v194
	ds_read_b128 v[184:187], v194 offset:1024
	ds_read_b128 v[196:199], v194 offset:2048
	ds_read_b128 v[200:203], v194 offset:3072
	ds_read_b128 v[204:207], v194 offset:4096
	ds_read_b128 v[208:211], v194 offset:5120
	ds_read_b128 v[212:215], v194 offset:6144
	ds_read_b128 v[216:219], v194 offset:7168
	global_load_lds_dwordx4 v[188:189], off
	v_lshl_add_u64 v[188:189], s[4:5], 0, v[150:151]
	s_add_i32 m0, s45, 0xe000
	s_nop 0
	global_load_lds_dwordx4 v[188:189], off
	s_waitcnt vmcnt(8) lgkmcnt(0)
	s_barrier
	s_setprio 1
	v_mfma_f32_16x16x32_bf16 v[126:129], v[130:133], v[180:183], v[126:129]
	v_mfma_f32_16x16x32_bf16 v[122:125], v[156:159], v[180:183], v[122:125]
	v_mfma_f32_16x16x32_bf16 v[110:113], v[130:133], v[196:199], v[110:113]
	v_mfma_f32_16x16x32_bf16 v[106:109], v[156:159], v[196:199], v[106:109]
	v_mfma_f32_16x16x32_bf16 v[94:97], v[130:133], v[204:207], v[94:97]
	v_mfma_f32_16x16x32_bf16 v[90:93], v[156:159], v[204:207], v[90:93]
	v_mfma_f32_16x16x32_bf16 v[78:81], v[130:133], v[212:215], v[78:81]
	v_mfma_f32_16x16x32_bf16 v[74:77], v[156:159], v[212:215], v[74:77]
	v_mfma_f32_16x16x32_bf16 v[126:129], v[134:137], v[184:187], v[126:129]
	v_mfma_f32_16x16x32_bf16 v[122:125], v[160:163], v[184:187], v[122:125]
	v_mfma_f32_16x16x32_bf16 v[110:113], v[134:137], v[200:203], v[110:113]
	v_mfma_f32_16x16x32_bf16 v[106:109], v[160:163], v[200:203], v[106:109]
	v_mfma_f32_16x16x32_bf16 v[94:97], v[134:137], v[208:211], v[94:97]
	v_mfma_f32_16x16x32_bf16 v[90:93], v[160:163], v[208:211], v[90:93]
	v_mfma_f32_16x16x32_bf16 v[78:81], v[134:137], v[216:219], v[78:81]
	v_mfma_f32_16x16x32_bf16 v[74:77], v[160:163], v[216:219], v[74:77]
	v_mfma_f32_16x16x32_bf16 v[118:121], v[164:167], v[180:183], v[118:121]
	v_mfma_f32_16x16x32_bf16 v[114:117], v[172:175], v[180:183], v[114:117]
	v_mfma_f32_16x16x32_bf16 v[102:105], v[164:167], v[196:199], v[102:105]
	v_mfma_f32_16x16x32_bf16 v[98:101], v[172:175], v[196:199], v[98:101]
	v_mfma_f32_16x16x32_bf16 v[86:89], v[164:167], v[204:207], v[86:89]
	v_mfma_f32_16x16x32_bf16 v[82:85], v[172:175], v[204:207], v[82:85]
	v_mfma_f32_16x16x32_bf16 v[70:73], v[164:167], v[212:215], v[70:73]
	v_mfma_f32_16x16x32_bf16 v[66:69], v[172:175], v[212:215], v[66:69]
	v_mfma_f32_16x16x32_bf16 v[118:121], v[168:171], v[184:187], v[118:121]
	v_mfma_f32_16x16x32_bf16 v[114:117], v[176:179], v[184:187], v[114:117]
	v_mfma_f32_16x16x32_bf16 v[102:105], v[168:171], v[200:203], v[102:105]
	v_mfma_f32_16x16x32_bf16 v[98:101], v[176:179], v[200:203], v[98:101]
	v_mfma_f32_16x16x32_bf16 v[86:89], v[168:171], v[208:211], v[86:89]
	v_mfma_f32_16x16x32_bf16 v[82:85], v[176:179], v[208:211], v[82:85]
	v_mfma_f32_16x16x32_bf16 v[70:73], v[168:171], v[216:219], v[70:73]
	v_mfma_f32_16x16x32_bf16 v[66:69], v[176:179], v[216:219], v[66:69]
	s_barrier
	s_setprio 0
	s_add_i32 s4, s61, s44
	v_lshl_add_u64 v[188:189], s[6:7], 0, v[140:141]
	s_mov_b32 m0, s4
	ds_read_b128 v[180:183], v194 offset:16384
	ds_read_b128 v[184:187], v194 offset:17408
	ds_read_b128 v[196:199], v194 offset:18432
	ds_read_b128 v[200:203], v194 offset:19456
	ds_read_b128 v[204:207], v194 offset:20480
	ds_read_b128 v[208:211], v194 offset:21504
	ds_read_b128 v[212:215], v194 offset:22528
	ds_read_b128 v[216:219], v194 offset:23552
	global_load_lds_dwordx4 v[188:189], off
	s_add_i32 m0, s4, 0x2000
	s_add_u32 s4, s6, 0xb0000
	v_lshl_add_u64 v[220:221], s[6:7], 0, v[144:145]
	s_addc_u32 s5, s7, 0
	s_add_i32 s38, s62, s44
	global_load_lds_dwordx4 v[220:221], off
	v_lshl_add_u64 v[222:223], s[4:5], 0, v[140:141]
	s_mov_b32 m0, s38
	v_lshl_add_u64 v[224:225], s[30:31], 0, v[142:143]
	global_load_lds_dwordx4 v[222:223], off
	v_lshl_add_u64 v[222:223], s[4:5], 0, v[144:145]
	s_add_i32 m0, s38, 0x2000
	s_nop 0
	global_load_lds_dwordx4 v[222:223], off
	v_lshl_add_u64 v[222:223], s[30:31], 0, v[138:139]
	s_mov_b32 m0, s45
	s_nop 0
	global_load_lds_dwordx4 v[222:223], off
	s_mov_b32 m0, s46
	s_nop 0
	global_load_lds_dwordx4 v[224:225], off
	s_waitcnt vmcnt(8) lgkmcnt(0)
	s_barrier
	s_setprio 1
	v_mfma_f32_16x16x32_bf16 v[62:65], v[130:133], v[180:183], v[62:65]
	v_mfma_f32_16x16x32_bf16 v[58:61], v[156:159], v[180:183], v[58:61]
	v_mfma_f32_16x16x32_bf16 v[46:49], v[130:133], v[196:199], v[46:49]
	v_mfma_f32_16x16x32_bf16 v[42:45], v[156:159], v[196:199], v[42:45]
	v_mfma_f32_16x16x32_bf16 v[30:33], v[130:133], v[204:207], v[30:33]
	v_mfma_f32_16x16x32_bf16 v[26:29], v[156:159], v[204:207], v[26:29]
	v_mfma_f32_16x16x32_bf16 v[14:17], v[130:133], v[212:215], v[14:17]
	v_mfma_f32_16x16x32_bf16 v[10:13], v[156:159], v[212:215], v[10:13]
	v_mfma_f32_16x16x32_bf16 v[62:65], v[134:137], v[184:187], v[62:65]
	v_mfma_f32_16x16x32_bf16 v[58:61], v[160:163], v[184:187], v[58:61]
	v_mfma_f32_16x16x32_bf16 v[46:49], v[134:137], v[200:203], v[46:49]
	v_mfma_f32_16x16x32_bf16 v[42:45], v[160:163], v[200:203], v[42:45]
	v_mfma_f32_16x16x32_bf16 v[30:33], v[134:137], v[208:211], v[30:33]
	v_mfma_f32_16x16x32_bf16 v[26:29], v[160:163], v[208:211], v[26:29]
	v_mfma_f32_16x16x32_bf16 v[14:17], v[134:137], v[216:219], v[14:17]
	v_mfma_f32_16x16x32_bf16 v[10:13], v[160:163], v[216:219], v[10:13]
	v_mfma_f32_16x16x32_bf16 v[54:57], v[164:167], v[180:183], v[54:57]
	v_mfma_f32_16x16x32_bf16 v[50:53], v[172:175], v[180:183], v[50:53]
	v_mfma_f32_16x16x32_bf16 v[38:41], v[164:167], v[196:199], v[38:41]
	v_mfma_f32_16x16x32_bf16 v[34:37], v[172:175], v[196:199], v[34:37]
	v_mfma_f32_16x16x32_bf16 v[22:25], v[164:167], v[204:207], v[22:25]
	v_mfma_f32_16x16x32_bf16 v[18:21], v[172:175], v[204:207], v[18:21]
	v_mfma_f32_16x16x32_bf16 v[6:9], v[164:167], v[212:215], v[6:9]
	v_mfma_f32_16x16x32_bf16 v[2:5], v[172:175], v[212:215], v[2:5]
	v_mfma_f32_16x16x32_bf16 v[54:57], v[168:171], v[184:187], v[54:57]
	v_mfma_f32_16x16x32_bf16 v[50:53], v[176:179], v[184:187], v[50:53]
	v_mfma_f32_16x16x32_bf16 v[38:41], v[168:171], v[200:203], v[38:41]
	v_mfma_f32_16x16x32_bf16 v[34:37], v[176:179], v[200:203], v[34:37]
	v_mfma_f32_16x16x32_bf16 v[22:25], v[168:171], v[208:211], v[22:25]
	v_mfma_f32_16x16x32_bf16 v[18:21], v[176:179], v[208:211], v[18:21]
	v_mfma_f32_16x16x32_bf16 v[6:9], v[168:171], v[216:219], v[6:9]
	v_mfma_f32_16x16x32_bf16 v[2:5], v[176:179], v[216:219], v[2:5]
	s_barrier
	s_setprio 0
; #define PG8_STAGE(bufoff, gbase, voff) do { _Pragma("unroll") for (int _i = 0; _i < 2; ++_i) \
;         __builtin_amdgcn_global_load_lds((const unsigned*)((const char*)(gbase) + (voff)[_i]), (PG8_LAS unsigned*)(lds + (bufoff) + ldsw + _i * 8192), 16, 0, 0); } while (0)
; #define PG8_LDA(dst, b, h) do { _Pragma("unroll") for (int m = 0; m < 4; ++m) _Pragma("unroll") for (int k = 0; k < 2; ++k) dst[m][k] = *(const PG8_LAS bf16x8*)(lds + PG8_SA(b, h) + aoff + m * 2048 + k * 1024); } while (0)
; #define PG8_LDB(dst, b, h) do { _Pragma("unroll") for (int n = 0; n < 2; ++n) _Pragma("unroll") for (int k = 0; k < 2; ++k) dst[n][k] = *(const PG8_LAS bf16x8*)(lds + PG8_SB(b, h) + boff + n * 2048 + k * 1024); } while (0)
; #define PG8_MMA(ai, bj, At, Bt) do { __builtin_amdgcn_s_setprio(1); _Pragma("unroll") for (int m = 0; m < 4; ++m) _Pragma("unroll") for (int n = 0; n < 2; ++n) _Pragma("unroll") for (int k = 0; k < 2; ++k) \
;         acc[ai][bj][m][n] = __builtin_amdgcn_mfma_f32_16x16x32_bf16(Bt[n][k], At[m][k], acc[ai][bj][m][n], 0, 0, 0); __builtin_amdgcn_s_setprio(0); } while (0)
; #define PG8_WAIT_V(n) asm volatile("s_waitcnt vmcnt(" #n ")" ::: "memory")
; #define PG8_WAIT_L(n) asm volatile("s_waitcnt lgkmcnt(" #n ")" ::: "memory")
; #define PG8_BAR __builtin_amdgcn_s_barrier()
; #define PG8_SCHED __builtin_amdgcn_sched_barrier(0)
; template <class Epi, class Sched, bool ALIGN_EPI = false, bool SP2 = false>
; __device__ __forceinline__ void gemm_phase(PG8_LAS unsigned char* lds, const Gemm g, const Sched& S, const Epi& E) {
;     ...
;             PG8_LDB(B0, 1, 0); PG8_LDB(B1, 1, 1); PG8_SCHED; PG8_LDA(At, 1, 0); PG8_STAGE(PG8_SA(0, 1), a2 + hstep, voffA);
;             PG8_WAIT_V(8); PG8_WAIT_L(0); PG8_BAR; PG8_MMA(0, 0, At, B0); PG8_MMA(0, 1, At, B1); PG8_BAR; PG8_SCHED;
.Lpz6_mid:
	s_add_i32 s38, 0, 0x18000
	v_add_u32_e32 v146, s38, v191
	s_add_i32 s39, 0, 0x1c000
	ds_read_b128 v[130:133], v146
	ds_read_b128 v[134:137], v146 offset:1024
	ds_read_b128 v[156:159], v146 offset:2048
	ds_read_b128 v[160:163], v146 offset:3072
	v_add_u32_e32 v146, s39, v191
	ds_read_b128 v[164:167], v146
	ds_read_b128 v[168:171], v146 offset:1024
	ds_read_b128 v[172:175], v146 offset:2048
	ds_read_b128 v[176:179], v146 offset:3072
	s_add_u32 s4, s30, 0xb0000
	s_addc_u32 s5, s31, 0
	s_mov_b32 m0, s47
	v_lshl_add_u64 v[226:227], s[4:5], 0, v[138:139]
	ds_read_b128 v[180:183], v194 offset:32768
	ds_read_b128 v[184:187], v194 offset:33792
	ds_read_b128 v[196:199], v194 offset:34816
	ds_read_b128 v[200:203], v194 offset:35840
	ds_read_b128 v[204:207], v194 offset:36864
	ds_read_b128 v[208:211], v194 offset:37888
	ds_read_b128 v[212:215], v194 offset:38912
	ds_read_b128 v[216:219], v194 offset:39936
	global_load_lds_dwordx4 v[226:227], off
	v_lshl_add_u64 v[226:227], s[4:5], 0, v[142:143]
	s_mov_b32 m0, s48
	s_nop 0
	global_load_lds_dwordx4 v[226:227], off
	s_waitcnt vmcnt(8) lgkmcnt(0)
	s_barrier
	s_setprio 1
	v_mfma_f32_16x16x32_bf16 v[126:129], v[130:133], v[180:183], v[126:129]
	v_mfma_f32_16x16x32_bf16 v[122:125], v[156:159], v[180:183], v[122:125]
	v_mfma_f32_16x16x32_bf16 v[110:113], v[130:133], v[196:199], v[110:113]
	v_mfma_f32_16x16x32_bf16 v[106:109], v[156:159], v[196:199], v[106:109]
	v_mfma_f32_16x16x32_bf16 v[94:97], v[130:133], v[204:207], v[94:97]
	v_mfma_f32_16x16x32_bf16 v[90:93], v[156:159], v[204:207], v[90:93]
	v_mfma_f32_16x16x32_bf16 v[78:81], v[130:133], v[212:215], v[78:81]
	v_mfma_f32_16x16x32_bf16 v[74:77], v[156:159], v[212:215], v[74:77]
	v_mfma_f32_16x16x32_bf16 v[126:129], v[134:137], v[184:187], v[126:129]
	v_mfma_f32_16x16x32_bf16 v[122:125], v[160:163], v[184:187], v[122:125]
	v_mfma_f32_16x16x32_bf16 v[110:113], v[134:137], v[200:203], v[110:113]
	v_mfma_f32_16x16x32_bf16 v[106:109], v[160:163], v[200:203], v[106:109]
	v_mfma_f32_16x16x32_bf16 v[94:97], v[134:137], v[208:211], v[94:97]
	v_mfma_f32_16x16x32_bf16 v[90:93], v[160:163], v[208:211], v[90:93]
	v_mfma_f32_16x16x32_bf16 v[78:81], v[134:137], v[216:219], v[78:81]
	v_mfma_f32_16x16x32_bf16 v[74:77], v[160:163], v[216:219], v[74:77]
	v_mfma_f32_16x16x32_bf16 v[118:121], v[164:167], v[180:183], v[118:121]
	v_mfma_f32_16x16x32_bf16 v[114:117], v[172:175], v[180:183], v[114:117]
	v_mfma_f32_16x16x32_bf16 v[102:105], v[164:167], v[196:199], v[102:105]
	v_mfma_f32_16x16x32_bf16 v[98:101], v[172:175], v[196:199], v[98:101]
	v_mfma_f32_16x16x32_bf16 v[86:89], v[164:167], v[204:207], v[86:89]
	v_mfma_f32_16x16x32_bf16 v[82:85], v[172:175], v[204:207], v[82:85]
	v_mfma_f32_16x16x32_bf16 v[70:73], v[164:167], v[212:215], v[70:73]
	v_mfma_f32_16x16x32_bf16 v[66:69], v[172:175], v[212:215], v[66:69]
	v_mfma_f32_16x16x32_bf16 v[118:121], v[168:171], v[184:187], v[118:121]
	v_mfma_f32_16x16x32_bf16 v[114:117], v[176:179], v[184:187], v[114:117]
	v_mfma_f32_16x16x32_bf16 v[102:105], v[168:171], v[200:203], v[102:105]
	v_mfma_f32_16x16x32_bf16 v[98:101], v[176:179], v[200:203], v[98:101]
	v_mfma_f32_16x16x32_bf16 v[86:89], v[168:171], v[208:211], v[86:89]
	v_mfma_f32_16x16x32_bf16 v[82:85], v[176:179], v[208:211], v[82:85]
	v_mfma_f32_16x16x32_bf16 v[70:73], v[168:171], v[216:219], v[70:73]
	v_mfma_f32_16x16x32_bf16 v[66:69], v[176:179], v[216:219], v[66:69]
	s_barrier
; #define PG8_STAGE(bufoff, gbase, voff) do { _Pragma("unroll") for (int _i = 0; _i < 2; ++_i) \
;         __builtin_amdgcn_global_load_lds((const unsigned*)((const char*)(gbase) + (voff)[_i]), (PG8_LAS unsigned*)(lds + (bufoff) + ldsw + _i * 8192), 16, 0, 0); } while (0)
; #define PG8_LDA(dst, b, h) do { _Pragma("unroll") for (int m = 0; m < 4; ++m) _Pragma("unroll") for (int k = 0; k < 2; ++k) dst[m][k] = *(const PG8_LAS bf16x8*)(lds + PG8_SA(b, h) + aoff + m * 2048 + k * 1024); } while (0)
; #define PG8_MMA(ai, bj, At, Bt) do { __builtin_amdgcn_s_setprio(1); _Pragma("unroll") for (int m = 0; m < 4; ++m) _Pragma("unroll") for (int n = 0; n < 2; ++n) _Pragma("unroll") for (int k = 0; k < 2; ++k) \
;         acc[ai][bj][m][n] = __builtin_amdgcn_mfma_f32_16x16x32_bf16(Bt[n][k], At[m][k], acc[ai][bj][m][n], 0, 0, 0); __builtin_amdgcn_s_setprio(0); } while (0)
; #define PG8_WAIT_V(n) asm volatile("s_waitcnt vmcnt(" #n ")" ::: "memory")
; #define PG8_WAIT_L(n) asm volatile("s_waitcnt lgkmcnt(" #n ")" ::: "memory")
; #define PG8_BAR __builtin_amdgcn_s_barrier()
; #define PG8_SCHED __builtin_amdgcn_sched_barrier(0)
; template <class Epi, class Sched, bool ALIGN_EPI = false, bool SP2 = false>
; __device__ __forceinline__ void gemm_phase(PG8_LAS unsigned char* lds, const Gemm g, const Sched& S, const Epi& E) {
;     ...
;             PG8_LDA(At, 1, 1); PG8_STAGE(PG8_SB(1, 0), b3, voffB); PG8_STAGE(PG8_SB(1, 1), b3 + hstep, voffB); PG8_STAGE(PG8_SA(1, 0), a3, voffA);
;             PG8_WAIT_V(8); PG8_WAIT_L(0); PG8_BAR; PG8_MMA(1, 0, At, B0); PG8_MMA(1, 1, At, B1); PG8_BAR; PG8_SCHED;
;     ...
;         if constexpr (ALIGN_EPI) { if (wr == 0) PG8_BAR; }
	s_setprio 0
	s_add_i32 s4, s38, s44
	v_lshl_add_u64 v[188:189], v[188:189], 0, s[18:19]
	s_mov_b32 m0, s4
	ds_read_b128 v[180:183], v194 offset:49152
	ds_read_b128 v[184:187], v194 offset:50176
	ds_read_b128 v[196:199], v194 offset:51200
	ds_read_b128 v[200:203], v194 offset:52224
	ds_read_b128 v[204:207], v194 offset:53248
	ds_read_b128 v[208:211], v194 offset:54272
	ds_read_b128 v[212:215], v194 offset:55296
	ds_read_b128 v[216:219], v194 offset:56320
	global_load_lds_dwordx4 v[188:189], off
	s_add_i32 m0, s4, 0x2000
	s_add_u32 s4, s6, 0xb0080
	v_lshl_add_u64 v[188:189], v[220:221], 0, s[18:19]
	s_addc_u32 s5, s7, 0
	s_add_i32 s6, s39, s44
	global_load_lds_dwordx4 v[188:189], off
	v_lshl_add_u64 v[188:189], s[4:5], 0, v[140:141]
	s_mov_b32 m0, s6
	s_nop 0
	global_load_lds_dwordx4 v[188:189], off
	v_lshl_add_u64 v[188:189], s[4:5], 0, v[144:145]
	s_add_i32 m0, s6, 0x2000
	s_nop 0
	global_load_lds_dwordx4 v[188:189], off
	v_lshl_add_u64 v[188:189], v[222:223], 0, s[20:21]
	s_mov_b32 m0, s55
	s_nop 0
	global_load_lds_dwordx4 v[188:189], off
	v_lshl_add_u64 v[188:189], v[224:225], 0, s[20:21]
	s_mov_b32 m0, s56
	s_nop 0
	global_load_lds_dwordx4 v[188:189], off
	s_waitcnt vmcnt(8) lgkmcnt(0)
	s_barrier
	s_setprio 1
	v_mfma_f32_16x16x32_bf16 v[62:65], v[130:133], v[180:183], v[62:65]
	v_mfma_f32_16x16x32_bf16 v[58:61], v[156:159], v[180:183], v[58:61]
	v_mfma_f32_16x16x32_bf16 v[46:49], v[130:133], v[196:199], v[46:49]
	v_mfma_f32_16x16x32_bf16 v[42:45], v[156:159], v[196:199], v[42:45]
	v_mfma_f32_16x16x32_bf16 v[30:33], v[130:133], v[204:207], v[30:33]
	v_mfma_f32_16x16x32_bf16 v[26:29], v[156:159], v[204:207], v[26:29]
	v_mfma_f32_16x16x32_bf16 v[14:17], v[130:133], v[212:215], v[14:17]
	v_mfma_f32_16x16x32_bf16 v[10:13], v[156:159], v[212:215], v[10:13]
	v_mfma_f32_16x16x32_bf16 v[62:65], v[134:137], v[184:187], v[62:65]
	v_mfma_f32_16x16x32_bf16 v[58:61], v[160:163], v[184:187], v[58:61]
	v_mfma_f32_16x16x32_bf16 v[46:49], v[134:137], v[200:203], v[46:49]
	v_mfma_f32_16x16x32_bf16 v[42:45], v[160:163], v[200:203], v[42:45]
	v_mfma_f32_16x16x32_bf16 v[30:33], v[134:137], v[208:211], v[30:33]
	v_mfma_f32_16x16x32_bf16 v[26:29], v[160:163], v[208:211], v[26:29]
	v_mfma_f32_16x16x32_bf16 v[14:17], v[134:137], v[216:219], v[14:17]
	v_mfma_f32_16x16x32_bf16 v[10:13], v[160:163], v[216:219], v[10:13]
	v_mfma_f32_16x16x32_bf16 v[54:57], v[164:167], v[180:183], v[54:57]
	v_mfma_f32_16x16x32_bf16 v[50:53], v[172:175], v[180:183], v[50:53]
	v_mfma_f32_16x16x32_bf16 v[38:41], v[164:167], v[196:199], v[38:41]
	v_mfma_f32_16x16x32_bf16 v[34:37], v[172:175], v[196:199], v[34:37]
	v_mfma_f32_16x16x32_bf16 v[22:25], v[164:167], v[204:207], v[22:25]
	v_mfma_f32_16x16x32_bf16 v[18:21], v[172:175], v[204:207], v[18:21]
	v_mfma_f32_16x16x32_bf16 v[6:9], v[164:167], v[212:215], v[6:9]
	v_mfma_f32_16x16x32_bf16 v[2:5], v[172:175], v[212:215], v[2:5]
	v_mfma_f32_16x16x32_bf16 v[54:57], v[168:171], v[184:187], v[54:57]
	v_mfma_f32_16x16x32_bf16 v[50:53], v[176:179], v[184:187], v[50:53]
	v_mfma_f32_16x16x32_bf16 v[38:41], v[168:171], v[200:203], v[38:41]
	v_mfma_f32_16x16x32_bf16 v[34:37], v[176:179], v[200:203], v[34:37]
	v_mfma_f32_16x16x32_bf16 v[22:25], v[168:171], v[208:211], v[22:25]
	v_mfma_f32_16x16x32_bf16 v[18:21], v[176:179], v[208:211], v[18:21]
	v_mfma_f32_16x16x32_bf16 v[6:9], v[168:171], v[216:219], v[6:9]
	v_mfma_f32_16x16x32_bf16 v[2:5], v[176:179], v[216:219], v[2:5]
	s_barrier
	s_setprio 0
	s_add_i32 s37, s37, 2
	s_add_u32 s35, s35, 0x100
	s_addc_u32 s36, s36, 0
	s_cmp_gt_u32 s37, 41
	s_mov_b64 s[4:5], s[0:1]
	s_cbranch_scc0 .LBB0_1069
	s_and_b64 vcc, exec, s[22:23]
	s_cbranch_vccz .LBB0_1072
	s_barrier
